# GEMM K-loops: LDS-DMA addresses in SGPR-base + 32-bit VGPR-offset form (removes 16 64-bit VALU adds per wave per K-iteration in all four GEMM phases)
# speedup vs baseline: 1.0173x; 1.0060x over previous
; #define PG8_STAGE(bufoff, gbase, voff) do { _Pragma("unroll") for (int _i = 0; _i < 2; ++_i) \
;         __builtin_amdgcn_global_load_lds((const unsigned*)((const char*)(gbase) + (voff)[_i]), (PG8_LAS unsigned*)(lds + (bufoff) + ldsw + _i * 8192), 16, 0, 0); } while (0)
; #define PG8_LDA(dst, b, h) do { _Pragma("unroll") for (int m = 0; m < 4; ++m) _Pragma("unroll") for (int k = 0; k < 2; ++k) dst[m][k] = *(const PG8_LAS bf16x8*)(lds + PG8_SA(b, h) + aoff + m * 2048 + k * 1024); } while (0)
; #define PG8_LDB(dst, b, h) do { _Pragma("unroll") for (int n = 0; n < 2; ++n) _Pragma("unroll") for (int k = 0; k < 2; ++k) dst[n][k] = *(const PG8_LAS bf16x8*)(lds + PG8_SB(b, h) + boff + n * 2048 + k * 1024); } while (0)
; #define PG8_MMA(ai, bj, At, Bt) do { __builtin_amdgcn_s_setprio(1); _Pragma("unroll") for (int m = 0; m < 4; ++m) _Pragma("unroll") for (int n = 0; n < 2; ++n) _Pragma("unroll") for (int k = 0; k < 2; ++k) \
;         acc[ai][bj][m][n] = __builtin_amdgcn_mfma_f32_16x16x32_bf16(Bt[n][k], At[m][k], acc[ai][bj][m][n], 0, 0, 0); __builtin_amdgcn_s_setprio(0); } while (0)
; #define PG8_WAIT_V(n) asm volatile("s_waitcnt vmcnt(" #n ")" ::: "memory")
; #define PG8_BAR __builtin_amdgcn_s_barrier()
; template <class Epi, class Sched, bool ALIGN_EPI = false, bool SP2 = false>
; __device__ __forceinline__ void gemm_phase(PG8_LAS unsigned char* lds, const Gemm g, const Sched& S, const Epi& E) {
;     ...
;         for (int t = 0; t < nt; t += 2) {
;             const bool last = (t == nt - 2);
;             const char* a1 = cA + (size_t)(t + 1) * kstep;
;             const char* a2 = last ? nA : cA + (size_t)(t + 2) * kstep; const char* b2 = last ? nB : cB + (size_t)(t + 2) * kstep;
;             const char* a3 = a2 + kstep; const char* b3 = b2 + kstep;
;             if (last && has_next) S.a_ready(nxt);
;             if constexpr (SP2) {
;             PG8_LDB(B0, 0, 0); PG8_LDB(B1, 0, 1); PG8_SCHED; PG8_LDA(At, 0, 0); PG8_STAGE(PG8_SA(1, 1), a1 + hstep, voffA);
;             PG8_WAIT_V(8); PG8_WAIT_L(0); PG8_BAR; PG8_MMA(0, 0, At, B0); PG8_MMA(0, 1, At, B1); PG8_BAR; PG8_SCHED;
;             PG8_LDA(At, 0, 1); PG8_STAGE(PG8_SB(0, 0), b2, voffB); PG8_STAGE(PG8_SB(0, 1), b2 + hstep, voffB); PG8_STAGE(PG8_SA(0, 0), a2, voffA);
;             PG8_WAIT_V(8); PG8_WAIT_L(0); PG8_BAR; PG8_MMA(1, 0, At, B0); PG8_MMA(1, 1, At, B1); PG8_BAR; PG8_SCHED;
.LBB0_131:
	s_ashr_i32 s1, s0, 31
	s_lshl_b64 s[14:15], s[0:1], 19
	s_add_u32 s94, s50, s14
	s_addc_u32 s95, s51, s15
	s_and_b64 s[14:15], s[6:7], exec
	s_cselect_b32 s1, s95, s9
	s_cselect_b32 s16, s94, s8
	s_ashr_i32 s89, s88, 31
	s_lshl_b64 s[14:15], s[88:89], 19
	s_add_u32 s96, s33, s14
	s_addc_u32 s97, s42, s15
	s_and_b64 s[14:15], s[6:7], exec
	s_cselect_b32 s30, s97, s11
	s_cselect_b32 s31, s96, s10
	s_add_u32 s8, s8, 0x40080
	s_addc_u32 s9, s9, 0
	s_add_u32 s34, s10, 0x100
	s_addc_u32 s35, s11, 0
	s_mov_b32 s36, -2
	s_waitcnt lgkmcnt(0)
	ds_read_b128 v[128:131], v194
	ds_read_b128 v[132:135], v194 offset:1024
	ds_read_b128 v[136:139], v194 offset:2048
	ds_read_b128 v[140:143], v194 offset:3072
	ds_read_b128 v[166:169], v195
	ds_read_b128 v[202:205], v195 offset:1024
	ds_read_b128 v[206:209], v195 offset:2048
	ds_read_b128 v[210:213], v195 offset:3072
	s_add_u32 s10, s8, 0xfffc0080
	s_addc_u32 s11, s9, -1
	s_cmp_eq_u32 s36, 12
	s_cselect_b32 s15, s1, s11
	s_cselect_b32 s14, s16, s10
	s_cselect_b32 s11, s30, s35
	s_cselect_b32 s10, s31, s34
	s_add_i32 m0, s91, 0xc000
	ds_read_b128 v[214:217], v196
	ds_read_b128 v[218:221], v196 offset:1024
	ds_read_b128 v[222:225], v196 offset:2048
	ds_read_b128 v[226:229], v196 offset:3072
	ds_read_b128 v[230:233], v196 offset:4096
	ds_read_b128 v[234:237], v196 offset:5120
	ds_read_b128 v[238:241], v196 offset:6144
	ds_read_b128 v[242:245], v196 offset:7168
	global_load_lds_dwordx4 v156, s[8:9]
	s_add_i32 m0, s91, 0xe000
	s_nop 0
	global_load_lds_dwordx4 v158, s[8:9]
	s_waitcnt vmcnt(8)
	s_waitcnt lgkmcnt(0)
	s_barrier
	s_setprio 1
	s_waitcnt lgkmcnt(0)
	v_mfma_f32_16x16x32_bf16 v[124:127], v[128:131], v[214:217], 0
	v_mfma_f32_16x16x32_bf16 v[120:123], v[136:139], v[214:217], 0
	v_mfma_f32_16x16x32_bf16 v[108:111], v[128:131], v[222:225], 0
	v_mfma_f32_16x16x32_bf16 v[104:107], v[136:139], v[222:225], 0
	v_mfma_f32_16x16x32_bf16 v[92:95], v[128:131], v[230:233], 0
	v_mfma_f32_16x16x32_bf16 v[88:91], v[136:139], v[230:233], 0
	v_mfma_f32_16x16x32_bf16 v[76:79], v[128:131], v[238:241], 0
	v_mfma_f32_16x16x32_bf16 v[72:75], v[136:139], v[238:241], 0
	v_mfma_f32_16x16x32_bf16 v[124:127], v[132:135], v[218:221], v[124:127]
	v_mfma_f32_16x16x32_bf16 v[120:123], v[140:143], v[218:221], v[120:123]
	v_mfma_f32_16x16x32_bf16 v[108:111], v[132:135], v[226:229], v[108:111]
	v_mfma_f32_16x16x32_bf16 v[104:107], v[140:143], v[226:229], v[104:107]
	v_mfma_f32_16x16x32_bf16 v[92:95], v[132:135], v[234:237], v[92:95]
	v_mfma_f32_16x16x32_bf16 v[88:91], v[140:143], v[234:237], v[88:91]
	v_mfma_f32_16x16x32_bf16 v[76:79], v[132:135], v[242:245], v[76:79]
	v_mfma_f32_16x16x32_bf16 v[72:75], v[140:143], v[242:245], v[72:75]
	s_setprio 0
	s_setprio 1
	v_mfma_f32_16x16x32_bf16 v[116:119], v[166:169], v[214:217], 0
	v_mfma_f32_16x16x32_bf16 v[112:115], v[206:209], v[214:217], 0
	v_mfma_f32_16x16x32_bf16 v[100:103], v[166:169], v[222:225], 0
	v_mfma_f32_16x16x32_bf16 v[96:99], v[206:209], v[222:225], 0
	v_mfma_f32_16x16x32_bf16 v[84:87], v[166:169], v[230:233], 0
	v_mfma_f32_16x16x32_bf16 v[80:83], v[206:209], v[230:233], 0
	v_mfma_f32_16x16x32_bf16 v[68:71], v[166:169], v[238:241], 0
	v_mfma_f32_16x16x32_bf16 v[64:67], v[206:209], v[238:241], 0
	v_mfma_f32_16x16x32_bf16 v[116:119], v[202:205], v[218:221], v[116:119]
	v_mfma_f32_16x16x32_bf16 v[112:115], v[210:213], v[218:221], v[112:115]
	v_mfma_f32_16x16x32_bf16 v[100:103], v[202:205], v[226:229], v[100:103]
	v_mfma_f32_16x16x32_bf16 v[96:99], v[210:213], v[226:229], v[96:99]
	v_mfma_f32_16x16x32_bf16 v[84:87], v[202:205], v[234:237], v[84:87]
	v_mfma_f32_16x16x32_bf16 v[80:83], v[210:213], v[234:237], v[80:83]
	v_mfma_f32_16x16x32_bf16 v[68:71], v[202:205], v[242:245], v[68:71]
	v_mfma_f32_16x16x32_bf16 v[64:67], v[210:213], v[242:245], v[64:67]
	s_setprio 0
	s_barrier
	s_add_i32 s37, s82, s43
	s_mov_b32 m0, s37
	ds_read_b128 v[214:217], v196 offset:16384
	ds_read_b128 v[218:221], v196 offset:17408
	ds_read_b128 v[222:225], v196 offset:18432
	ds_read_b128 v[226:229], v196 offset:19456
	ds_read_b128 v[230:233], v196 offset:20480
	ds_read_b128 v[234:237], v196 offset:21504
	ds_read_b128 v[238:241], v196 offset:22528
	ds_read_b128 v[242:245], v196 offset:23552
	global_load_lds_dwordx4 v146, s[10:11]
	s_add_i32 m0, s37, 0x2000
	s_add_u32 s38, s10, 0x40000
	s_addc_u32 s39, s11, 0
	s_add_u32 s98, s10, s20
	s_addc_u32 s99, s11, s21
	s_add_u32 s100, s14, s20
	s_addc_u32 s101, s15, s21
	s_add_i32 s37, s83, s43
	global_load_lds_dwordx4 v150, s[10:11]
	s_mov_b32 m0, s37
	s_nop 0
	global_load_lds_dwordx4 v146, s[38:39]
	s_add_i32 m0, s37, 0x2000
	s_nop 0
	global_load_lds_dwordx4 v150, s[38:39]
	s_mov_b32 m0, s91
	s_nop 0
	global_load_lds_dwordx4 v144, s[14:15]
	s_mov_b32 m0, s93
	s_nop 0
	global_load_lds_dwordx4 v148, s[14:15]
	s_waitcnt vmcnt(8)
	s_waitcnt lgkmcnt(0)
	s_barrier
; #define PG8_STAGE(bufoff, gbase, voff) do { _Pragma("unroll") for (int _i = 0; _i < 2; ++_i) \
;         __builtin_amdgcn_global_load_lds((const unsigned*)((const char*)(gbase) + (voff)[_i]), (PG8_LAS unsigned*)(lds + (bufoff) + ldsw + _i * 8192), 16, 0, 0); } while (0)
; #define PG8_LDA(dst, b, h) do { _Pragma("unroll") for (int m = 0; m < 4; ++m) _Pragma("unroll") for (int k = 0; k < 2; ++k) dst[m][k] = *(const PG8_LAS bf16x8*)(lds + PG8_SA(b, h) + aoff + m * 2048 + k * 1024); } while (0)
; #define PG8_LDB(dst, b, h) do { _Pragma("unroll") for (int n = 0; n < 2; ++n) _Pragma("unroll") for (int k = 0; k < 2; ++k) dst[n][k] = *(const PG8_LAS bf16x8*)(lds + PG8_SB(b, h) + boff + n * 2048 + k * 1024); } while (0)
; #define PG8_MMA(ai, bj, At, Bt) do { __builtin_amdgcn_s_setprio(1); _Pragma("unroll") for (int m = 0; m < 4; ++m) _Pragma("unroll") for (int n = 0; n < 2; ++n) _Pragma("unroll") for (int k = 0; k < 2; ++k) \
;         acc[ai][bj][m][n] = __builtin_amdgcn_mfma_f32_16x16x32_bf16(Bt[n][k], At[m][k], acc[ai][bj][m][n], 0, 0, 0); __builtin_amdgcn_s_setprio(0); } while (0)
; #define PG8_WAIT_V(n) asm volatile("s_waitcnt vmcnt(" #n ")" ::: "memory")
; #define PG8_WAIT_L(n) asm volatile("s_waitcnt lgkmcnt(" #n ")" ::: "memory")
; #define PG8_BAR __builtin_amdgcn_s_barrier()
; #define PG8_SCHED __builtin_amdgcn_sched_barrier(0)
; template <class Epi, class Sched, bool ALIGN_EPI = false, bool SP2 = false>
; __device__ __forceinline__ void gemm_phase(PG8_LAS unsigned char* lds, const Gemm g, const Sched& S, const Epi& E) {
;     ...
;             PG8_WAIT_V(8); PG8_WAIT_L(0); PG8_BAR; PG8_MMA(1, 0, At, B0); PG8_MMA(1, 1, At, B1); PG8_BAR; PG8_SCHED;
;             PG8_LDB(B0, 1, 0); PG8_LDB(B1, 1, 1); PG8_SCHED; PG8_LDA(At, 1, 0); PG8_STAGE(PG8_SA(0, 1), a2 + hstep, voffA);
;             PG8_WAIT_V(8); PG8_WAIT_L(0); PG8_BAR; PG8_MMA(0, 0, At, B0); PG8_MMA(0, 1, At, B1); PG8_BAR; PG8_SCHED;
	s_setprio 1
	s_waitcnt lgkmcnt(0)
	v_mfma_f32_16x16x32_bf16 v[60:63], v[128:131], v[214:217], 0
	v_mfma_f32_16x16x32_bf16 v[56:59], v[136:139], v[214:217], 0
	v_mfma_f32_16x16x32_bf16 v[44:47], v[128:131], v[222:225], 0
	v_mfma_f32_16x16x32_bf16 v[40:43], v[136:139], v[222:225], 0
	v_mfma_f32_16x16x32_bf16 v[28:31], v[128:131], v[230:233], 0
	v_mfma_f32_16x16x32_bf16 v[24:27], v[136:139], v[230:233], 0
	v_mfma_f32_16x16x32_bf16 v[12:15], v[128:131], v[238:241], 0
	v_mfma_f32_16x16x32_bf16 v[8:11], v[136:139], v[238:241], 0
	v_mfma_f32_16x16x32_bf16 v[60:63], v[132:135], v[218:221], v[60:63]
	v_mfma_f32_16x16x32_bf16 v[56:59], v[140:143], v[218:221], v[56:59]
	v_mfma_f32_16x16x32_bf16 v[44:47], v[132:135], v[226:229], v[44:47]
	v_mfma_f32_16x16x32_bf16 v[40:43], v[140:143], v[226:229], v[40:43]
	v_mfma_f32_16x16x32_bf16 v[28:31], v[132:135], v[234:237], v[28:31]
	v_mfma_f32_16x16x32_bf16 v[24:27], v[140:143], v[234:237], v[24:27]
	v_mfma_f32_16x16x32_bf16 v[12:15], v[132:135], v[242:245], v[12:15]
	v_mfma_f32_16x16x32_bf16 v[8:11], v[140:143], v[242:245], v[8:11]
	s_setprio 0
	s_setprio 1
	v_mfma_f32_16x16x32_bf16 v[52:55], v[166:169], v[214:217], 0
	v_mfma_f32_16x16x32_bf16 v[48:51], v[206:209], v[214:217], 0
	v_mfma_f32_16x16x32_bf16 v[36:39], v[166:169], v[222:225], 0
	v_mfma_f32_16x16x32_bf16 v[32:35], v[206:209], v[222:225], 0
	v_mfma_f32_16x16x32_bf16 v[20:23], v[166:169], v[230:233], 0
	v_mfma_f32_16x16x32_bf16 v[16:19], v[206:209], v[230:233], 0
	v_mfma_f32_16x16x32_bf16 v[4:7], v[166:169], v[238:241], 0
	v_mfma_f32_16x16x32_bf16 v[0:3], v[206:209], v[238:241], 0
	v_mfma_f32_16x16x32_bf16 v[52:55], v[202:205], v[218:221], v[52:55]
	v_mfma_f32_16x16x32_bf16 v[48:51], v[210:213], v[218:221], v[48:51]
	v_mfma_f32_16x16x32_bf16 v[36:39], v[202:205], v[226:229], v[36:39]
	v_mfma_f32_16x16x32_bf16 v[32:35], v[210:213], v[226:229], v[32:35]
	v_mfma_f32_16x16x32_bf16 v[20:23], v[202:205], v[234:237], v[20:23]
	v_mfma_f32_16x16x32_bf16 v[16:19], v[210:213], v[234:237], v[16:19]
	v_mfma_f32_16x16x32_bf16 v[4:7], v[202:205], v[242:245], v[4:7]
	v_mfma_f32_16x16x32_bf16 v[0:3], v[210:213], v[242:245], v[0:3]
	s_setprio 0
	s_barrier
	s_add_i32 s37, 0, 0x18000
	s_add_i32 s38, 0, 0x1c000
	v_add_u32_e32 v140, s37, v173
	v_add_u32_e32 v152, s38, v173
	ds_read_b128 v[128:131], v140
	ds_read_b128 v[132:135], v140 offset:1024
	ds_read_b128 v[136:139], v140 offset:2048
	ds_read_b128 v[140:143], v140 offset:3072
	ds_read_b128 v[166:169], v152
	ds_read_b128 v[202:205], v152 offset:1024
	ds_read_b128 v[206:209], v152 offset:2048
	ds_read_b128 v[210:213], v152 offset:3072
	s_add_u32 s14, s14, 0x40000
	s_addc_u32 s15, s15, 0
	s_mov_b32 m0, s52
	ds_read_b128 v[214:217], v196 offset:32768
	ds_read_b128 v[218:221], v196 offset:33792
	ds_read_b128 v[222:225], v196 offset:34816
	ds_read_b128 v[226:229], v196 offset:35840
	ds_read_b128 v[230:233], v196 offset:36864
	ds_read_b128 v[234:237], v196 offset:37888
	ds_read_b128 v[238:241], v196 offset:38912
	ds_read_b128 v[242:245], v196 offset:39936
	global_load_lds_dwordx4 v144, s[14:15]
	s_mov_b32 m0, s53
	s_nop 0
	global_load_lds_dwordx4 v148, s[14:15]
	s_waitcnt vmcnt(8)
	s_waitcnt lgkmcnt(0)
	s_barrier
	s_setprio 1
	s_waitcnt lgkmcnt(0)
	v_mfma_f32_16x16x32_bf16 v[124:127], v[128:131], v[214:217], v[124:127]
	v_mfma_f32_16x16x32_bf16 v[120:123], v[136:139], v[214:217], v[120:123]
	v_mfma_f32_16x16x32_bf16 v[108:111], v[128:131], v[222:225], v[108:111]
	v_mfma_f32_16x16x32_bf16 v[104:107], v[136:139], v[222:225], v[104:107]
	v_mfma_f32_16x16x32_bf16 v[92:95], v[128:131], v[230:233], v[92:95]
	v_mfma_f32_16x16x32_bf16 v[88:91], v[136:139], v[230:233], v[88:91]
	v_mfma_f32_16x16x32_bf16 v[76:79], v[128:131], v[238:241], v[76:79]
	v_mfma_f32_16x16x32_bf16 v[72:75], v[136:139], v[238:241], v[72:75]
	v_mfma_f32_16x16x32_bf16 v[124:127], v[132:135], v[218:221], v[124:127]
	v_mfma_f32_16x16x32_bf16 v[120:123], v[140:143], v[218:221], v[120:123]
	v_mfma_f32_16x16x32_bf16 v[108:111], v[132:135], v[226:229], v[108:111]
	v_mfma_f32_16x16x32_bf16 v[104:107], v[140:143], v[226:229], v[104:107]
	v_mfma_f32_16x16x32_bf16 v[92:95], v[132:135], v[234:237], v[92:95]
	v_mfma_f32_16x16x32_bf16 v[88:91], v[140:143], v[234:237], v[88:91]
	v_mfma_f32_16x16x32_bf16 v[76:79], v[132:135], v[242:245], v[76:79]
	v_mfma_f32_16x16x32_bf16 v[72:75], v[140:143], v[242:245], v[72:75]
	s_setprio 0
	s_setprio 1
	v_mfma_f32_16x16x32_bf16 v[116:119], v[166:169], v[214:217], v[116:119]
	v_mfma_f32_16x16x32_bf16 v[112:115], v[206:209], v[214:217], v[112:115]
	v_mfma_f32_16x16x32_bf16 v[100:103], v[166:169], v[222:225], v[100:103]
	v_mfma_f32_16x16x32_bf16 v[96:99], v[206:209], v[222:225], v[96:99]
	v_mfma_f32_16x16x32_bf16 v[84:87], v[166:169], v[230:233], v[84:87]
	v_mfma_f32_16x16x32_bf16 v[80:83], v[206:209], v[230:233], v[80:83]
	v_mfma_f32_16x16x32_bf16 v[68:71], v[166:169], v[238:241], v[68:71]
	v_mfma_f32_16x16x32_bf16 v[64:67], v[206:209], v[238:241], v[64:67]
	v_mfma_f32_16x16x32_bf16 v[116:119], v[202:205], v[218:221], v[116:119]
	v_mfma_f32_16x16x32_bf16 v[112:115], v[210:213], v[218:221], v[112:115]
	v_mfma_f32_16x16x32_bf16 v[100:103], v[202:205], v[226:229], v[100:103]
	v_mfma_f32_16x16x32_bf16 v[96:99], v[210:213], v[226:229], v[96:99]
	v_mfma_f32_16x16x32_bf16 v[84:87], v[202:205], v[234:237], v[84:87]
	v_mfma_f32_16x16x32_bf16 v[80:83], v[210:213], v[234:237], v[80:83]
	v_mfma_f32_16x16x32_bf16 v[68:71], v[202:205], v[242:245], v[68:71]
	v_mfma_f32_16x16x32_bf16 v[64:67], v[210:213], v[242:245], v[64:67]
	s_setprio 0
	s_barrier
; #define PG8_STAGE(bufoff, gbase, voff) do { _Pragma("unroll") for (int _i = 0; _i < 2; ++_i) \
;         __builtin_amdgcn_global_load_lds((const unsigned*)((const char*)(gbase) + (voff)[_i]), (PG8_LAS unsigned*)(lds + (bufoff) + ldsw + _i * 8192), 16, 0, 0); } while (0)
; #define PG8_LDA(dst, b, h) do { _Pragma("unroll") for (int m = 0; m < 4; ++m) _Pragma("unroll") for (int k = 0; k < 2; ++k) dst[m][k] = *(const PG8_LAS bf16x8*)(lds + PG8_SA(b, h) + aoff + m * 2048 + k * 1024); } while (0)
; #define PG8_LDB(dst, b, h) do { _Pragma("unroll") for (int n = 0; n < 2; ++n) _Pragma("unroll") for (int k = 0; k < 2; ++k) dst[n][k] = *(const PG8_LAS bf16x8*)(lds + PG8_SB(b, h) + boff + n * 2048 + k * 1024); } while (0)
; #define PG8_MMA(ai, bj, At, Bt) do { __builtin_amdgcn_s_setprio(1); _Pragma("unroll") for (int m = 0; m < 4; ++m) _Pragma("unroll") for (int n = 0; n < 2; ++n) _Pragma("unroll") for (int k = 0; k < 2; ++k) \
;         acc[ai][bj][m][n] = __builtin_amdgcn_mfma_f32_16x16x32_bf16(Bt[n][k], At[m][k], acc[ai][bj][m][n], 0, 0, 0); __builtin_amdgcn_s_setprio(0); } while (0)
; #define PG8_WAIT_V(n) asm volatile("s_waitcnt vmcnt(" #n ")" ::: "memory")
; template <class Epi, class Sched, bool ALIGN_EPI = false, bool SP2 = false>
; __device__ __forceinline__ void gemm_phase(PG8_LAS unsigned char* lds, const Gemm g, const Sched& S, const Epi& E) {
;     ...
;             PG8_LDB(B0, 0, 0); PG8_LDB(B1, 0, 1); PG8_SCHED; PG8_LDA(At, 0, 0); PG8_STAGE(PG8_SA(1, 1), a1 + hstep, voffA);
;             PG8_WAIT_V(8); PG8_WAIT_L(0); PG8_BAR; PG8_MMA(0, 0, At, B0); PG8_MMA(0, 1, At, B1); PG8_BAR; PG8_SCHED;
;             PG8_LDA(At, 0, 1); PG8_STAGE(PG8_SB(0, 0), b2, voffB); PG8_STAGE(PG8_SB(0, 1), b2 + hstep, voffB); PG8_STAGE(PG8_SA(0, 0), a2, voffA);
;             PG8_WAIT_V(8); PG8_WAIT_L(0); PG8_BAR; PG8_MMA(1, 0, At, B0); PG8_MMA(1, 1, At, B1); PG8_BAR; PG8_SCHED;
;             PG8_LDB(B0, 1, 0); PG8_LDB(B1, 1, 1); PG8_SCHED; PG8_LDA(At, 1, 0); PG8_STAGE(PG8_SA(0, 1), a2 + hstep, voffA);
;             PG8_WAIT_V(8); PG8_WAIT_L(0); PG8_BAR; PG8_MMA(0, 0, At, B0); PG8_MMA(0, 1, At, B1); PG8_BAR; PG8_SCHED;
;             PG8_LDA(At, 1, 1); PG8_STAGE(PG8_SB(1, 0), b3, voffB); PG8_STAGE(PG8_SB(1, 1), b3 + hstep, voffB); PG8_STAGE(PG8_SA(1, 0), a3, voffA);
;             PG8_WAIT_V(8); PG8_WAIT_L(0); PG8_BAR; PG8_MMA(1, 0, At, B0); PG8_MMA(1, 1, At, B1); PG8_BAR; PG8_SCHED;
	s_add_i32 s14, s37, s43
	s_mov_b32 m0, s14
	ds_read_b128 v[214:217], v196 offset:49152
	ds_read_b128 v[218:221], v196 offset:50176
	ds_read_b128 v[222:225], v196 offset:51200
	ds_read_b128 v[226:229], v196 offset:52224
	ds_read_b128 v[230:233], v196 offset:53248
	ds_read_b128 v[234:237], v196 offset:54272
	ds_read_b128 v[238:241], v196 offset:55296
	ds_read_b128 v[242:245], v196 offset:56320
	global_load_lds_dwordx4 v146, s[98:99]
	s_add_i32 m0, s14, 0x2000
	s_add_u32 s10, s10, 0x40080
	s_addc_u32 s11, s11, 0
	s_add_i32 s14, s38, s43
	global_load_lds_dwordx4 v150, s[98:99]
	s_mov_b32 m0, s14
	s_nop 0
	global_load_lds_dwordx4 v146, s[10:11]
	s_add_i32 m0, s14, 0x2000
	s_nop 0
	global_load_lds_dwordx4 v150, s[10:11]
	s_mov_b32 m0, s55
	s_nop 0
	global_load_lds_dwordx4 v144, s[100:101]
	s_mov_b32 m0, s70
	s_nop 0
	global_load_lds_dwordx4 v148, s[100:101]
	s_waitcnt vmcnt(8)
	s_waitcnt lgkmcnt(0)
	s_barrier
	s_setprio 1
	s_waitcnt lgkmcnt(0)
	v_mfma_f32_16x16x32_bf16 v[60:63], v[128:131], v[214:217], v[60:63]
	v_mfma_f32_16x16x32_bf16 v[56:59], v[136:139], v[214:217], v[56:59]
	v_mfma_f32_16x16x32_bf16 v[44:47], v[128:131], v[222:225], v[44:47]
	v_mfma_f32_16x16x32_bf16 v[40:43], v[136:139], v[222:225], v[40:43]
	v_mfma_f32_16x16x32_bf16 v[28:31], v[128:131], v[230:233], v[28:31]
	v_mfma_f32_16x16x32_bf16 v[24:27], v[136:139], v[230:233], v[24:27]
	v_mfma_f32_16x16x32_bf16 v[12:15], v[128:131], v[238:241], v[12:15]
	v_mfma_f32_16x16x32_bf16 v[8:11], v[136:139], v[238:241], v[8:11]
	v_mfma_f32_16x16x32_bf16 v[60:63], v[132:135], v[218:221], v[60:63]
	v_mfma_f32_16x16x32_bf16 v[56:59], v[140:143], v[218:221], v[56:59]
	v_mfma_f32_16x16x32_bf16 v[44:47], v[132:135], v[226:229], v[44:47]
	v_mfma_f32_16x16x32_bf16 v[40:43], v[140:143], v[226:229], v[40:43]
	v_mfma_f32_16x16x32_bf16 v[28:31], v[132:135], v[234:237], v[28:31]
	v_mfma_f32_16x16x32_bf16 v[24:27], v[140:143], v[234:237], v[24:27]
	v_mfma_f32_16x16x32_bf16 v[12:15], v[132:135], v[242:245], v[12:15]
	v_mfma_f32_16x16x32_bf16 v[8:11], v[140:143], v[242:245], v[8:11]
	s_setprio 0
	s_setprio 1
	v_mfma_f32_16x16x32_bf16 v[52:55], v[166:169], v[214:217], v[52:55]
	v_mfma_f32_16x16x32_bf16 v[48:51], v[206:209], v[214:217], v[48:51]
	v_mfma_f32_16x16x32_bf16 v[36:39], v[166:169], v[222:225], v[36:39]
	v_mfma_f32_16x16x32_bf16 v[32:35], v[206:209], v[222:225], v[32:35]
	v_mfma_f32_16x16x32_bf16 v[20:23], v[166:169], v[230:233], v[20:23]
	v_mfma_f32_16x16x32_bf16 v[16:19], v[206:209], v[230:233], v[16:19]
	v_mfma_f32_16x16x32_bf16 v[4:7], v[166:169], v[238:241], v[4:7]
	v_mfma_f32_16x16x32_bf16 v[0:3], v[206:209], v[238:241], v[0:3]
	v_mfma_f32_16x16x32_bf16 v[52:55], v[202:205], v[218:221], v[52:55]
	v_mfma_f32_16x16x32_bf16 v[48:51], v[210:213], v[218:221], v[48:51]
	v_mfma_f32_16x16x32_bf16 v[36:39], v[202:205], v[226:229], v[36:39]
	v_mfma_f32_16x16x32_bf16 v[32:35], v[210:213], v[226:229], v[32:35]
	v_mfma_f32_16x16x32_bf16 v[20:23], v[202:205], v[234:237], v[20:23]
	v_mfma_f32_16x16x32_bf16 v[16:19], v[210:213], v[234:237], v[16:19]
	v_mfma_f32_16x16x32_bf16 v[4:7], v[202:205], v[242:245], v[4:7]
	v_mfma_f32_16x16x32_bf16 v[0:3], v[210:213], v[242:245], v[0:3]
	s_setprio 0
	s_barrier
	s_add_i32 s36, s36, 2
	s_add_u32 s8, s8, 0x100
	s_addc_u32 s9, s9, 0
	s_add_u32 s34, s34, 0x100
	s_addc_u32 s35, s35, 0
	s_cmp_gt_u32 s36, 13
.LBB0_132:
	ds_read_b128 v[128:131], v194
	ds_read_b128 v[132:135], v194 offset:1024
	ds_read_b128 v[136:139], v194 offset:2048
	ds_read_b128 v[140:143], v194 offset:3072
	ds_read_b128 v[166:169], v195
	ds_read_b128 v[202:205], v195 offset:1024
	ds_read_b128 v[206:209], v195 offset:2048
	ds_read_b128 v[210:213], v195 offset:3072
	s_add_u32 s10, s8, 0xfffc0080
	s_addc_u32 s11, s9, -1
	s_cmp_eq_u32 s36, 12
	s_cselect_b32 s15, s1, s11
	s_cselect_b32 s14, s16, s10
	s_cselect_b32 s11, s30, s35
	s_cselect_b32 s10, s31, s34
	s_add_i32 m0, s91, 0xc000
	ds_read_b128 v[214:217], v196
	ds_read_b128 v[218:221], v196 offset:1024
	ds_read_b128 v[222:225], v196 offset:2048
	ds_read_b128 v[226:229], v196 offset:3072
	ds_read_b128 v[230:233], v196 offset:4096
	ds_read_b128 v[234:237], v196 offset:5120
	ds_read_b128 v[238:241], v196 offset:6144
	ds_read_b128 v[242:245], v196 offset:7168
	global_load_lds_dwordx4 v156, s[8:9]
	s_add_i32 m0, s91, 0xe000
	s_nop 0
	global_load_lds_dwordx4 v158, s[8:9]
	s_waitcnt vmcnt(8)
	s_waitcnt lgkmcnt(0)
	s_barrier
	s_setprio 1
	s_waitcnt lgkmcnt(0)
	v_mfma_f32_16x16x32_bf16 v[124:127], v[128:131], v[214:217], v[124:127]
	v_mfma_f32_16x16x32_bf16 v[120:123], v[136:139], v[214:217], v[120:123]
	v_mfma_f32_16x16x32_bf16 v[108:111], v[128:131], v[222:225], v[108:111]
	v_mfma_f32_16x16x32_bf16 v[104:107], v[136:139], v[222:225], v[104:107]
	v_mfma_f32_16x16x32_bf16 v[92:95], v[128:131], v[230:233], v[92:95]
	v_mfma_f32_16x16x32_bf16 v[88:91], v[136:139], v[230:233], v[88:91]
	v_mfma_f32_16x16x32_bf16 v[76:79], v[128:131], v[238:241], v[76:79]
	v_mfma_f32_16x16x32_bf16 v[72:75], v[136:139], v[238:241], v[72:75]
	v_mfma_f32_16x16x32_bf16 v[124:127], v[132:135], v[218:221], v[124:127]
	v_mfma_f32_16x16x32_bf16 v[120:123], v[140:143], v[218:221], v[120:123]
	v_mfma_f32_16x16x32_bf16 v[108:111], v[132:135], v[226:229], v[108:111]
	v_mfma_f32_16x16x32_bf16 v[104:107], v[140:143], v[226:229], v[104:107]
	v_mfma_f32_16x16x32_bf16 v[92:95], v[132:135], v[234:237], v[92:95]
	v_mfma_f32_16x16x32_bf16 v[88:91], v[140:143], v[234:237], v[88:91]
	v_mfma_f32_16x16x32_bf16 v[76:79], v[132:135], v[242:245], v[76:79]
	v_mfma_f32_16x16x32_bf16 v[72:75], v[140:143], v[242:245], v[72:75]
	s_setprio 0
	s_setprio 1
	v_mfma_f32_16x16x32_bf16 v[116:119], v[166:169], v[214:217], v[116:119]
	v_mfma_f32_16x16x32_bf16 v[112:115], v[206:209], v[214:217], v[112:115]
	v_mfma_f32_16x16x32_bf16 v[100:103], v[166:169], v[222:225], v[100:103]
	v_mfma_f32_16x16x32_bf16 v[96:99], v[206:209], v[222:225], v[96:99]
	v_mfma_f32_16x16x32_bf16 v[84:87], v[166:169], v[230:233], v[84:87]
	v_mfma_f32_16x16x32_bf16 v[80:83], v[206:209], v[230:233], v[80:83]
	v_mfma_f32_16x16x32_bf16 v[68:71], v[166:169], v[238:241], v[68:71]
	v_mfma_f32_16x16x32_bf16 v[64:67], v[206:209], v[238:241], v[64:67]
	v_mfma_f32_16x16x32_bf16 v[116:119], v[202:205], v[218:221], v[116:119]
	v_mfma_f32_16x16x32_bf16 v[112:115], v[210:213], v[218:221], v[112:115]
	v_mfma_f32_16x16x32_bf16 v[100:103], v[202:205], v[226:229], v[100:103]
	v_mfma_f32_16x16x32_bf16 v[96:99], v[210:213], v[226:229], v[96:99]
	v_mfma_f32_16x16x32_bf16 v[84:87], v[202:205], v[234:237], v[84:87]
	v_mfma_f32_16x16x32_bf16 v[80:83], v[210:213], v[234:237], v[80:83]
	v_mfma_f32_16x16x32_bf16 v[68:71], v[202:205], v[242:245], v[68:71]
	v_mfma_f32_16x16x32_bf16 v[64:67], v[210:213], v[242:245], v[64:67]
	s_setprio 0
	s_barrier
; #define PG8_STAGE(bufoff, gbase, voff) do { _Pragma("unroll") for (int _i = 0; _i < 2; ++_i) \
;         __builtin_amdgcn_global_load_lds((const unsigned*)((const char*)(gbase) + (voff)[_i]), (PG8_LAS unsigned*)(lds + (bufoff) + ldsw + _i * 8192), 16, 0, 0); } while (0)
; #define PG8_LDA(dst, b, h) do { _Pragma("unroll") for (int m = 0; m < 4; ++m) _Pragma("unroll") for (int k = 0; k < 2; ++k) dst[m][k] = *(const PG8_LAS bf16x8*)(lds + PG8_SA(b, h) + aoff + m * 2048 + k * 1024); } while (0)
; #define PG8_LDB(dst, b, h) do { _Pragma("unroll") for (int n = 0; n < 2; ++n) _Pragma("unroll") for (int k = 0; k < 2; ++k) dst[n][k] = *(const PG8_LAS bf16x8*)(lds + PG8_SB(b, h) + boff + n * 2048 + k * 1024); } while (0)
; #define PG8_MMA(ai, bj, At, Bt) do { __builtin_amdgcn_s_setprio(1); _Pragma("unroll") for (int m = 0; m < 4; ++m) _Pragma("unroll") for (int n = 0; n < 2; ++n) _Pragma("unroll") for (int k = 0; k < 2; ++k) \
;         acc[ai][bj][m][n] = __builtin_amdgcn_mfma_f32_16x16x32_bf16(Bt[n][k], At[m][k], acc[ai][bj][m][n], 0, 0, 0); __builtin_amdgcn_s_setprio(0); } while (0)
; #define PG8_WAIT_V(n) asm volatile("s_waitcnt vmcnt(" #n ")" ::: "memory")
; #define PG8_WAIT_L(n) asm volatile("s_waitcnt lgkmcnt(" #n ")" ::: "memory")
; #define PG8_BAR __builtin_amdgcn_s_barrier()
; #define PG8_SCHED __builtin_amdgcn_sched_barrier(0)
; template <class Epi, class Sched, bool ALIGN_EPI = false, bool SP2 = false>
; __device__ __forceinline__ void gemm_phase(PG8_LAS unsigned char* lds, const Gemm g, const Sched& S, const Epi& E) {
;     ...
;             PG8_LDA(At, 0, 1); PG8_STAGE(PG8_SB(0, 0), b2, voffB); PG8_STAGE(PG8_SB(0, 1), b2 + hstep, voffB); PG8_STAGE(PG8_SA(0, 0), a2, voffA);
;             PG8_WAIT_V(8); PG8_WAIT_L(0); PG8_BAR; PG8_MMA(1, 0, At, B0); PG8_MMA(1, 1, At, B1); PG8_BAR; PG8_SCHED;
;             PG8_LDB(B0, 1, 0); PG8_LDB(B1, 1, 1); PG8_SCHED; PG8_LDA(At, 1, 0); PG8_STAGE(PG8_SA(0, 1), a2 + hstep, voffA);
;             PG8_WAIT_V(8); PG8_WAIT_L(0); PG8_BAR; PG8_MMA(0, 0, At, B0); PG8_MMA(0, 1, At, B1); PG8_BAR; PG8_SCHED;
	s_add_i32 s37, s82, s43
	s_mov_b32 m0, s37
	ds_read_b128 v[214:217], v196 offset:16384
	ds_read_b128 v[218:221], v196 offset:17408
	ds_read_b128 v[222:225], v196 offset:18432
	ds_read_b128 v[226:229], v196 offset:19456
	ds_read_b128 v[230:233], v196 offset:20480
	ds_read_b128 v[234:237], v196 offset:21504
	ds_read_b128 v[238:241], v196 offset:22528
	ds_read_b128 v[242:245], v196 offset:23552
	global_load_lds_dwordx4 v146, s[10:11]
	s_add_i32 m0, s37, 0x2000
	s_add_u32 s38, s10, 0x40000
	s_addc_u32 s39, s11, 0
	s_add_u32 s98, s10, s20
	s_addc_u32 s99, s11, s21
	s_add_u32 s100, s14, s20
	s_addc_u32 s101, s15, s21
	s_add_i32 s37, s83, s43
	global_load_lds_dwordx4 v150, s[10:11]
	s_mov_b32 m0, s37
	s_nop 0
	global_load_lds_dwordx4 v146, s[38:39]
	s_add_i32 m0, s37, 0x2000
	s_nop 0
	global_load_lds_dwordx4 v150, s[38:39]
	s_mov_b32 m0, s91
	s_nop 0
	global_load_lds_dwordx4 v144, s[14:15]
	s_mov_b32 m0, s93
	s_nop 0
	global_load_lds_dwordx4 v148, s[14:15]
	s_waitcnt vmcnt(8)
	s_waitcnt lgkmcnt(0)
	s_barrier
	s_setprio 1
	s_waitcnt lgkmcnt(0)
	v_mfma_f32_16x16x32_bf16 v[60:63], v[128:131], v[214:217], v[60:63]
	v_mfma_f32_16x16x32_bf16 v[56:59], v[136:139], v[214:217], v[56:59]
	v_mfma_f32_16x16x32_bf16 v[44:47], v[128:131], v[222:225], v[44:47]
	v_mfma_f32_16x16x32_bf16 v[40:43], v[136:139], v[222:225], v[40:43]
	v_mfma_f32_16x16x32_bf16 v[28:31], v[128:131], v[230:233], v[28:31]
	v_mfma_f32_16x16x32_bf16 v[24:27], v[136:139], v[230:233], v[24:27]
	v_mfma_f32_16x16x32_bf16 v[12:15], v[128:131], v[238:241], v[12:15]
	v_mfma_f32_16x16x32_bf16 v[8:11], v[136:139], v[238:241], v[8:11]
	v_mfma_f32_16x16x32_bf16 v[60:63], v[132:135], v[218:221], v[60:63]
	v_mfma_f32_16x16x32_bf16 v[56:59], v[140:143], v[218:221], v[56:59]
	v_mfma_f32_16x16x32_bf16 v[44:47], v[132:135], v[226:229], v[44:47]
	v_mfma_f32_16x16x32_bf16 v[40:43], v[140:143], v[226:229], v[40:43]
	v_mfma_f32_16x16x32_bf16 v[28:31], v[132:135], v[234:237], v[28:31]
	v_mfma_f32_16x16x32_bf16 v[24:27], v[140:143], v[234:237], v[24:27]
	v_mfma_f32_16x16x32_bf16 v[12:15], v[132:135], v[242:245], v[12:15]
	v_mfma_f32_16x16x32_bf16 v[8:11], v[140:143], v[242:245], v[8:11]
	s_setprio 0
	s_setprio 1
	v_mfma_f32_16x16x32_bf16 v[52:55], v[166:169], v[214:217], v[52:55]
	v_mfma_f32_16x16x32_bf16 v[48:51], v[206:209], v[214:217], v[48:51]
	v_mfma_f32_16x16x32_bf16 v[36:39], v[166:169], v[222:225], v[36:39]
	v_mfma_f32_16x16x32_bf16 v[32:35], v[206:209], v[222:225], v[32:35]
	v_mfma_f32_16x16x32_bf16 v[20:23], v[166:169], v[230:233], v[20:23]
	v_mfma_f32_16x16x32_bf16 v[16:19], v[206:209], v[230:233], v[16:19]
	v_mfma_f32_16x16x32_bf16 v[4:7], v[166:169], v[238:241], v[4:7]
	v_mfma_f32_16x16x32_bf16 v[0:3], v[206:209], v[238:241], v[0:3]
	v_mfma_f32_16x16x32_bf16 v[52:55], v[202:205], v[218:221], v[52:55]
	v_mfma_f32_16x16x32_bf16 v[48:51], v[210:213], v[218:221], v[48:51]
	v_mfma_f32_16x16x32_bf16 v[36:39], v[202:205], v[226:229], v[36:39]
	v_mfma_f32_16x16x32_bf16 v[32:35], v[210:213], v[226:229], v[32:35]
	v_mfma_f32_16x16x32_bf16 v[20:23], v[202:205], v[234:237], v[20:23]
	v_mfma_f32_16x16x32_bf16 v[16:19], v[210:213], v[234:237], v[16:19]
	v_mfma_f32_16x16x32_bf16 v[4:7], v[202:205], v[242:245], v[4:7]
	v_mfma_f32_16x16x32_bf16 v[0:3], v[210:213], v[242:245], v[0:3]
	s_setprio 0
	s_barrier
	s_add_i32 s37, 0, 0x18000
	s_add_i32 s38, 0, 0x1c000
	v_add_u32_e32 v140, s37, v173
	v_add_u32_e32 v152, s38, v173
	ds_read_b128 v[128:131], v140
	ds_read_b128 v[132:135], v140 offset:1024
	ds_read_b128 v[136:139], v140 offset:2048
	ds_read_b128 v[140:143], v140 offset:3072
	ds_read_b128 v[166:169], v152
	ds_read_b128 v[202:205], v152 offset:1024
	ds_read_b128 v[206:209], v152 offset:2048
	ds_read_b128 v[210:213], v152 offset:3072
	s_add_u32 s14, s14, 0x40000
	s_addc_u32 s15, s15, 0
	s_mov_b32 m0, s52
	ds_read_b128 v[214:217], v196 offset:32768
	ds_read_b128 v[218:221], v196 offset:33792
	ds_read_b128 v[222:225], v196 offset:34816
	ds_read_b128 v[226:229], v196 offset:35840
	ds_read_b128 v[230:233], v196 offset:36864
	ds_read_b128 v[234:237], v196 offset:37888
	ds_read_b128 v[238:241], v196 offset:38912
	ds_read_b128 v[242:245], v196 offset:39936
	global_load_lds_dwordx4 v144, s[14:15]
	s_mov_b32 m0, s53
	s_nop 0
	global_load_lds_dwordx4 v148, s[14:15]
	s_waitcnt vmcnt(8)
	s_waitcnt lgkmcnt(0)
	s_barrier
; #define PG8_STAGE(bufoff, gbase, voff) do { _Pragma("unroll") for (int _i = 0; _i < 2; ++_i) \
;         __builtin_amdgcn_global_load_lds((const unsigned*)((const char*)(gbase) + (voff)[_i]), (PG8_LAS unsigned*)(lds + (bufoff) + ldsw + _i * 8192), 16, 0, 0); } while (0)
; #define PG8_LDA(dst, b, h) do { _Pragma("unroll") for (int m = 0; m < 4; ++m) _Pragma("unroll") for (int k = 0; k < 2; ++k) dst[m][k] = *(const PG8_LAS bf16x8*)(lds + PG8_SA(b, h) + aoff + m * 2048 + k * 1024); } while (0)
; #define PG8_MMA(ai, bj, At, Bt) do { __builtin_amdgcn_s_setprio(1); _Pragma("unroll") for (int m = 0; m < 4; ++m) _Pragma("unroll") for (int n = 0; n < 2; ++n) _Pragma("unroll") for (int k = 0; k < 2; ++k) \
;         acc[ai][bj][m][n] = __builtin_amdgcn_mfma_f32_16x16x32_bf16(Bt[n][k], At[m][k], acc[ai][bj][m][n], 0, 0, 0); __builtin_amdgcn_s_setprio(0); } while (0)
; #define PG8_WAIT_V(n) asm volatile("s_waitcnt vmcnt(" #n ")" ::: "memory")
; #define PG8_WAIT_L(n) asm volatile("s_waitcnt lgkmcnt(" #n ")" ::: "memory")
; #define PG8_BAR __builtin_amdgcn_s_barrier()
; #define PG8_SCHED __builtin_amdgcn_sched_barrier(0)
; template <class Epi, class Sched, bool ALIGN_EPI = false, bool SP2 = false>
; __device__ __forceinline__ void gemm_phase(PG8_LAS unsigned char* lds, const Gemm g, const Sched& S, const Epi& E) {
;     ...
;             PG8_WAIT_V(8); PG8_WAIT_L(0); PG8_BAR; PG8_MMA(0, 0, At, B0); PG8_MMA(0, 1, At, B1); PG8_BAR; PG8_SCHED;
;             PG8_LDA(At, 1, 1); PG8_STAGE(PG8_SB(1, 0), b3, voffB); PG8_STAGE(PG8_SB(1, 1), b3 + hstep, voffB); PG8_STAGE(PG8_SA(1, 0), a3, voffA);
;             PG8_WAIT_V(8); PG8_WAIT_L(0); PG8_BAR; PG8_MMA(1, 0, At, B0); PG8_MMA(1, 1, At, B1); PG8_BAR; PG8_SCHED;
	s_setprio 1
	s_waitcnt lgkmcnt(0)
	v_mfma_f32_16x16x32_bf16 v[124:127], v[128:131], v[214:217], v[124:127]
	v_mfma_f32_16x16x32_bf16 v[120:123], v[136:139], v[214:217], v[120:123]
	v_mfma_f32_16x16x32_bf16 v[108:111], v[128:131], v[222:225], v[108:111]
	v_mfma_f32_16x16x32_bf16 v[104:107], v[136:139], v[222:225], v[104:107]
	v_mfma_f32_16x16x32_bf16 v[92:95], v[128:131], v[230:233], v[92:95]
	v_mfma_f32_16x16x32_bf16 v[88:91], v[136:139], v[230:233], v[88:91]
	v_mfma_f32_16x16x32_bf16 v[76:79], v[128:131], v[238:241], v[76:79]
	v_mfma_f32_16x16x32_bf16 v[72:75], v[136:139], v[238:241], v[72:75]
	v_mfma_f32_16x16x32_bf16 v[124:127], v[132:135], v[218:221], v[124:127]
	v_mfma_f32_16x16x32_bf16 v[120:123], v[140:143], v[218:221], v[120:123]
	v_mfma_f32_16x16x32_bf16 v[108:111], v[132:135], v[226:229], v[108:111]
	v_mfma_f32_16x16x32_bf16 v[104:107], v[140:143], v[226:229], v[104:107]
	v_mfma_f32_16x16x32_bf16 v[92:95], v[132:135], v[234:237], v[92:95]
	v_mfma_f32_16x16x32_bf16 v[88:91], v[140:143], v[234:237], v[88:91]
	v_mfma_f32_16x16x32_bf16 v[76:79], v[132:135], v[242:245], v[76:79]
	v_mfma_f32_16x16x32_bf16 v[72:75], v[140:143], v[242:245], v[72:75]
	s_setprio 0
	s_setprio 1
	v_mfma_f32_16x16x32_bf16 v[116:119], v[166:169], v[214:217], v[116:119]
	v_mfma_f32_16x16x32_bf16 v[112:115], v[206:209], v[214:217], v[112:115]
	v_mfma_f32_16x16x32_bf16 v[100:103], v[166:169], v[222:225], v[100:103]
	v_mfma_f32_16x16x32_bf16 v[96:99], v[206:209], v[222:225], v[96:99]
	v_mfma_f32_16x16x32_bf16 v[84:87], v[166:169], v[230:233], v[84:87]
	v_mfma_f32_16x16x32_bf16 v[80:83], v[206:209], v[230:233], v[80:83]
	v_mfma_f32_16x16x32_bf16 v[68:71], v[166:169], v[238:241], v[68:71]
	v_mfma_f32_16x16x32_bf16 v[64:67], v[206:209], v[238:241], v[64:67]
	v_mfma_f32_16x16x32_bf16 v[116:119], v[202:205], v[218:221], v[116:119]
	v_mfma_f32_16x16x32_bf16 v[112:115], v[210:213], v[218:221], v[112:115]
	v_mfma_f32_16x16x32_bf16 v[100:103], v[202:205], v[226:229], v[100:103]
	v_mfma_f32_16x16x32_bf16 v[96:99], v[210:213], v[226:229], v[96:99]
	v_mfma_f32_16x16x32_bf16 v[84:87], v[202:205], v[234:237], v[84:87]
	v_mfma_f32_16x16x32_bf16 v[80:83], v[210:213], v[234:237], v[80:83]
	v_mfma_f32_16x16x32_bf16 v[68:71], v[202:205], v[242:245], v[68:71]
	v_mfma_f32_16x16x32_bf16 v[64:67], v[210:213], v[242:245], v[64:67]
	s_setprio 0
	s_barrier
	s_add_i32 s14, s37, s43
	s_mov_b32 m0, s14
	ds_read_b128 v[214:217], v196 offset:49152
	ds_read_b128 v[218:221], v196 offset:50176
	ds_read_b128 v[222:225], v196 offset:51200
	ds_read_b128 v[226:229], v196 offset:52224
	ds_read_b128 v[230:233], v196 offset:53248
	ds_read_b128 v[234:237], v196 offset:54272
	ds_read_b128 v[238:241], v196 offset:55296
	ds_read_b128 v[242:245], v196 offset:56320
	global_load_lds_dwordx4 v146, s[98:99]
	s_add_i32 m0, s14, 0x2000
	s_add_u32 s10, s10, 0x40080
	s_addc_u32 s11, s11, 0
	s_add_i32 s14, s38, s43
	global_load_lds_dwordx4 v150, s[98:99]
	s_mov_b32 m0, s14
	s_nop 0
	global_load_lds_dwordx4 v146, s[10:11]
	s_add_i32 m0, s14, 0x2000
	s_nop 0
	global_load_lds_dwordx4 v150, s[10:11]
	s_mov_b32 m0, s55
	s_nop 0
	global_load_lds_dwordx4 v144, s[100:101]
	s_mov_b32 m0, s70
	s_nop 0
	global_load_lds_dwordx4 v148, s[100:101]
	s_waitcnt vmcnt(8)
	s_waitcnt lgkmcnt(0)
	s_barrier
	s_setprio 1
	s_waitcnt lgkmcnt(0)
	v_mfma_f32_16x16x32_bf16 v[60:63], v[128:131], v[214:217], v[60:63]
	v_mfma_f32_16x16x32_bf16 v[56:59], v[136:139], v[214:217], v[56:59]
	v_mfma_f32_16x16x32_bf16 v[44:47], v[128:131], v[222:225], v[44:47]
	v_mfma_f32_16x16x32_bf16 v[40:43], v[136:139], v[222:225], v[40:43]
	v_mfma_f32_16x16x32_bf16 v[28:31], v[128:131], v[230:233], v[28:31]
	v_mfma_f32_16x16x32_bf16 v[24:27], v[136:139], v[230:233], v[24:27]
	v_mfma_f32_16x16x32_bf16 v[12:15], v[128:131], v[238:241], v[12:15]
	v_mfma_f32_16x16x32_bf16 v[8:11], v[136:139], v[238:241], v[8:11]
	v_mfma_f32_16x16x32_bf16 v[60:63], v[132:135], v[218:221], v[60:63]
	v_mfma_f32_16x16x32_bf16 v[56:59], v[140:143], v[218:221], v[56:59]
	v_mfma_f32_16x16x32_bf16 v[44:47], v[132:135], v[226:229], v[44:47]
	v_mfma_f32_16x16x32_bf16 v[40:43], v[140:143], v[226:229], v[40:43]
	v_mfma_f32_16x16x32_bf16 v[28:31], v[132:135], v[234:237], v[28:31]
	v_mfma_f32_16x16x32_bf16 v[24:27], v[140:143], v[234:237], v[24:27]
	v_mfma_f32_16x16x32_bf16 v[12:15], v[132:135], v[242:245], v[12:15]
	v_mfma_f32_16x16x32_bf16 v[8:11], v[140:143], v[242:245], v[8:11]
	s_setprio 0
	s_setprio 1
	v_mfma_f32_16x16x32_bf16 v[52:55], v[166:169], v[214:217], v[52:55]
	v_mfma_f32_16x16x32_bf16 v[48:51], v[206:209], v[214:217], v[48:51]
	v_mfma_f32_16x16x32_bf16 v[36:39], v[166:169], v[222:225], v[36:39]
	v_mfma_f32_16x16x32_bf16 v[32:35], v[206:209], v[222:225], v[32:35]
	v_mfma_f32_16x16x32_bf16 v[20:23], v[166:169], v[230:233], v[20:23]
	v_mfma_f32_16x16x32_bf16 v[16:19], v[206:209], v[230:233], v[16:19]
	v_mfma_f32_16x16x32_bf16 v[4:7], v[166:169], v[238:241], v[4:7]
	v_mfma_f32_16x16x32_bf16 v[0:3], v[206:209], v[238:241], v[0:3]
	v_mfma_f32_16x16x32_bf16 v[52:55], v[202:205], v[218:221], v[52:55]
	v_mfma_f32_16x16x32_bf16 v[48:51], v[210:213], v[218:221], v[48:51]
	v_mfma_f32_16x16x32_bf16 v[36:39], v[202:205], v[226:229], v[36:39]
	v_mfma_f32_16x16x32_bf16 v[32:35], v[210:213], v[226:229], v[32:35]
	v_mfma_f32_16x16x32_bf16 v[20:23], v[202:205], v[234:237], v[20:23]
	v_mfma_f32_16x16x32_bf16 v[16:19], v[210:213], v[234:237], v[16:19]
	v_mfma_f32_16x16x32_bf16 v[4:7], v[202:205], v[242:245], v[4:7]
	v_mfma_f32_16x16x32_bf16 v[0:3], v[210:213], v[242:245], v[0:3]
	s_setprio 0
	s_barrier
	s_add_i32 s36, s36, 2
	s_add_u32 s8, s8, 0x100
	s_addc_u32 s9, s9, 0
	s_add_u32 s34, s34, 0x100
	s_addc_u32 s35, s35, 0
	s_cmp_gt_u32 s36, 13
	s_cbranch_scc0 .LBB0_132
	s_and_b64 vcc, exec, s[22:23]
	s_cbranch_vccz .LBB0_135
	s_barrier

; #define PG8_STAGE(bufoff, gbase, voff) do { _Pragma("unroll") for (int _i = 0; _i < 2; ++_i) \
;         __builtin_amdgcn_global_load_lds((const unsigned*)((const char*)(gbase) + (voff)[_i]), (PG8_LAS unsigned*)(lds + (bufoff) + ldsw + _i * 8192), 16, 0, 0); } while (0)
; #define PG8_LDA(dst, b, h) do { _Pragma("unroll") for (int m = 0; m < 4; ++m) _Pragma("unroll") for (int k = 0; k < 2; ++k) dst[m][k] = *(const PG8_LAS bf16x8*)(lds + PG8_SA(b, h) + aoff + m * 2048 + k * 1024); } while (0)
; #define PG8_LDB(dst, b, h) do { _Pragma("unroll") for (int n = 0; n < 2; ++n) _Pragma("unroll") for (int k = 0; k < 2; ++k) dst[n][k] = *(const PG8_LAS bf16x8*)(lds + PG8_SB(b, h) + boff + n * 2048 + k * 1024); } while (0)
; #define PG8_WAIT_V(n) asm volatile("s_waitcnt vmcnt(" #n ")" ::: "memory")
; #define PG8_WAIT_L(n) asm volatile("s_waitcnt lgkmcnt(" #n ")" ::: "memory")
; #define PG8_BAR __builtin_amdgcn_s_barrier()
; #define PG8_SCHED __builtin_amdgcn_sched_barrier(0)
; template <class Epi, class Sched, bool ALIGN_EPI = false, bool SP2 = false>
; __device__ __forceinline__ void gemm_phase(PG8_LAS unsigned char* lds, const Gemm g, const Sched& S, const Epi& E) {
;     ...
;         const char* nA = has_next ? (const char*)g.A + (size_t)nxt.pm * tstep : cA; const char* nB = has_next ? (const char*)g.Bt + (size_t)nxt.pn * tstep : cB;
;         for (int t = 0; t < nt; t += 2) {
;             const bool last = (t == nt - 2);
;             const char* a1 = cA + (size_t)(t + 1) * kstep;
;             const char* a2 = last ? nA : cA + (size_t)(t + 2) * kstep; const char* b2 = last ? nB : cB + (size_t)(t + 2) * kstep;
;             const char* a3 = a2 + kstep; const char* b3 = b2 + kstep;
;             if (last && has_next) S.a_ready(nxt);
;             if constexpr (SP2) {
;             PG8_LDB(B0, 0, 0); PG8_LDB(B1, 0, 1); PG8_SCHED; PG8_LDA(At, 0, 0); PG8_STAGE(PG8_SA(1, 1), a1 + hstep, voffA);
;             PG8_WAIT_V(8); PG8_WAIT_L(0); PG8_BAR; PG8_MMA(0, 0, At, B0); PG8_MMA(0, 1, At, B1); PG8_BAR; PG8_SCHED;
;             PG8_LDA(At, 0, 1); PG8_STAGE(PG8_SB(0, 0), b2, voffB); PG8_STAGE(PG8_SB(0, 1), b2 + hstep, voffB); PG8_STAGE(PG8_SA(0, 0), a2, voffA);
;             PG8_WAIT_V(8); PG8_WAIT_L(0); PG8_BAR; PG8_MMA(1, 0, At, B0); PG8_MMA(1, 1, At, B1); PG8_BAR; PG8_SCHED;
.LBB0_809:
	s_ashr_i32 s23, s22, 31
	s_lshl_b64 s[24:25], s[22:23], 19
	s_add_u32 s24, s33, s24
	s_addc_u32 s25, s84, s25
	s_and_b64 s[26:27], s[8:9], exec
	s_cselect_b32 s23, s25, s31
	s_cselect_b32 s29, s24, s30
	s_ashr_i32 s21, s20, 31
	s_lshl_b64 s[26:27], s[20:21], 19
	s_add_u32 s26, s34, s26
	s_addc_u32 s27, s35, s27
	s_and_b64 s[38:39], s[8:9], exec
	s_cselect_b32 s21, s27, s37
	s_cselect_b32 s58, s26, s36
	s_add_u32 s30, s30, 0x40080
	s_addc_u32 s31, s31, 0
	s_add_u32 s59, s36, 0x100
	s_addc_u32 s60, s37, 0
	s_mov_b32 s61, -2
	s_waitcnt lgkmcnt(0)
	s_waitcnt vmcnt(0)
	ds_read_b128 v[144:147], v151
	ds_read_b128 v[154:157], v151 offset:1024
	ds_read_b128 v[158:161], v151 offset:2048
	ds_read_b128 v[162:165], v151 offset:3072
	ds_read_b128 v[166:169], v152
	ds_read_b128 v[170:173], v152 offset:1024
	ds_read_b128 v[174:177], v152 offset:2048
	ds_read_b128 v[178:181], v152 offset:3072
	s_add_u32 s36, s30, 0xfffc0080
	s_addc_u32 s37, s31, -1
	s_cmp_eq_u32 s61, 12
	s_cselect_b32 s39, s23, s37
	s_cselect_b32 s38, s29, s36
	s_cselect_b32 s37, s21, s60
	s_cselect_b32 s36, s58, s59
	s_add_i32 m0, s41, 0xc000
	ds_read_b128 v[188:191], v153
	ds_read_b128 v[192:195], v153 offset:1024
	ds_read_b128 v[196:199], v153 offset:2048
	ds_read_b128 v[200:203], v153 offset:3072
	ds_read_b128 v[204:207], v153 offset:4096
	ds_read_b128 v[208:211], v153 offset:5120
	ds_read_b128 v[212:215], v153 offset:6144
	ds_read_b128 v[216:219], v153 offset:7168
	global_load_lds_dwordx4 v136, s[30:31]
	s_add_i32 m0, s41, 0xe000
	s_nop 0
	global_load_lds_dwordx4 v138, s[30:31]
	s_waitcnt vmcnt(8)
	s_waitcnt lgkmcnt(0)
	s_barrier
	s_setprio 1
	s_waitcnt lgkmcnt(0)
	v_mfma_f32_16x16x32_bf16 v[124:127], v[144:147], v[188:191], 0
	v_mfma_f32_16x16x32_bf16 v[120:123], v[158:161], v[188:191], 0
	v_mfma_f32_16x16x32_bf16 v[108:111], v[144:147], v[196:199], 0
	v_mfma_f32_16x16x32_bf16 v[104:107], v[158:161], v[196:199], 0
	v_mfma_f32_16x16x32_bf16 v[92:95], v[144:147], v[204:207], 0
	v_mfma_f32_16x16x32_bf16 v[88:91], v[158:161], v[204:207], 0
	v_mfma_f32_16x16x32_bf16 v[76:79], v[144:147], v[212:215], 0
	v_mfma_f32_16x16x32_bf16 v[72:75], v[158:161], v[212:215], 0
	v_mfma_f32_16x16x32_bf16 v[124:127], v[154:157], v[192:195], v[124:127]
	v_mfma_f32_16x16x32_bf16 v[120:123], v[162:165], v[192:195], v[120:123]
	v_mfma_f32_16x16x32_bf16 v[108:111], v[154:157], v[200:203], v[108:111]
	v_mfma_f32_16x16x32_bf16 v[104:107], v[162:165], v[200:203], v[104:107]
	v_mfma_f32_16x16x32_bf16 v[92:95], v[154:157], v[208:211], v[92:95]
	v_mfma_f32_16x16x32_bf16 v[88:91], v[162:165], v[208:211], v[88:91]
	v_mfma_f32_16x16x32_bf16 v[76:79], v[154:157], v[216:219], v[76:79]
	v_mfma_f32_16x16x32_bf16 v[72:75], v[162:165], v[216:219], v[72:75]
	s_setprio 0
	s_setprio 1
	v_mfma_f32_16x16x32_bf16 v[116:119], v[166:169], v[188:191], 0
	v_mfma_f32_16x16x32_bf16 v[112:115], v[174:177], v[188:191], 0
	v_mfma_f32_16x16x32_bf16 v[100:103], v[166:169], v[196:199], 0
	v_mfma_f32_16x16x32_bf16 v[96:99], v[174:177], v[196:199], 0
	v_mfma_f32_16x16x32_bf16 v[84:87], v[166:169], v[204:207], 0
	v_mfma_f32_16x16x32_bf16 v[80:83], v[174:177], v[204:207], 0
	v_mfma_f32_16x16x32_bf16 v[68:71], v[166:169], v[212:215], 0
	v_mfma_f32_16x16x32_bf16 v[64:67], v[174:177], v[212:215], 0
	v_mfma_f32_16x16x32_bf16 v[116:119], v[170:173], v[192:195], v[116:119]
	v_mfma_f32_16x16x32_bf16 v[112:115], v[178:181], v[192:195], v[112:115]
	v_mfma_f32_16x16x32_bf16 v[100:103], v[170:173], v[200:203], v[100:103]
	v_mfma_f32_16x16x32_bf16 v[96:99], v[178:181], v[200:203], v[96:99]
	v_mfma_f32_16x16x32_bf16 v[84:87], v[170:173], v[208:211], v[84:87]
	v_mfma_f32_16x16x32_bf16 v[80:83], v[178:181], v[208:211], v[80:83]
	v_mfma_f32_16x16x32_bf16 v[68:71], v[170:173], v[216:219], v[68:71]
	v_mfma_f32_16x16x32_bf16 v[64:67], v[178:181], v[216:219], v[64:67]
	s_setprio 0
	s_barrier
	s_add_i32 s62, s55, s40
	s_mov_b32 m0, s62
	ds_read_b128 v[188:191], v153 offset:16384
	ds_read_b128 v[192:195], v153 offset:17408
	ds_read_b128 v[196:199], v153 offset:18432
	ds_read_b128 v[200:203], v153 offset:19456
	ds_read_b128 v[204:207], v153 offset:20480
	ds_read_b128 v[208:211], v153 offset:21504
	ds_read_b128 v[212:215], v153 offset:22528
	ds_read_b128 v[216:219], v153 offset:23552
	global_load_lds_dwordx4 v130, s[36:37]
	s_add_i32 m0, s62, 0x2000
	s_add_u32 s62, s36, 0x40000
	s_addc_u32 s63, s37, 0
	s_add_u32 s98, s36, s16
	s_addc_u32 s99, s37, s17
	s_add_u32 s100, s38, s16
	s_addc_u32 s101, s39, s17
	s_add_i32 s64, s56, s40
	global_load_lds_dwordx4 v134, s[36:37]
	s_mov_b32 m0, s64
	s_nop 0
	global_load_lds_dwordx4 v130, s[62:63]
	s_add_i32 m0, s64, 0x2000
	s_nop 0
	global_load_lds_dwordx4 v134, s[62:63]
	s_mov_b32 m0, s41
	s_nop 0
	global_load_lds_dwordx4 v128, s[38:39]
	s_mov_b32 m0, s42
	s_nop 0
	global_load_lds_dwordx4 v132, s[38:39]
	s_waitcnt vmcnt(8)
	s_waitcnt lgkmcnt(0)
	s_barrier
; #define PG8_STAGE(bufoff, gbase, voff) do { _Pragma("unroll") for (int _i = 0; _i < 2; ++_i) \
;         __builtin_amdgcn_global_load_lds((const unsigned*)((const char*)(gbase) + (voff)[_i]), (PG8_LAS unsigned*)(lds + (bufoff) + ldsw + _i * 8192), 16, 0, 0); } while (0)
; #define PG8_LDA(dst, b, h) do { _Pragma("unroll") for (int m = 0; m < 4; ++m) _Pragma("unroll") for (int k = 0; k < 2; ++k) dst[m][k] = *(const PG8_LAS bf16x8*)(lds + PG8_SA(b, h) + aoff + m * 2048 + k * 1024); } while (0)
; #define PG8_LDB(dst, b, h) do { _Pragma("unroll") for (int n = 0; n < 2; ++n) _Pragma("unroll") for (int k = 0; k < 2; ++k) dst[n][k] = *(const PG8_LAS bf16x8*)(lds + PG8_SB(b, h) + boff + n * 2048 + k * 1024); } while (0)
; #define PG8_MMA(ai, bj, At, Bt) do { __builtin_amdgcn_s_setprio(1); _Pragma("unroll") for (int m = 0; m < 4; ++m) _Pragma("unroll") for (int n = 0; n < 2; ++n) _Pragma("unroll") for (int k = 0; k < 2; ++k) \
;         acc[ai][bj][m][n] = __builtin_amdgcn_mfma_f32_16x16x32_bf16(Bt[n][k], At[m][k], acc[ai][bj][m][n], 0, 0, 0); __builtin_amdgcn_s_setprio(0); } while (0)
; #define PG8_WAIT_V(n) asm volatile("s_waitcnt vmcnt(" #n ")" ::: "memory")
; #define PG8_WAIT_L(n) asm volatile("s_waitcnt lgkmcnt(" #n ")" ::: "memory")
; #define PG8_BAR __builtin_amdgcn_s_barrier()
; #define PG8_SCHED __builtin_amdgcn_sched_barrier(0)
; template <class Epi, class Sched, bool ALIGN_EPI = false, bool SP2 = false>
; __device__ __forceinline__ void gemm_phase(PG8_LAS unsigned char* lds, const Gemm g, const Sched& S, const Epi& E) {
;     ...
;             PG8_WAIT_V(8); PG8_WAIT_L(0); PG8_BAR; PG8_MMA(1, 0, At, B0); PG8_MMA(1, 1, At, B1); PG8_BAR; PG8_SCHED;
;             PG8_LDB(B0, 1, 0); PG8_LDB(B1, 1, 1); PG8_SCHED; PG8_LDA(At, 1, 0); PG8_STAGE(PG8_SA(0, 1), a2 + hstep, voffA);
;             PG8_WAIT_V(8); PG8_WAIT_L(0); PG8_BAR; PG8_MMA(0, 0, At, B0); PG8_MMA(0, 1, At, B1); PG8_BAR; PG8_SCHED;
	s_setprio 1
	s_waitcnt lgkmcnt(0)
	v_mfma_f32_16x16x32_bf16 v[60:63], v[144:147], v[188:191], 0
	v_mfma_f32_16x16x32_bf16 v[56:59], v[158:161], v[188:191], 0
	v_mfma_f32_16x16x32_bf16 v[44:47], v[144:147], v[196:199], 0
	v_mfma_f32_16x16x32_bf16 v[40:43], v[158:161], v[196:199], 0
	v_mfma_f32_16x16x32_bf16 v[28:31], v[144:147], v[204:207], 0
	v_mfma_f32_16x16x32_bf16 v[24:27], v[158:161], v[204:207], 0
	v_mfma_f32_16x16x32_bf16 v[12:15], v[144:147], v[212:215], 0
	v_mfma_f32_16x16x32_bf16 v[8:11], v[158:161], v[212:215], 0
	v_mfma_f32_16x16x32_bf16 v[60:63], v[154:157], v[192:195], v[60:63]
	v_mfma_f32_16x16x32_bf16 v[56:59], v[162:165], v[192:195], v[56:59]
	v_mfma_f32_16x16x32_bf16 v[44:47], v[154:157], v[200:203], v[44:47]
	v_mfma_f32_16x16x32_bf16 v[40:43], v[162:165], v[200:203], v[40:43]
	v_mfma_f32_16x16x32_bf16 v[28:31], v[154:157], v[208:211], v[28:31]
	v_mfma_f32_16x16x32_bf16 v[24:27], v[162:165], v[208:211], v[24:27]
	v_mfma_f32_16x16x32_bf16 v[12:15], v[154:157], v[216:219], v[12:15]
	v_mfma_f32_16x16x32_bf16 v[8:11], v[162:165], v[216:219], v[8:11]
	s_setprio 0
	s_setprio 1
	v_mfma_f32_16x16x32_bf16 v[52:55], v[166:169], v[188:191], 0
	v_mfma_f32_16x16x32_bf16 v[48:51], v[174:177], v[188:191], 0
	v_mfma_f32_16x16x32_bf16 v[36:39], v[166:169], v[196:199], 0
	v_mfma_f32_16x16x32_bf16 v[32:35], v[174:177], v[196:199], 0
	v_mfma_f32_16x16x32_bf16 v[20:23], v[166:169], v[204:207], 0
	v_mfma_f32_16x16x32_bf16 v[16:19], v[174:177], v[204:207], 0
	v_mfma_f32_16x16x32_bf16 v[4:7], v[166:169], v[212:215], 0
	v_mfma_f32_16x16x32_bf16 v[0:3], v[174:177], v[212:215], 0
	v_mfma_f32_16x16x32_bf16 v[52:55], v[170:173], v[192:195], v[52:55]
	v_mfma_f32_16x16x32_bf16 v[48:51], v[178:181], v[192:195], v[48:51]
	v_mfma_f32_16x16x32_bf16 v[36:39], v[170:173], v[200:203], v[36:39]
	v_mfma_f32_16x16x32_bf16 v[32:35], v[178:181], v[200:203], v[32:35]
	v_mfma_f32_16x16x32_bf16 v[20:23], v[170:173], v[208:211], v[20:23]
	v_mfma_f32_16x16x32_bf16 v[16:19], v[178:181], v[208:211], v[16:19]
	v_mfma_f32_16x16x32_bf16 v[4:7], v[170:173], v[216:219], v[4:7]
	v_mfma_f32_16x16x32_bf16 v[0:3], v[178:181], v[216:219], v[0:3]
	s_setprio 0
	s_barrier
	s_add_i32 s62, 0, 0x18000
	s_add_i32 s63, 0, 0x1c000
	v_add_u32_e32 v162, s62, v149
	v_add_u32_e32 v178, s63, v149
	ds_read_b128 v[144:147], v162
	ds_read_b128 v[154:157], v162 offset:1024
	ds_read_b128 v[158:161], v162 offset:2048
	ds_read_b128 v[162:165], v162 offset:3072
	ds_read_b128 v[166:169], v178
	ds_read_b128 v[170:173], v178 offset:1024
	ds_read_b128 v[174:177], v178 offset:2048
	ds_read_b128 v[178:181], v178 offset:3072
	s_add_u32 s38, s38, 0x40000
	s_addc_u32 s39, s39, 0
	s_mov_b32 m0, s43
	ds_read_b128 v[188:191], v153 offset:32768
	ds_read_b128 v[192:195], v153 offset:33792
	ds_read_b128 v[196:199], v153 offset:34816
	ds_read_b128 v[200:203], v153 offset:35840
	ds_read_b128 v[204:207], v153 offset:36864
	ds_read_b128 v[208:211], v153 offset:37888
	ds_read_b128 v[212:215], v153 offset:38912
	ds_read_b128 v[216:219], v153 offset:39936
	global_load_lds_dwordx4 v128, s[38:39]
	s_mov_b32 m0, s44
	s_nop 0
	global_load_lds_dwordx4 v132, s[38:39]
	s_waitcnt vmcnt(8)
	s_waitcnt lgkmcnt(0)
	s_barrier
	s_setprio 1
	s_waitcnt lgkmcnt(0)
	v_mfma_f32_16x16x32_bf16 v[124:127], v[144:147], v[188:191], v[124:127]
	v_mfma_f32_16x16x32_bf16 v[120:123], v[158:161], v[188:191], v[120:123]
	v_mfma_f32_16x16x32_bf16 v[108:111], v[144:147], v[196:199], v[108:111]
	v_mfma_f32_16x16x32_bf16 v[104:107], v[158:161], v[196:199], v[104:107]
	v_mfma_f32_16x16x32_bf16 v[92:95], v[144:147], v[204:207], v[92:95]
	v_mfma_f32_16x16x32_bf16 v[88:91], v[158:161], v[204:207], v[88:91]
	v_mfma_f32_16x16x32_bf16 v[76:79], v[144:147], v[212:215], v[76:79]
	v_mfma_f32_16x16x32_bf16 v[72:75], v[158:161], v[212:215], v[72:75]
	v_mfma_f32_16x16x32_bf16 v[124:127], v[154:157], v[192:195], v[124:127]
	v_mfma_f32_16x16x32_bf16 v[120:123], v[162:165], v[192:195], v[120:123]
	v_mfma_f32_16x16x32_bf16 v[108:111], v[154:157], v[200:203], v[108:111]
	v_mfma_f32_16x16x32_bf16 v[104:107], v[162:165], v[200:203], v[104:107]
	v_mfma_f32_16x16x32_bf16 v[92:95], v[154:157], v[208:211], v[92:95]
	v_mfma_f32_16x16x32_bf16 v[88:91], v[162:165], v[208:211], v[88:91]
	v_mfma_f32_16x16x32_bf16 v[76:79], v[154:157], v[216:219], v[76:79]
	v_mfma_f32_16x16x32_bf16 v[72:75], v[162:165], v[216:219], v[72:75]
	s_setprio 0
	s_setprio 1
	v_mfma_f32_16x16x32_bf16 v[116:119], v[166:169], v[188:191], v[116:119]
	v_mfma_f32_16x16x32_bf16 v[112:115], v[174:177], v[188:191], v[112:115]
	v_mfma_f32_16x16x32_bf16 v[100:103], v[166:169], v[196:199], v[100:103]
	v_mfma_f32_16x16x32_bf16 v[96:99], v[174:177], v[196:199], v[96:99]
	v_mfma_f32_16x16x32_bf16 v[84:87], v[166:169], v[204:207], v[84:87]
	v_mfma_f32_16x16x32_bf16 v[80:83], v[174:177], v[204:207], v[80:83]
	v_mfma_f32_16x16x32_bf16 v[68:71], v[166:169], v[212:215], v[68:71]
	v_mfma_f32_16x16x32_bf16 v[64:67], v[174:177], v[212:215], v[64:67]
	v_mfma_f32_16x16x32_bf16 v[116:119], v[170:173], v[192:195], v[116:119]
	v_mfma_f32_16x16x32_bf16 v[112:115], v[178:181], v[192:195], v[112:115]
	v_mfma_f32_16x16x32_bf16 v[100:103], v[170:173], v[200:203], v[100:103]
	v_mfma_f32_16x16x32_bf16 v[96:99], v[178:181], v[200:203], v[96:99]
	v_mfma_f32_16x16x32_bf16 v[84:87], v[170:173], v[208:211], v[84:87]
	v_mfma_f32_16x16x32_bf16 v[80:83], v[178:181], v[208:211], v[80:83]
	v_mfma_f32_16x16x32_bf16 v[68:71], v[170:173], v[216:219], v[68:71]
	v_mfma_f32_16x16x32_bf16 v[64:67], v[178:181], v[216:219], v[64:67]
	s_setprio 0
	s_barrier
; #define PG8_STAGE(bufoff, gbase, voff) do { _Pragma("unroll") for (int _i = 0; _i < 2; ++_i) \
;         __builtin_amdgcn_global_load_lds((const unsigned*)((const char*)(gbase) + (voff)[_i]), (PG8_LAS unsigned*)(lds + (bufoff) + ldsw + _i * 8192), 16, 0, 0); } while (0)
; #define PG8_LDA(dst, b, h) do { _Pragma("unroll") for (int m = 0; m < 4; ++m) _Pragma("unroll") for (int k = 0; k < 2; ++k) dst[m][k] = *(const PG8_LAS bf16x8*)(lds + PG8_SA(b, h) + aoff + m * 2048 + k * 1024); } while (0)
; #define PG8_LDB(dst, b, h) do { _Pragma("unroll") for (int n = 0; n < 2; ++n) _Pragma("unroll") for (int k = 0; k < 2; ++k) dst[n][k] = *(const PG8_LAS bf16x8*)(lds + PG8_SB(b, h) + boff + n * 2048 + k * 1024); } while (0)
; #define PG8_MMA(ai, bj, At, Bt) do { __builtin_amdgcn_s_setprio(1); _Pragma("unroll") for (int m = 0; m < 4; ++m) _Pragma("unroll") for (int n = 0; n < 2; ++n) _Pragma("unroll") for (int k = 0; k < 2; ++k) \
;         acc[ai][bj][m][n] = __builtin_amdgcn_mfma_f32_16x16x32_bf16(Bt[n][k], At[m][k], acc[ai][bj][m][n], 0, 0, 0); __builtin_amdgcn_s_setprio(0); } while (0)
; #define PG8_WAIT_V(n) asm volatile("s_waitcnt vmcnt(" #n ")" ::: "memory")
; template <class Epi, class Sched, bool ALIGN_EPI = false, bool SP2 = false>
; __device__ __forceinline__ void gemm_phase(PG8_LAS unsigned char* lds, const Gemm g, const Sched& S, const Epi& E) {
;     ...
;             PG8_LDB(B0, 0, 0); PG8_LDB(B1, 0, 1); PG8_SCHED; PG8_LDA(At, 0, 0); PG8_STAGE(PG8_SA(1, 1), a1 + hstep, voffA);
;             PG8_WAIT_V(8); PG8_WAIT_L(0); PG8_BAR; PG8_MMA(0, 0, At, B0); PG8_MMA(0, 1, At, B1); PG8_BAR; PG8_SCHED;
;             PG8_LDA(At, 0, 1); PG8_STAGE(PG8_SB(0, 0), b2, voffB); PG8_STAGE(PG8_SB(0, 1), b2 + hstep, voffB); PG8_STAGE(PG8_SA(0, 0), a2, voffA);
;             PG8_WAIT_V(8); PG8_WAIT_L(0); PG8_BAR; PG8_MMA(1, 0, At, B0); PG8_MMA(1, 1, At, B1); PG8_BAR; PG8_SCHED;
;             PG8_LDB(B0, 1, 0); PG8_LDB(B1, 1, 1); PG8_SCHED; PG8_LDA(At, 1, 0); PG8_STAGE(PG8_SA(0, 1), a2 + hstep, voffA);
;             PG8_WAIT_V(8); PG8_WAIT_L(0); PG8_BAR; PG8_MMA(0, 0, At, B0); PG8_MMA(0, 1, At, B1); PG8_BAR; PG8_SCHED;
;             PG8_LDA(At, 1, 1); PG8_STAGE(PG8_SB(1, 0), b3, voffB); PG8_STAGE(PG8_SB(1, 1), b3 + hstep, voffB); PG8_STAGE(PG8_SA(1, 0), a3, voffA);
;             PG8_WAIT_V(8); PG8_WAIT_L(0); PG8_BAR; PG8_MMA(1, 0, At, B0); PG8_MMA(1, 1, At, B1); PG8_BAR; PG8_SCHED;
	s_add_i32 s38, s62, s40
	s_mov_b32 m0, s38
	ds_read_b128 v[188:191], v153 offset:49152
	ds_read_b128 v[192:195], v153 offset:50176
	ds_read_b128 v[196:199], v153 offset:51200
	ds_read_b128 v[200:203], v153 offset:52224
	ds_read_b128 v[204:207], v153 offset:53248
	ds_read_b128 v[208:211], v153 offset:54272
	ds_read_b128 v[212:215], v153 offset:55296
	ds_read_b128 v[216:219], v153 offset:56320
	global_load_lds_dwordx4 v130, s[98:99]
	s_add_i32 m0, s38, 0x2000
	s_add_u32 s36, s36, 0x40080
	s_addc_u32 s37, s37, 0
	s_add_i32 s38, s63, s40
	global_load_lds_dwordx4 v134, s[98:99]
	s_mov_b32 m0, s38
	s_nop 0
	global_load_lds_dwordx4 v130, s[36:37]
	s_add_i32 m0, s38, 0x2000
	s_nop 0
	global_load_lds_dwordx4 v134, s[36:37]
	s_mov_b32 m0, s46
	s_nop 0
	global_load_lds_dwordx4 v128, s[100:101]
	s_mov_b32 m0, s47
	s_nop 0
	global_load_lds_dwordx4 v132, s[100:101]
	s_waitcnt vmcnt(8)
	s_waitcnt lgkmcnt(0)
	s_barrier
	s_setprio 1
	s_waitcnt lgkmcnt(0)
	v_mfma_f32_16x16x32_bf16 v[60:63], v[144:147], v[188:191], v[60:63]
	v_mfma_f32_16x16x32_bf16 v[56:59], v[158:161], v[188:191], v[56:59]
	v_mfma_f32_16x16x32_bf16 v[44:47], v[144:147], v[196:199], v[44:47]
	v_mfma_f32_16x16x32_bf16 v[40:43], v[158:161], v[196:199], v[40:43]
	v_mfma_f32_16x16x32_bf16 v[28:31], v[144:147], v[204:207], v[28:31]
	v_mfma_f32_16x16x32_bf16 v[24:27], v[158:161], v[204:207], v[24:27]
	v_mfma_f32_16x16x32_bf16 v[12:15], v[144:147], v[212:215], v[12:15]
	v_mfma_f32_16x16x32_bf16 v[8:11], v[158:161], v[212:215], v[8:11]
	v_mfma_f32_16x16x32_bf16 v[60:63], v[154:157], v[192:195], v[60:63]
	v_mfma_f32_16x16x32_bf16 v[56:59], v[162:165], v[192:195], v[56:59]
	v_mfma_f32_16x16x32_bf16 v[44:47], v[154:157], v[200:203], v[44:47]
	v_mfma_f32_16x16x32_bf16 v[40:43], v[162:165], v[200:203], v[40:43]
	v_mfma_f32_16x16x32_bf16 v[28:31], v[154:157], v[208:211], v[28:31]
	v_mfma_f32_16x16x32_bf16 v[24:27], v[162:165], v[208:211], v[24:27]
	v_mfma_f32_16x16x32_bf16 v[12:15], v[154:157], v[216:219], v[12:15]
	v_mfma_f32_16x16x32_bf16 v[8:11], v[162:165], v[216:219], v[8:11]
	s_setprio 0
	s_setprio 1
	v_mfma_f32_16x16x32_bf16 v[52:55], v[166:169], v[188:191], v[52:55]
	v_mfma_f32_16x16x32_bf16 v[48:51], v[174:177], v[188:191], v[48:51]
	v_mfma_f32_16x16x32_bf16 v[36:39], v[166:169], v[196:199], v[36:39]
	v_mfma_f32_16x16x32_bf16 v[32:35], v[174:177], v[196:199], v[32:35]
	v_mfma_f32_16x16x32_bf16 v[20:23], v[166:169], v[204:207], v[20:23]
	v_mfma_f32_16x16x32_bf16 v[16:19], v[174:177], v[204:207], v[16:19]
	v_mfma_f32_16x16x32_bf16 v[4:7], v[166:169], v[212:215], v[4:7]
	v_mfma_f32_16x16x32_bf16 v[0:3], v[174:177], v[212:215], v[0:3]
	v_mfma_f32_16x16x32_bf16 v[52:55], v[170:173], v[192:195], v[52:55]
	v_mfma_f32_16x16x32_bf16 v[48:51], v[178:181], v[192:195], v[48:51]
	v_mfma_f32_16x16x32_bf16 v[36:39], v[170:173], v[200:203], v[36:39]
	v_mfma_f32_16x16x32_bf16 v[32:35], v[178:181], v[200:203], v[32:35]
	v_mfma_f32_16x16x32_bf16 v[20:23], v[170:173], v[208:211], v[20:23]
	v_mfma_f32_16x16x32_bf16 v[16:19], v[178:181], v[208:211], v[16:19]
	v_mfma_f32_16x16x32_bf16 v[4:7], v[170:173], v[216:219], v[4:7]
	v_mfma_f32_16x16x32_bf16 v[0:3], v[178:181], v[216:219], v[0:3]
	s_setprio 0
	s_barrier
	s_add_i32 s61, s61, 2
	s_add_u32 s30, s30, 0x100
	s_addc_u32 s31, s31, 0
	s_add_u32 s59, s59, 0x100
	s_addc_u32 s60, s60, 0
	s_cmp_gt_u32 s61, 13
.LBB0_810:
	ds_read_b128 v[144:147], v151
	ds_read_b128 v[154:157], v151 offset:1024
	ds_read_b128 v[158:161], v151 offset:2048
	ds_read_b128 v[162:165], v151 offset:3072
	ds_read_b128 v[166:169], v152
	ds_read_b128 v[170:173], v152 offset:1024
	ds_read_b128 v[174:177], v152 offset:2048
	ds_read_b128 v[178:181], v152 offset:3072
	s_add_u32 s36, s30, 0xfffc0080
	s_addc_u32 s37, s31, -1
	s_cmp_eq_u32 s61, 12
	s_cselect_b32 s39, s23, s37
	s_cselect_b32 s38, s29, s36
	s_cselect_b32 s37, s21, s60
	s_cselect_b32 s36, s58, s59
	s_add_i32 m0, s41, 0xc000
	ds_read_b128 v[188:191], v153
	ds_read_b128 v[192:195], v153 offset:1024
	ds_read_b128 v[196:199], v153 offset:2048
	ds_read_b128 v[200:203], v153 offset:3072
	ds_read_b128 v[204:207], v153 offset:4096
	ds_read_b128 v[208:211], v153 offset:5120
	ds_read_b128 v[212:215], v153 offset:6144
	ds_read_b128 v[216:219], v153 offset:7168
	global_load_lds_dwordx4 v136, s[30:31]
	s_add_i32 m0, s41, 0xe000
	s_nop 0
	global_load_lds_dwordx4 v138, s[30:31]
	s_waitcnt vmcnt(8)
	s_waitcnt lgkmcnt(0)
	s_barrier
	s_setprio 1
	s_waitcnt lgkmcnt(0)
	v_mfma_f32_16x16x32_bf16 v[124:127], v[144:147], v[188:191], v[124:127]
	v_mfma_f32_16x16x32_bf16 v[120:123], v[158:161], v[188:191], v[120:123]
	v_mfma_f32_16x16x32_bf16 v[108:111], v[144:147], v[196:199], v[108:111]
	v_mfma_f32_16x16x32_bf16 v[104:107], v[158:161], v[196:199], v[104:107]
	v_mfma_f32_16x16x32_bf16 v[92:95], v[144:147], v[204:207], v[92:95]
	v_mfma_f32_16x16x32_bf16 v[88:91], v[158:161], v[204:207], v[88:91]
	v_mfma_f32_16x16x32_bf16 v[76:79], v[144:147], v[212:215], v[76:79]
	v_mfma_f32_16x16x32_bf16 v[72:75], v[158:161], v[212:215], v[72:75]
	v_mfma_f32_16x16x32_bf16 v[124:127], v[154:157], v[192:195], v[124:127]
	v_mfma_f32_16x16x32_bf16 v[120:123], v[162:165], v[192:195], v[120:123]
	v_mfma_f32_16x16x32_bf16 v[108:111], v[154:157], v[200:203], v[108:111]
	v_mfma_f32_16x16x32_bf16 v[104:107], v[162:165], v[200:203], v[104:107]
	v_mfma_f32_16x16x32_bf16 v[92:95], v[154:157], v[208:211], v[92:95]
	v_mfma_f32_16x16x32_bf16 v[88:91], v[162:165], v[208:211], v[88:91]
	v_mfma_f32_16x16x32_bf16 v[76:79], v[154:157], v[216:219], v[76:79]
	v_mfma_f32_16x16x32_bf16 v[72:75], v[162:165], v[216:219], v[72:75]
	s_setprio 0
	s_setprio 1
	v_mfma_f32_16x16x32_bf16 v[116:119], v[166:169], v[188:191], v[116:119]
	v_mfma_f32_16x16x32_bf16 v[112:115], v[174:177], v[188:191], v[112:115]
	v_mfma_f32_16x16x32_bf16 v[100:103], v[166:169], v[196:199], v[100:103]
	v_mfma_f32_16x16x32_bf16 v[96:99], v[174:177], v[196:199], v[96:99]
	v_mfma_f32_16x16x32_bf16 v[84:87], v[166:169], v[204:207], v[84:87]
	v_mfma_f32_16x16x32_bf16 v[80:83], v[174:177], v[204:207], v[80:83]
	v_mfma_f32_16x16x32_bf16 v[68:71], v[166:169], v[212:215], v[68:71]
	v_mfma_f32_16x16x32_bf16 v[64:67], v[174:177], v[212:215], v[64:67]
	v_mfma_f32_16x16x32_bf16 v[116:119], v[170:173], v[192:195], v[116:119]
	v_mfma_f32_16x16x32_bf16 v[112:115], v[178:181], v[192:195], v[112:115]
	v_mfma_f32_16x16x32_bf16 v[100:103], v[170:173], v[200:203], v[100:103]
	v_mfma_f32_16x16x32_bf16 v[96:99], v[178:181], v[200:203], v[96:99]
	v_mfma_f32_16x16x32_bf16 v[84:87], v[170:173], v[208:211], v[84:87]
	v_mfma_f32_16x16x32_bf16 v[80:83], v[178:181], v[208:211], v[80:83]
	v_mfma_f32_16x16x32_bf16 v[68:71], v[170:173], v[216:219], v[68:71]
	v_mfma_f32_16x16x32_bf16 v[64:67], v[178:181], v[216:219], v[64:67]
	s_setprio 0
	s_barrier
; #define PG8_STAGE(bufoff, gbase, voff) do { _Pragma("unroll") for (int _i = 0; _i < 2; ++_i) \
;         __builtin_amdgcn_global_load_lds((const unsigned*)((const char*)(gbase) + (voff)[_i]), (PG8_LAS unsigned*)(lds + (bufoff) + ldsw + _i * 8192), 16, 0, 0); } while (0)
; #define PG8_LDA(dst, b, h) do { _Pragma("unroll") for (int m = 0; m < 4; ++m) _Pragma("unroll") for (int k = 0; k < 2; ++k) dst[m][k] = *(const PG8_LAS bf16x8*)(lds + PG8_SA(b, h) + aoff + m * 2048 + k * 1024); } while (0)
; #define PG8_LDB(dst, b, h) do { _Pragma("unroll") for (int n = 0; n < 2; ++n) _Pragma("unroll") for (int k = 0; k < 2; ++k) dst[n][k] = *(const PG8_LAS bf16x8*)(lds + PG8_SB(b, h) + boff + n * 2048 + k * 1024); } while (0)
; #define PG8_MMA(ai, bj, At, Bt) do { __builtin_amdgcn_s_setprio(1); _Pragma("unroll") for (int m = 0; m < 4; ++m) _Pragma("unroll") for (int n = 0; n < 2; ++n) _Pragma("unroll") for (int k = 0; k < 2; ++k) \
;         acc[ai][bj][m][n] = __builtin_amdgcn_mfma_f32_16x16x32_bf16(Bt[n][k], At[m][k], acc[ai][bj][m][n], 0, 0, 0); __builtin_amdgcn_s_setprio(0); } while (0)
; #define PG8_WAIT_V(n) asm volatile("s_waitcnt vmcnt(" #n ")" ::: "memory")
; #define PG8_WAIT_L(n) asm volatile("s_waitcnt lgkmcnt(" #n ")" ::: "memory")
; #define PG8_BAR __builtin_amdgcn_s_barrier()
; #define PG8_SCHED __builtin_amdgcn_sched_barrier(0)
; template <class Epi, class Sched, bool ALIGN_EPI = false, bool SP2 = false>
; __device__ __forceinline__ void gemm_phase(PG8_LAS unsigned char* lds, const Gemm g, const Sched& S, const Epi& E) {
;     ...
;             PG8_LDA(At, 0, 1); PG8_STAGE(PG8_SB(0, 0), b2, voffB); PG8_STAGE(PG8_SB(0, 1), b2 + hstep, voffB); PG8_STAGE(PG8_SA(0, 0), a2, voffA);
;             PG8_WAIT_V(8); PG8_WAIT_L(0); PG8_BAR; PG8_MMA(1, 0, At, B0); PG8_MMA(1, 1, At, B1); PG8_BAR; PG8_SCHED;
;             PG8_LDB(B0, 1, 0); PG8_LDB(B1, 1, 1); PG8_SCHED; PG8_LDA(At, 1, 0); PG8_STAGE(PG8_SA(0, 1), a2 + hstep, voffA);
;             PG8_WAIT_V(8); PG8_WAIT_L(0); PG8_BAR; PG8_MMA(0, 0, At, B0); PG8_MMA(0, 1, At, B1); PG8_BAR; PG8_SCHED;
	s_add_i32 s62, s55, s40
	s_mov_b32 m0, s62
	ds_read_b128 v[188:191], v153 offset:16384
	ds_read_b128 v[192:195], v153 offset:17408
	ds_read_b128 v[196:199], v153 offset:18432
	ds_read_b128 v[200:203], v153 offset:19456
	ds_read_b128 v[204:207], v153 offset:20480
	ds_read_b128 v[208:211], v153 offset:21504
	ds_read_b128 v[212:215], v153 offset:22528
	ds_read_b128 v[216:219], v153 offset:23552
	global_load_lds_dwordx4 v130, s[36:37]
	s_add_i32 m0, s62, 0x2000
	s_add_u32 s62, s36, 0x40000
	s_addc_u32 s63, s37, 0
	s_add_u32 s98, s36, s16
	s_addc_u32 s99, s37, s17
	s_add_u32 s100, s38, s16
	s_addc_u32 s101, s39, s17
	s_add_i32 s64, s56, s40
	global_load_lds_dwordx4 v134, s[36:37]
	s_mov_b32 m0, s64
	s_nop 0
	global_load_lds_dwordx4 v130, s[62:63]
	s_add_i32 m0, s64, 0x2000
	s_nop 0
	global_load_lds_dwordx4 v134, s[62:63]
	s_mov_b32 m0, s41
	s_nop 0
	global_load_lds_dwordx4 v128, s[38:39]
	s_mov_b32 m0, s42
	s_nop 0
	global_load_lds_dwordx4 v132, s[38:39]
	s_waitcnt vmcnt(8)
	s_waitcnt lgkmcnt(0)
	s_barrier
	s_setprio 1
	s_waitcnt lgkmcnt(0)
	v_mfma_f32_16x16x32_bf16 v[60:63], v[144:147], v[188:191], v[60:63]
	v_mfma_f32_16x16x32_bf16 v[56:59], v[158:161], v[188:191], v[56:59]
	v_mfma_f32_16x16x32_bf16 v[44:47], v[144:147], v[196:199], v[44:47]
	v_mfma_f32_16x16x32_bf16 v[40:43], v[158:161], v[196:199], v[40:43]
	v_mfma_f32_16x16x32_bf16 v[28:31], v[144:147], v[204:207], v[28:31]
	v_mfma_f32_16x16x32_bf16 v[24:27], v[158:161], v[204:207], v[24:27]
	v_mfma_f32_16x16x32_bf16 v[12:15], v[144:147], v[212:215], v[12:15]
	v_mfma_f32_16x16x32_bf16 v[8:11], v[158:161], v[212:215], v[8:11]
	v_mfma_f32_16x16x32_bf16 v[60:63], v[154:157], v[192:195], v[60:63]
	v_mfma_f32_16x16x32_bf16 v[56:59], v[162:165], v[192:195], v[56:59]
	v_mfma_f32_16x16x32_bf16 v[44:47], v[154:157], v[200:203], v[44:47]
	v_mfma_f32_16x16x32_bf16 v[40:43], v[162:165], v[200:203], v[40:43]
	v_mfma_f32_16x16x32_bf16 v[28:31], v[154:157], v[208:211], v[28:31]
	v_mfma_f32_16x16x32_bf16 v[24:27], v[162:165], v[208:211], v[24:27]
	v_mfma_f32_16x16x32_bf16 v[12:15], v[154:157], v[216:219], v[12:15]
	v_mfma_f32_16x16x32_bf16 v[8:11], v[162:165], v[216:219], v[8:11]
	s_setprio 0
	s_setprio 1
	v_mfma_f32_16x16x32_bf16 v[52:55], v[166:169], v[188:191], v[52:55]
	v_mfma_f32_16x16x32_bf16 v[48:51], v[174:177], v[188:191], v[48:51]
	v_mfma_f32_16x16x32_bf16 v[36:39], v[166:169], v[196:199], v[36:39]
	v_mfma_f32_16x16x32_bf16 v[32:35], v[174:177], v[196:199], v[32:35]
	v_mfma_f32_16x16x32_bf16 v[20:23], v[166:169], v[204:207], v[20:23]
	v_mfma_f32_16x16x32_bf16 v[16:19], v[174:177], v[204:207], v[16:19]
	v_mfma_f32_16x16x32_bf16 v[4:7], v[166:169], v[212:215], v[4:7]
	v_mfma_f32_16x16x32_bf16 v[0:3], v[174:177], v[212:215], v[0:3]
	v_mfma_f32_16x16x32_bf16 v[52:55], v[170:173], v[192:195], v[52:55]
	v_mfma_f32_16x16x32_bf16 v[48:51], v[178:181], v[192:195], v[48:51]
	v_mfma_f32_16x16x32_bf16 v[36:39], v[170:173], v[200:203], v[36:39]
	v_mfma_f32_16x16x32_bf16 v[32:35], v[178:181], v[200:203], v[32:35]
	v_mfma_f32_16x16x32_bf16 v[20:23], v[170:173], v[208:211], v[20:23]
	v_mfma_f32_16x16x32_bf16 v[16:19], v[178:181], v[208:211], v[16:19]
	v_mfma_f32_16x16x32_bf16 v[4:7], v[170:173], v[216:219], v[4:7]
	v_mfma_f32_16x16x32_bf16 v[0:3], v[178:181], v[216:219], v[0:3]
	s_setprio 0
	s_barrier
	s_add_i32 s62, 0, 0x18000
	s_add_i32 s63, 0, 0x1c000
	v_add_u32_e32 v162, s62, v149
	v_add_u32_e32 v178, s63, v149
	ds_read_b128 v[144:147], v162
	ds_read_b128 v[154:157], v162 offset:1024
	ds_read_b128 v[158:161], v162 offset:2048
	ds_read_b128 v[162:165], v162 offset:3072
	ds_read_b128 v[166:169], v178
	ds_read_b128 v[170:173], v178 offset:1024
	ds_read_b128 v[174:177], v178 offset:2048
	ds_read_b128 v[178:181], v178 offset:3072
	s_add_u32 s38, s38, 0x40000
	s_addc_u32 s39, s39, 0
	s_mov_b32 m0, s43
	ds_read_b128 v[188:191], v153 offset:32768
	ds_read_b128 v[192:195], v153 offset:33792
	ds_read_b128 v[196:199], v153 offset:34816
	ds_read_b128 v[200:203], v153 offset:35840
	ds_read_b128 v[204:207], v153 offset:36864
	ds_read_b128 v[208:211], v153 offset:37888
	ds_read_b128 v[212:215], v153 offset:38912
	ds_read_b128 v[216:219], v153 offset:39936
	global_load_lds_dwordx4 v128, s[38:39]
	s_mov_b32 m0, s44
	s_nop 0
	global_load_lds_dwordx4 v132, s[38:39]
	s_waitcnt vmcnt(8)
	s_waitcnt lgkmcnt(0)
	s_barrier
; #define PG8_STAGE(bufoff, gbase, voff) do { _Pragma("unroll") for (int _i = 0; _i < 2; ++_i) \
;         __builtin_amdgcn_global_load_lds((const unsigned*)((const char*)(gbase) + (voff)[_i]), (PG8_LAS unsigned*)(lds + (bufoff) + ldsw + _i * 8192), 16, 0, 0); } while (0)
; #define PG8_LDA(dst, b, h) do { _Pragma("unroll") for (int m = 0; m < 4; ++m) _Pragma("unroll") for (int k = 0; k < 2; ++k) dst[m][k] = *(const PG8_LAS bf16x8*)(lds + PG8_SA(b, h) + aoff + m * 2048 + k * 1024); } while (0)
; #define PG8_MMA(ai, bj, At, Bt) do { __builtin_amdgcn_s_setprio(1); _Pragma("unroll") for (int m = 0; m < 4; ++m) _Pragma("unroll") for (int n = 0; n < 2; ++n) _Pragma("unroll") for (int k = 0; k < 2; ++k) \
;         acc[ai][bj][m][n] = __builtin_amdgcn_mfma_f32_16x16x32_bf16(Bt[n][k], At[m][k], acc[ai][bj][m][n], 0, 0, 0); __builtin_amdgcn_s_setprio(0); } while (0)
; #define PG8_WAIT_V(n) asm volatile("s_waitcnt vmcnt(" #n ")" ::: "memory")
; #define PG8_WAIT_L(n) asm volatile("s_waitcnt lgkmcnt(" #n ")" ::: "memory")
; #define PG8_BAR __builtin_amdgcn_s_barrier()
; #define PG8_SCHED __builtin_amdgcn_sched_barrier(0)
; template <class Epi, class Sched, bool ALIGN_EPI = false, bool SP2 = false>
; __device__ __forceinline__ void gemm_phase(PG8_LAS unsigned char* lds, const Gemm g, const Sched& S, const Epi& E) {
;     ...
;         for (int t = 0; t < nt; t += 2) {
;     ...
;             PG8_WAIT_V(8); PG8_WAIT_L(0); PG8_BAR; PG8_MMA(0, 0, At, B0); PG8_MMA(0, 1, At, B1); PG8_BAR; PG8_SCHED;
;             PG8_LDA(At, 1, 1); PG8_STAGE(PG8_SB(1, 0), b3, voffB); PG8_STAGE(PG8_SB(1, 1), b3 + hstep, voffB); PG8_STAGE(PG8_SA(1, 0), a3, voffA);
;             PG8_WAIT_V(8); PG8_WAIT_L(0); PG8_BAR; PG8_MMA(1, 0, At, B0); PG8_MMA(1, 1, At, B1); PG8_BAR; PG8_SCHED;
	s_setprio 1
	s_waitcnt lgkmcnt(0)
	v_mfma_f32_16x16x32_bf16 v[124:127], v[144:147], v[188:191], v[124:127]
	v_mfma_f32_16x16x32_bf16 v[120:123], v[158:161], v[188:191], v[120:123]
	v_mfma_f32_16x16x32_bf16 v[108:111], v[144:147], v[196:199], v[108:111]
	v_mfma_f32_16x16x32_bf16 v[104:107], v[158:161], v[196:199], v[104:107]
	v_mfma_f32_16x16x32_bf16 v[92:95], v[144:147], v[204:207], v[92:95]
	v_mfma_f32_16x16x32_bf16 v[88:91], v[158:161], v[204:207], v[88:91]
	v_mfma_f32_16x16x32_bf16 v[76:79], v[144:147], v[212:215], v[76:79]
	v_mfma_f32_16x16x32_bf16 v[72:75], v[158:161], v[212:215], v[72:75]
	v_mfma_f32_16x16x32_bf16 v[124:127], v[154:157], v[192:195], v[124:127]
	v_mfma_f32_16x16x32_bf16 v[120:123], v[162:165], v[192:195], v[120:123]
	v_mfma_f32_16x16x32_bf16 v[108:111], v[154:157], v[200:203], v[108:111]
	v_mfma_f32_16x16x32_bf16 v[104:107], v[162:165], v[200:203], v[104:107]
	v_mfma_f32_16x16x32_bf16 v[92:95], v[154:157], v[208:211], v[92:95]
	v_mfma_f32_16x16x32_bf16 v[88:91], v[162:165], v[208:211], v[88:91]
	v_mfma_f32_16x16x32_bf16 v[76:79], v[154:157], v[216:219], v[76:79]
	v_mfma_f32_16x16x32_bf16 v[72:75], v[162:165], v[216:219], v[72:75]
	s_setprio 0
	s_setprio 1
	v_mfma_f32_16x16x32_bf16 v[116:119], v[166:169], v[188:191], v[116:119]
	v_mfma_f32_16x16x32_bf16 v[112:115], v[174:177], v[188:191], v[112:115]
	v_mfma_f32_16x16x32_bf16 v[100:103], v[166:169], v[196:199], v[100:103]
	v_mfma_f32_16x16x32_bf16 v[96:99], v[174:177], v[196:199], v[96:99]
	v_mfma_f32_16x16x32_bf16 v[84:87], v[166:169], v[204:207], v[84:87]
	v_mfma_f32_16x16x32_bf16 v[80:83], v[174:177], v[204:207], v[80:83]
	v_mfma_f32_16x16x32_bf16 v[68:71], v[166:169], v[212:215], v[68:71]
	v_mfma_f32_16x16x32_bf16 v[64:67], v[174:177], v[212:215], v[64:67]
	v_mfma_f32_16x16x32_bf16 v[116:119], v[170:173], v[192:195], v[116:119]
	v_mfma_f32_16x16x32_bf16 v[112:115], v[178:181], v[192:195], v[112:115]
	v_mfma_f32_16x16x32_bf16 v[100:103], v[170:173], v[200:203], v[100:103]
	v_mfma_f32_16x16x32_bf16 v[96:99], v[178:181], v[200:203], v[96:99]
	v_mfma_f32_16x16x32_bf16 v[84:87], v[170:173], v[208:211], v[84:87]
	v_mfma_f32_16x16x32_bf16 v[80:83], v[178:181], v[208:211], v[80:83]
	v_mfma_f32_16x16x32_bf16 v[68:71], v[170:173], v[216:219], v[68:71]
	v_mfma_f32_16x16x32_bf16 v[64:67], v[178:181], v[216:219], v[64:67]
	s_setprio 0
	s_barrier
	s_add_i32 s38, s62, s40
	s_mov_b32 m0, s38
	ds_read_b128 v[188:191], v153 offset:49152
	ds_read_b128 v[192:195], v153 offset:50176
	ds_read_b128 v[196:199], v153 offset:51200
	ds_read_b128 v[200:203], v153 offset:52224
	ds_read_b128 v[204:207], v153 offset:53248
	ds_read_b128 v[208:211], v153 offset:54272
	ds_read_b128 v[212:215], v153 offset:55296
	ds_read_b128 v[216:219], v153 offset:56320
	global_load_lds_dwordx4 v130, s[98:99]
	s_add_i32 m0, s38, 0x2000
	s_add_u32 s36, s36, 0x40080
	s_addc_u32 s37, s37, 0
	s_add_i32 s38, s63, s40
	global_load_lds_dwordx4 v134, s[98:99]
	s_mov_b32 m0, s38
	s_nop 0
	global_load_lds_dwordx4 v130, s[36:37]
	s_add_i32 m0, s38, 0x2000
	s_nop 0
	global_load_lds_dwordx4 v134, s[36:37]
	s_mov_b32 m0, s46
	s_nop 0
	global_load_lds_dwordx4 v128, s[100:101]
	s_mov_b32 m0, s47
	s_nop 0
	global_load_lds_dwordx4 v132, s[100:101]
	s_waitcnt vmcnt(8)
	s_waitcnt lgkmcnt(0)
	s_barrier
	s_setprio 1
	s_waitcnt lgkmcnt(0)
	v_mfma_f32_16x16x32_bf16 v[60:63], v[144:147], v[188:191], v[60:63]
	v_mfma_f32_16x16x32_bf16 v[56:59], v[158:161], v[188:191], v[56:59]
	v_mfma_f32_16x16x32_bf16 v[44:47], v[144:147], v[196:199], v[44:47]
	v_mfma_f32_16x16x32_bf16 v[40:43], v[158:161], v[196:199], v[40:43]
	v_mfma_f32_16x16x32_bf16 v[28:31], v[144:147], v[204:207], v[28:31]
	v_mfma_f32_16x16x32_bf16 v[24:27], v[158:161], v[204:207], v[24:27]
	v_mfma_f32_16x16x32_bf16 v[12:15], v[144:147], v[212:215], v[12:15]
	v_mfma_f32_16x16x32_bf16 v[8:11], v[158:161], v[212:215], v[8:11]
	v_mfma_f32_16x16x32_bf16 v[60:63], v[154:157], v[192:195], v[60:63]
	v_mfma_f32_16x16x32_bf16 v[56:59], v[162:165], v[192:195], v[56:59]
	v_mfma_f32_16x16x32_bf16 v[44:47], v[154:157], v[200:203], v[44:47]
	v_mfma_f32_16x16x32_bf16 v[40:43], v[162:165], v[200:203], v[40:43]
	v_mfma_f32_16x16x32_bf16 v[28:31], v[154:157], v[208:211], v[28:31]
	v_mfma_f32_16x16x32_bf16 v[24:27], v[162:165], v[208:211], v[24:27]
	v_mfma_f32_16x16x32_bf16 v[12:15], v[154:157], v[216:219], v[12:15]
	v_mfma_f32_16x16x32_bf16 v[8:11], v[162:165], v[216:219], v[8:11]
	s_setprio 0
	s_setprio 1
	v_mfma_f32_16x16x32_bf16 v[52:55], v[166:169], v[188:191], v[52:55]
	v_mfma_f32_16x16x32_bf16 v[48:51], v[174:177], v[188:191], v[48:51]
	v_mfma_f32_16x16x32_bf16 v[36:39], v[166:169], v[196:199], v[36:39]
	v_mfma_f32_16x16x32_bf16 v[32:35], v[174:177], v[196:199], v[32:35]
	v_mfma_f32_16x16x32_bf16 v[20:23], v[166:169], v[204:207], v[20:23]
	v_mfma_f32_16x16x32_bf16 v[16:19], v[174:177], v[204:207], v[16:19]
	v_mfma_f32_16x16x32_bf16 v[4:7], v[166:169], v[212:215], v[4:7]
	v_mfma_f32_16x16x32_bf16 v[0:3], v[174:177], v[212:215], v[0:3]
	v_mfma_f32_16x16x32_bf16 v[52:55], v[170:173], v[192:195], v[52:55]
	v_mfma_f32_16x16x32_bf16 v[48:51], v[178:181], v[192:195], v[48:51]
	v_mfma_f32_16x16x32_bf16 v[36:39], v[170:173], v[200:203], v[36:39]
	v_mfma_f32_16x16x32_bf16 v[32:35], v[178:181], v[200:203], v[32:35]
	v_mfma_f32_16x16x32_bf16 v[20:23], v[170:173], v[208:211], v[20:23]
	v_mfma_f32_16x16x32_bf16 v[16:19], v[178:181], v[208:211], v[16:19]
	v_mfma_f32_16x16x32_bf16 v[4:7], v[170:173], v[216:219], v[4:7]
	v_mfma_f32_16x16x32_bf16 v[0:3], v[178:181], v[216:219], v[0:3]
	s_setprio 0
	s_barrier
	s_add_i32 s61, s61, 2
	s_add_u32 s30, s30, 0x100
	s_addc_u32 s31, s31, 0
	s_add_u32 s59, s59, 0x100
	s_addc_u32 s60, s60, 0
	s_cmp_gt_u32 s61, 13
	s_cbranch_scc0 .LBB0_810
	s_and_b64 vcc, exec, s[18:19]
	s_cbranch_vccz .LBB0_813
	s_barrier

; #define PG8_STAGE(bufoff, gbase, voff) do { _Pragma("unroll") for (int _i = 0; _i < 2; ++_i) \
;         __builtin_amdgcn_global_load_lds((const unsigned*)((const char*)(gbase) + (voff)[_i]), (PG8_LAS unsigned*)(lds + (bufoff) + ldsw + _i * 8192), 16, 0, 0); } while (0)
; #define PG8_LDA(dst, b, h) do { _Pragma("unroll") for (int m = 0; m < 4; ++m) _Pragma("unroll") for (int k = 0; k < 2; ++k) dst[m][k] = *(const PG8_LAS bf16x8*)(lds + PG8_SA(b, h) + aoff + m * 2048 + k * 1024); } while (0)
; #define PG8_LDB(dst, b, h) do { _Pragma("unroll") for (int n = 0; n < 2; ++n) _Pragma("unroll") for (int k = 0; k < 2; ++k) dst[n][k] = *(const PG8_LAS bf16x8*)(lds + PG8_SB(b, h) + boff + n * 2048 + k * 1024); } while (0)
; #define PG8_MMA(ai, bj, At, Bt) do { __builtin_amdgcn_s_setprio(1); _Pragma("unroll") for (int m = 0; m < 4; ++m) _Pragma("unroll") for (int n = 0; n < 2; ++n) _Pragma("unroll") for (int k = 0; k < 2; ++k) \
;         acc[ai][bj][m][n] = __builtin_amdgcn_mfma_f32_16x16x32_bf16(Bt[n][k], At[m][k], acc[ai][bj][m][n], 0, 0, 0); __builtin_amdgcn_s_setprio(0); } while (0)
; #define PG8_BAR __builtin_amdgcn_s_barrier()
; template <class Epi, class Sched, bool ALIGN_EPI = false, bool SP2 = false>
; __device__ __forceinline__ void gemm_phase(PG8_LAS unsigned char* lds, const Gemm g, const Sched& S, const Epi& E) {
;     ...
;         const bool has_next = S.next(ui + 1, nxt);
;         const char* nA = has_next ? (const char*)g.A + (size_t)nxt.pm * tstep : cA; const char* nB = has_next ? (const char*)g.Bt + (size_t)nxt.pn * tstep : cB;
;         for (int t = 0; t < nt; t += 2) {
;             const bool last = (t == nt - 2);
;             const char* a1 = cA + (size_t)(t + 1) * kstep;
;             const char* a2 = last ? nA : cA + (size_t)(t + 2) * kstep; const char* b2 = last ? nB : cB + (size_t)(t + 2) * kstep;
;             const char* a3 = a2 + kstep; const char* b3 = b2 + kstep;
;             if (last && has_next) S.a_ready(nxt);
;             if constexpr (SP2) {
;             PG8_LDB(B0, 0, 0); PG8_LDB(B1, 0, 1); PG8_SCHED; PG8_LDA(At, 0, 0); PG8_STAGE(PG8_SA(1, 1), a1 + hstep, voffA);
;             PG8_WAIT_V(8); PG8_WAIT_L(0); PG8_BAR; PG8_MMA(0, 0, At, B0); PG8_MMA(0, 1, At, B1); PG8_BAR; PG8_SCHED;
;             PG8_LDA(At, 0, 1); PG8_STAGE(PG8_SB(0, 0), b2, voffB); PG8_STAGE(PG8_SB(0, 1), b2 + hstep, voffB); PG8_STAGE(PG8_SA(0, 0), a2, voffA);
.LBB0_859:
	s_ashr_i32 s19, s18, 31
	s_lshl_b64 s[20:21], s[18:19], 19
	s_add_u32 s20, s50, s20
	s_addc_u32 s21, s51, s21
	s_and_b64 s[22:23], s[6:7], exec
	s_cselect_b32 s19, s21, s27
	s_cselect_b32 s54, s20, s26
	s_ashr_i32 s17, s16, 31
	s_lshl_b64 s[22:23], s[16:17], 19
	s_add_u32 s22, s33, s22
	s_addc_u32 s23, s34, s23
	s_and_b64 s[30:31], s[6:7], exec
	s_cselect_b32 s17, s23, s29
	s_cselect_b32 s55, s22, s28
	s_add_u32 s26, s26, 0x40080
	s_addc_u32 s27, s27, 0
	s_add_u32 s56, s28, 0x100
	s_addc_u32 s57, s29, 0
	s_mov_b32 s58, -2
	s_lshl_b32 s59, s24, 14
	v_add_u32_e32 v248, s59, v246
	global_load_dwordx4 v[230:233], v248, s[0:1]
	global_load_dwordx4 v[234:237], v248, s[0:1] offset:16
	global_load_dwordx4 v[238:241], v248, s[0:1] offset:32
	global_load_dwordx4 v[242:245], v248, s[0:1] offset:48
	ds_read_b128 v[146:149], v152
	ds_read_b128 v[156:159], v152 offset:1024
	ds_read_b128 v[160:163], v152 offset:2048
	ds_read_b128 v[164:167], v152 offset:3072
	ds_read_b128 v[168:171], v153
	ds_read_b128 v[172:175], v153 offset:1024
	ds_read_b128 v[176:179], v153 offset:2048
	ds_read_b128 v[186:189], v153 offset:3072
	s_add_u32 s28, s26, 0xfffc0080
	s_addc_u32 s29, s27, -1
	s_cmp_eq_u32 s58, 12
	s_cselect_b32 s31, s19, s29
	s_cselect_b32 s30, s54, s28
	s_cselect_b32 s29, s17, s57
	s_cselect_b32 s28, s55, s56
	s_add_i32 m0, s38, 0xc000
	ds_read_b128 v[190:193], v154
	ds_read_b128 v[194:197], v154 offset:1024
	ds_read_b128 v[198:201], v154 offset:2048
	ds_read_b128 v[202:205], v154 offset:3072
	ds_read_b128 v[206:209], v154 offset:4096
	ds_read_b128 v[210:213], v154 offset:5120
	ds_read_b128 v[214:217], v154 offset:6144
	ds_read_b128 v[218:221], v154 offset:7168
	global_load_lds_dwordx4 v138, s[26:27]
	s_add_i32 m0, s38, 0xe000
	s_nop 0
	global_load_lds_dwordx4 v140, s[26:27]
	s_waitcnt vmcnt(20)
	s_waitcnt lgkmcnt(0)
	s_barrier
	s_setprio 1
	s_waitcnt lgkmcnt(0)
	v_mfma_f32_16x16x32_bf16 v[124:127], v[146:149], v[190:193], 0
	v_mfma_f32_16x16x32_bf16 v[120:123], v[160:163], v[190:193], 0
	v_mfma_f32_16x16x32_bf16 v[108:111], v[146:149], v[198:201], 0
	v_mfma_f32_16x16x32_bf16 v[104:107], v[160:163], v[198:201], 0
	v_mfma_f32_16x16x32_bf16 v[92:95], v[146:149], v[206:209], 0
	v_mfma_f32_16x16x32_bf16 v[88:91], v[160:163], v[206:209], 0
	v_mfma_f32_16x16x32_bf16 v[76:79], v[146:149], v[214:217], 0
	v_mfma_f32_16x16x32_bf16 v[72:75], v[160:163], v[214:217], 0
	v_mfma_f32_16x16x32_bf16 v[124:127], v[156:159], v[194:197], v[124:127]
	v_mfma_f32_16x16x32_bf16 v[120:123], v[164:167], v[194:197], v[120:123]
	v_mfma_f32_16x16x32_bf16 v[108:111], v[156:159], v[202:205], v[108:111]
	v_mfma_f32_16x16x32_bf16 v[104:107], v[164:167], v[202:205], v[104:107]
	v_mfma_f32_16x16x32_bf16 v[92:95], v[156:159], v[210:213], v[92:95]
	v_mfma_f32_16x16x32_bf16 v[88:91], v[164:167], v[210:213], v[88:91]
	v_mfma_f32_16x16x32_bf16 v[76:79], v[156:159], v[218:221], v[76:79]
	v_mfma_f32_16x16x32_bf16 v[72:75], v[164:167], v[218:221], v[72:75]
	s_setprio 0
	s_setprio 1
	v_mfma_f32_16x16x32_bf16 v[116:119], v[168:171], v[190:193], 0
	v_mfma_f32_16x16x32_bf16 v[112:115], v[176:179], v[190:193], 0
	v_mfma_f32_16x16x32_bf16 v[100:103], v[168:171], v[198:201], 0
	v_mfma_f32_16x16x32_bf16 v[96:99], v[176:179], v[198:201], 0
	v_mfma_f32_16x16x32_bf16 v[84:87], v[168:171], v[206:209], 0
	v_mfma_f32_16x16x32_bf16 v[80:83], v[176:179], v[206:209], 0
	v_mfma_f32_16x16x32_bf16 v[68:71], v[168:171], v[214:217], 0
	v_mfma_f32_16x16x32_bf16 v[64:67], v[176:179], v[214:217], 0
	v_mfma_f32_16x16x32_bf16 v[116:119], v[172:175], v[194:197], v[116:119]
	v_mfma_f32_16x16x32_bf16 v[112:115], v[186:189], v[194:197], v[112:115]
	v_mfma_f32_16x16x32_bf16 v[100:103], v[172:175], v[202:205], v[100:103]
	v_mfma_f32_16x16x32_bf16 v[96:99], v[186:189], v[202:205], v[96:99]
	v_mfma_f32_16x16x32_bf16 v[84:87], v[172:175], v[210:213], v[84:87]
	v_mfma_f32_16x16x32_bf16 v[80:83], v[186:189], v[210:213], v[80:83]
	v_mfma_f32_16x16x32_bf16 v[68:71], v[172:175], v[218:221], v[68:71]
	v_mfma_f32_16x16x32_bf16 v[64:67], v[186:189], v[218:221], v[64:67]
	s_setprio 0
	s_barrier
	s_add_i32 s59, s45, s35
	s_mov_b32 m0, s59
	ds_read_b128 v[190:193], v154 offset:16384
	ds_read_b128 v[194:197], v154 offset:17408
	ds_read_b128 v[198:201], v154 offset:18432
	ds_read_b128 v[202:205], v154 offset:19456
	ds_read_b128 v[206:209], v154 offset:20480
	ds_read_b128 v[210:213], v154 offset:21504
	ds_read_b128 v[214:217], v154 offset:22528
	ds_read_b128 v[218:221], v154 offset:23552
	global_load_lds_dwordx4 v132, s[28:29]
	s_add_i32 m0, s59, 0x2000
	s_add_u32 s60, s28, 0x40000
	s_addc_u32 s61, s29, 0
	s_add_u32 s98, s28, s12
	s_addc_u32 s99, s29, s13
	s_add_u32 s100, s30, s12
	s_addc_u32 s101, s31, s13
	s_add_i32 s59, s46, s35
	global_load_lds_dwordx4 v128, s[28:29]
	s_mov_b32 m0, s59
	s_nop 0
	global_load_lds_dwordx4 v132, s[60:61]
	s_add_i32 m0, s59, 0x2000
	s_nop 0
	global_load_lds_dwordx4 v128, s[60:61]
	s_mov_b32 m0, s38
	s_nop 0
	global_load_lds_dwordx4 v134, s[30:31]
	s_mov_b32 m0, s39
	s_nop 0
	global_load_lds_dwordx4 v130, s[30:31]
	s_waitcnt vmcnt(20)
	s_waitcnt lgkmcnt(0)
	s_barrier
; #define PG8_STAGE(bufoff, gbase, voff) do { _Pragma("unroll") for (int _i = 0; _i < 2; ++_i) \
;         __builtin_amdgcn_global_load_lds((const unsigned*)((const char*)(gbase) + (voff)[_i]), (PG8_LAS unsigned*)(lds + (bufoff) + ldsw + _i * 8192), 16, 0, 0); } while (0)
; #define PG8_LDA(dst, b, h) do { _Pragma("unroll") for (int m = 0; m < 4; ++m) _Pragma("unroll") for (int k = 0; k < 2; ++k) dst[m][k] = *(const PG8_LAS bf16x8*)(lds + PG8_SA(b, h) + aoff + m * 2048 + k * 1024); } while (0)
; #define PG8_LDB(dst, b, h) do { _Pragma("unroll") for (int n = 0; n < 2; ++n) _Pragma("unroll") for (int k = 0; k < 2; ++k) dst[n][k] = *(const PG8_LAS bf16x8*)(lds + PG8_SB(b, h) + boff + n * 2048 + k * 1024); } while (0)
; #define PG8_MMA(ai, bj, At, Bt) do { __builtin_amdgcn_s_setprio(1); _Pragma("unroll") for (int m = 0; m < 4; ++m) _Pragma("unroll") for (int n = 0; n < 2; ++n) _Pragma("unroll") for (int k = 0; k < 2; ++k) \
;         acc[ai][bj][m][n] = __builtin_amdgcn_mfma_f32_16x16x32_bf16(Bt[n][k], At[m][k], acc[ai][bj][m][n], 0, 0, 0); __builtin_amdgcn_s_setprio(0); } while (0)
; #define PG8_WAIT_V(n) asm volatile("s_waitcnt vmcnt(" #n ")" ::: "memory")
; #define PG8_WAIT_L(n) asm volatile("s_waitcnt lgkmcnt(" #n ")" ::: "memory")
; #define PG8_BAR __builtin_amdgcn_s_barrier()
; #define PG8_SCHED __builtin_amdgcn_sched_barrier(0)
; template <class Epi, class Sched, bool ALIGN_EPI = false, bool SP2 = false>
; __device__ __forceinline__ void gemm_phase(PG8_LAS unsigned char* lds, const Gemm g, const Sched& S, const Epi& E) {
;     ...
;             PG8_WAIT_V(8); PG8_WAIT_L(0); PG8_BAR; PG8_MMA(1, 0, At, B0); PG8_MMA(1, 1, At, B1); PG8_BAR; PG8_SCHED;
;             PG8_LDB(B0, 1, 0); PG8_LDB(B1, 1, 1); PG8_SCHED; PG8_LDA(At, 1, 0); PG8_STAGE(PG8_SA(0, 1), a2 + hstep, voffA);
;             PG8_WAIT_V(8); PG8_WAIT_L(0); PG8_BAR; PG8_MMA(0, 0, At, B0); PG8_MMA(0, 1, At, B1); PG8_BAR; PG8_SCHED;
	s_setprio 1
	s_waitcnt lgkmcnt(0)
	v_mfma_f32_16x16x32_bf16 v[60:63], v[146:149], v[190:193], 0
	v_mfma_f32_16x16x32_bf16 v[56:59], v[160:163], v[190:193], 0
	v_mfma_f32_16x16x32_bf16 v[44:47], v[146:149], v[198:201], 0
	v_mfma_f32_16x16x32_bf16 v[40:43], v[160:163], v[198:201], 0
	v_mfma_f32_16x16x32_bf16 v[28:31], v[146:149], v[206:209], 0
	v_mfma_f32_16x16x32_bf16 v[24:27], v[160:163], v[206:209], 0
	v_mfma_f32_16x16x32_bf16 v[12:15], v[146:149], v[214:217], 0
	v_mfma_f32_16x16x32_bf16 v[8:11], v[160:163], v[214:217], 0
	v_mfma_f32_16x16x32_bf16 v[60:63], v[156:159], v[194:197], v[60:63]
	v_mfma_f32_16x16x32_bf16 v[56:59], v[164:167], v[194:197], v[56:59]
	v_mfma_f32_16x16x32_bf16 v[44:47], v[156:159], v[202:205], v[44:47]
	v_mfma_f32_16x16x32_bf16 v[40:43], v[164:167], v[202:205], v[40:43]
	v_mfma_f32_16x16x32_bf16 v[28:31], v[156:159], v[210:213], v[28:31]
	v_mfma_f32_16x16x32_bf16 v[24:27], v[164:167], v[210:213], v[24:27]
	v_mfma_f32_16x16x32_bf16 v[12:15], v[156:159], v[218:221], v[12:15]
	v_mfma_f32_16x16x32_bf16 v[8:11], v[164:167], v[218:221], v[8:11]
	s_setprio 0
	s_setprio 1
	v_mfma_f32_16x16x32_bf16 v[52:55], v[168:171], v[190:193], 0
	v_mfma_f32_16x16x32_bf16 v[48:51], v[176:179], v[190:193], 0
	v_mfma_f32_16x16x32_bf16 v[36:39], v[168:171], v[198:201], 0
	v_mfma_f32_16x16x32_bf16 v[32:35], v[176:179], v[198:201], 0
	v_mfma_f32_16x16x32_bf16 v[20:23], v[168:171], v[206:209], 0
	v_mfma_f32_16x16x32_bf16 v[16:19], v[176:179], v[206:209], 0
	v_mfma_f32_16x16x32_bf16 v[4:7], v[168:171], v[214:217], 0
	v_mfma_f32_16x16x32_bf16 v[0:3], v[176:179], v[214:217], 0
	v_mfma_f32_16x16x32_bf16 v[52:55], v[172:175], v[194:197], v[52:55]
	v_mfma_f32_16x16x32_bf16 v[48:51], v[186:189], v[194:197], v[48:51]
	v_mfma_f32_16x16x32_bf16 v[36:39], v[172:175], v[202:205], v[36:39]
	v_mfma_f32_16x16x32_bf16 v[32:35], v[186:189], v[202:205], v[32:35]
	v_mfma_f32_16x16x32_bf16 v[20:23], v[172:175], v[210:213], v[20:23]
	v_mfma_f32_16x16x32_bf16 v[16:19], v[186:189], v[210:213], v[16:19]
	v_mfma_f32_16x16x32_bf16 v[4:7], v[172:175], v[218:221], v[4:7]
	v_mfma_f32_16x16x32_bf16 v[0:3], v[186:189], v[218:221], v[0:3]
	s_setprio 0
	s_barrier
	s_add_i32 s59, 0, 0x18000
	s_add_i32 s60, 0, 0x1c000
	v_add_u32_e32 v164, s59, v151
	v_add_u32_e32 v185, s60, v151
	ds_read_b128 v[146:149], v164
	ds_read_b128 v[156:159], v164 offset:1024
	ds_read_b128 v[160:163], v164 offset:2048
	ds_read_b128 v[164:167], v164 offset:3072
	ds_read_b128 v[168:171], v185
	ds_read_b128 v[172:175], v185 offset:1024
	ds_read_b128 v[176:179], v185 offset:2048
	ds_read_b128 v[186:189], v185 offset:3072
	s_add_u32 s30, s30, 0x40000
	s_addc_u32 s31, s31, 0
	s_mov_b32 m0, s40
	ds_read_b128 v[190:193], v154 offset:32768
	ds_read_b128 v[194:197], v154 offset:33792
	ds_read_b128 v[198:201], v154 offset:34816
	ds_read_b128 v[202:205], v154 offset:35840
	ds_read_b128 v[206:209], v154 offset:36864
	ds_read_b128 v[210:213], v154 offset:37888
	ds_read_b128 v[214:217], v154 offset:38912
	ds_read_b128 v[218:221], v154 offset:39936
	global_load_lds_dwordx4 v134, s[30:31]
	s_mov_b32 m0, s41
	s_nop 0
	global_load_lds_dwordx4 v130, s[30:31]
	s_waitcnt vmcnt(8)
	s_waitcnt lgkmcnt(0)
	s_barrier
	s_setprio 1
	s_waitcnt lgkmcnt(0)
	v_mfma_f32_16x16x32_bf16 v[124:127], v[146:149], v[190:193], v[124:127]
	v_mfma_f32_16x16x32_bf16 v[120:123], v[160:163], v[190:193], v[120:123]
	v_mfma_f32_16x16x32_bf16 v[108:111], v[146:149], v[198:201], v[108:111]
	v_mfma_f32_16x16x32_bf16 v[104:107], v[160:163], v[198:201], v[104:107]
	v_mfma_f32_16x16x32_bf16 v[92:95], v[146:149], v[206:209], v[92:95]
	v_mfma_f32_16x16x32_bf16 v[88:91], v[160:163], v[206:209], v[88:91]
	v_mfma_f32_16x16x32_bf16 v[76:79], v[146:149], v[214:217], v[76:79]
	v_mfma_f32_16x16x32_bf16 v[72:75], v[160:163], v[214:217], v[72:75]
	v_mfma_f32_16x16x32_bf16 v[124:127], v[156:159], v[194:197], v[124:127]
	v_mfma_f32_16x16x32_bf16 v[120:123], v[164:167], v[194:197], v[120:123]
	v_mfma_f32_16x16x32_bf16 v[108:111], v[156:159], v[202:205], v[108:111]
	v_mfma_f32_16x16x32_bf16 v[104:107], v[164:167], v[202:205], v[104:107]
	v_mfma_f32_16x16x32_bf16 v[92:95], v[156:159], v[210:213], v[92:95]
	v_mfma_f32_16x16x32_bf16 v[88:91], v[164:167], v[210:213], v[88:91]
	v_mfma_f32_16x16x32_bf16 v[76:79], v[156:159], v[218:221], v[76:79]
	v_mfma_f32_16x16x32_bf16 v[72:75], v[164:167], v[218:221], v[72:75]
	s_setprio 0
	s_setprio 1
	v_mfma_f32_16x16x32_bf16 v[116:119], v[168:171], v[190:193], v[116:119]
	v_mfma_f32_16x16x32_bf16 v[112:115], v[176:179], v[190:193], v[112:115]
	v_mfma_f32_16x16x32_bf16 v[100:103], v[168:171], v[198:201], v[100:103]
	v_mfma_f32_16x16x32_bf16 v[96:99], v[176:179], v[198:201], v[96:99]
	v_mfma_f32_16x16x32_bf16 v[84:87], v[168:171], v[206:209], v[84:87]
	v_mfma_f32_16x16x32_bf16 v[80:83], v[176:179], v[206:209], v[80:83]
	v_mfma_f32_16x16x32_bf16 v[68:71], v[168:171], v[214:217], v[68:71]
	v_mfma_f32_16x16x32_bf16 v[64:67], v[176:179], v[214:217], v[64:67]
	v_mfma_f32_16x16x32_bf16 v[116:119], v[172:175], v[194:197], v[116:119]
	v_mfma_f32_16x16x32_bf16 v[112:115], v[186:189], v[194:197], v[112:115]
	v_mfma_f32_16x16x32_bf16 v[100:103], v[172:175], v[202:205], v[100:103]
	v_mfma_f32_16x16x32_bf16 v[96:99], v[186:189], v[202:205], v[96:99]
	v_mfma_f32_16x16x32_bf16 v[84:87], v[172:175], v[210:213], v[84:87]
	v_mfma_f32_16x16x32_bf16 v[80:83], v[186:189], v[210:213], v[80:83]
	v_mfma_f32_16x16x32_bf16 v[68:71], v[172:175], v[218:221], v[68:71]
	v_mfma_f32_16x16x32_bf16 v[64:67], v[186:189], v[218:221], v[64:67]
	s_setprio 0
	s_barrier
; #define PG8_STAGE(bufoff, gbase, voff) do { _Pragma("unroll") for (int _i = 0; _i < 2; ++_i) \
;         __builtin_amdgcn_global_load_lds((const unsigned*)((const char*)(gbase) + (voff)[_i]), (PG8_LAS unsigned*)(lds + (bufoff) + ldsw + _i * 8192), 16, 0, 0); } while (0)
; #define PG8_LDA(dst, b, h) do { _Pragma("unroll") for (int m = 0; m < 4; ++m) _Pragma("unroll") for (int k = 0; k < 2; ++k) dst[m][k] = *(const PG8_LAS bf16x8*)(lds + PG8_SA(b, h) + aoff + m * 2048 + k * 1024); } while (0)
; #define PG8_LDB(dst, b, h) do { _Pragma("unroll") for (int n = 0; n < 2; ++n) _Pragma("unroll") for (int k = 0; k < 2; ++k) dst[n][k] = *(const PG8_LAS bf16x8*)(lds + PG8_SB(b, h) + boff + n * 2048 + k * 1024); } while (0)
; #define PG8_MMA(ai, bj, At, Bt) do { __builtin_amdgcn_s_setprio(1); _Pragma("unroll") for (int m = 0; m < 4; ++m) _Pragma("unroll") for (int n = 0; n < 2; ++n) _Pragma("unroll") for (int k = 0; k < 2; ++k) \
;         acc[ai][bj][m][n] = __builtin_amdgcn_mfma_f32_16x16x32_bf16(Bt[n][k], At[m][k], acc[ai][bj][m][n], 0, 0, 0); __builtin_amdgcn_s_setprio(0); } while (0)
; #define PG8_WAIT_V(n) asm volatile("s_waitcnt vmcnt(" #n ")" ::: "memory")
; #define PG8_WAIT_L(n) asm volatile("s_waitcnt lgkmcnt(" #n ")" ::: "memory")
; #define PG8_BAR __builtin_amdgcn_s_barrier()
; #define PG8_SCHED __builtin_amdgcn_sched_barrier(0)
; template <class Epi, class Sched, bool ALIGN_EPI = false, bool SP2 = false>
; __device__ __forceinline__ void gemm_phase(PG8_LAS unsigned char* lds, const Gemm g, const Sched& S, const Epi& E) {
;     ...
;         for (int t = 0; t < nt; t += 2) {
;     ...
;             PG8_LDB(B0, 0, 0); PG8_LDB(B1, 0, 1); PG8_SCHED; PG8_LDA(At, 0, 0); PG8_STAGE(PG8_SA(1, 1), a1 + hstep, voffA);
;             PG8_WAIT_V(8); PG8_WAIT_L(0); PG8_BAR; PG8_MMA(0, 0, At, B0); PG8_MMA(0, 1, At, B1); PG8_BAR; PG8_SCHED;
;             PG8_LDA(At, 0, 1); PG8_STAGE(PG8_SB(0, 0), b2, voffB); PG8_STAGE(PG8_SB(0, 1), b2 + hstep, voffB); PG8_STAGE(PG8_SA(0, 0), a2, voffA);
;     ...
;             PG8_LDA(At, 1, 1); PG8_STAGE(PG8_SB(1, 0), b3, voffB); PG8_STAGE(PG8_SB(1, 1), b3 + hstep, voffB); PG8_STAGE(PG8_SA(1, 0), a3, voffA);
;             PG8_WAIT_V(8); PG8_WAIT_L(0); PG8_BAR; PG8_MMA(1, 0, At, B0); PG8_MMA(1, 1, At, B1); PG8_BAR; PG8_SCHED;
	s_add_i32 s30, s59, s35
	s_mov_b32 m0, s30
	ds_read_b128 v[190:193], v154 offset:49152
	ds_read_b128 v[194:197], v154 offset:50176
	ds_read_b128 v[198:201], v154 offset:51200
	ds_read_b128 v[202:205], v154 offset:52224
	ds_read_b128 v[206:209], v154 offset:53248
	ds_read_b128 v[210:213], v154 offset:54272
	ds_read_b128 v[214:217], v154 offset:55296
	ds_read_b128 v[218:221], v154 offset:56320
	global_load_lds_dwordx4 v132, s[98:99]
	s_add_i32 m0, s30, 0x2000
	s_add_u32 s28, s28, 0x40080
	s_addc_u32 s29, s29, 0
	s_add_i32 s30, s60, s35
	global_load_lds_dwordx4 v128, s[98:99]
	s_mov_b32 m0, s30
	s_nop 0
	global_load_lds_dwordx4 v132, s[28:29]
	s_add_i32 m0, s30, 0x2000
	s_nop 0
	global_load_lds_dwordx4 v128, s[28:29]
	s_mov_b32 m0, s42
	s_nop 0
	global_load_lds_dwordx4 v134, s[100:101]
	s_mov_b32 m0, s43
	s_nop 0
	global_load_lds_dwordx4 v130, s[100:101]
	s_waitcnt vmcnt(8)
	s_waitcnt lgkmcnt(0)
	s_barrier
	s_setprio 1
	s_waitcnt lgkmcnt(0)
	v_mfma_f32_16x16x32_bf16 v[60:63], v[146:149], v[190:193], v[60:63]
	v_mfma_f32_16x16x32_bf16 v[56:59], v[160:163], v[190:193], v[56:59]
	v_mfma_f32_16x16x32_bf16 v[44:47], v[146:149], v[198:201], v[44:47]
	v_mfma_f32_16x16x32_bf16 v[40:43], v[160:163], v[198:201], v[40:43]
	v_mfma_f32_16x16x32_bf16 v[28:31], v[146:149], v[206:209], v[28:31]
	v_mfma_f32_16x16x32_bf16 v[24:27], v[160:163], v[206:209], v[24:27]
	v_mfma_f32_16x16x32_bf16 v[12:15], v[146:149], v[214:217], v[12:15]
	v_mfma_f32_16x16x32_bf16 v[8:11], v[160:163], v[214:217], v[8:11]
	v_mfma_f32_16x16x32_bf16 v[60:63], v[156:159], v[194:197], v[60:63]
	v_mfma_f32_16x16x32_bf16 v[56:59], v[164:167], v[194:197], v[56:59]
	v_mfma_f32_16x16x32_bf16 v[44:47], v[156:159], v[202:205], v[44:47]
	v_mfma_f32_16x16x32_bf16 v[40:43], v[164:167], v[202:205], v[40:43]
	v_mfma_f32_16x16x32_bf16 v[28:31], v[156:159], v[210:213], v[28:31]
	v_mfma_f32_16x16x32_bf16 v[24:27], v[164:167], v[210:213], v[24:27]
	v_mfma_f32_16x16x32_bf16 v[12:15], v[156:159], v[218:221], v[12:15]
	v_mfma_f32_16x16x32_bf16 v[8:11], v[164:167], v[218:221], v[8:11]
	s_setprio 0
	s_setprio 1
	v_mfma_f32_16x16x32_bf16 v[52:55], v[168:171], v[190:193], v[52:55]
	v_mfma_f32_16x16x32_bf16 v[48:51], v[176:179], v[190:193], v[48:51]
	v_mfma_f32_16x16x32_bf16 v[36:39], v[168:171], v[198:201], v[36:39]
	v_mfma_f32_16x16x32_bf16 v[32:35], v[176:179], v[198:201], v[32:35]
	v_mfma_f32_16x16x32_bf16 v[20:23], v[168:171], v[206:209], v[20:23]
	v_mfma_f32_16x16x32_bf16 v[16:19], v[176:179], v[206:209], v[16:19]
	v_mfma_f32_16x16x32_bf16 v[4:7], v[168:171], v[214:217], v[4:7]
	v_mfma_f32_16x16x32_bf16 v[0:3], v[176:179], v[214:217], v[0:3]
	v_mfma_f32_16x16x32_bf16 v[52:55], v[172:175], v[194:197], v[52:55]
	v_mfma_f32_16x16x32_bf16 v[48:51], v[186:189], v[194:197], v[48:51]
	v_mfma_f32_16x16x32_bf16 v[36:39], v[172:175], v[202:205], v[36:39]
	v_mfma_f32_16x16x32_bf16 v[32:35], v[186:189], v[202:205], v[32:35]
	v_mfma_f32_16x16x32_bf16 v[20:23], v[172:175], v[210:213], v[20:23]
	v_mfma_f32_16x16x32_bf16 v[16:19], v[186:189], v[210:213], v[16:19]
	v_mfma_f32_16x16x32_bf16 v[4:7], v[172:175], v[218:221], v[4:7]
	v_mfma_f32_16x16x32_bf16 v[0:3], v[186:189], v[218:221], v[0:3]
	s_setprio 0
	s_barrier
	s_add_i32 s58, s58, 2
	s_add_u32 s26, s26, 0x100
	s_addc_u32 s27, s27, 0
	s_add_u32 s56, s56, 0x100
	s_addc_u32 s57, s57, 0
	s_cmp_gt_u32 s58, 13
.LBB0_860:
	ds_read_b128 v[146:149], v152
	ds_read_b128 v[156:159], v152 offset:1024
	ds_read_b128 v[160:163], v152 offset:2048
	ds_read_b128 v[164:167], v152 offset:3072
	ds_read_b128 v[168:171], v153
	ds_read_b128 v[172:175], v153 offset:1024
	ds_read_b128 v[176:179], v153 offset:2048
	ds_read_b128 v[186:189], v153 offset:3072
	s_add_u32 s28, s26, 0xfffc0080
	s_addc_u32 s29, s27, -1
	s_cmp_eq_u32 s58, 12
	s_cselect_b32 s31, s19, s29
	s_cselect_b32 s30, s54, s28
	s_cselect_b32 s29, s17, s57
	s_cselect_b32 s28, s55, s56
	s_add_i32 m0, s38, 0xc000
	ds_read_b128 v[190:193], v154
	ds_read_b128 v[194:197], v154 offset:1024
	ds_read_b128 v[198:201], v154 offset:2048
	ds_read_b128 v[202:205], v154 offset:3072
	ds_read_b128 v[206:209], v154 offset:4096
	ds_read_b128 v[210:213], v154 offset:5120
	ds_read_b128 v[214:217], v154 offset:6144
	ds_read_b128 v[218:221], v154 offset:7168
	global_load_lds_dwordx4 v138, s[26:27]
	s_add_i32 m0, s38, 0xe000
	s_nop 0
	global_load_lds_dwordx4 v140, s[26:27]
	s_waitcnt vmcnt(8)
	s_waitcnt lgkmcnt(0)
	s_barrier
	s_setprio 1
	s_waitcnt lgkmcnt(0)
	v_mfma_f32_16x16x32_bf16 v[124:127], v[146:149], v[190:193], v[124:127]
	v_mfma_f32_16x16x32_bf16 v[120:123], v[160:163], v[190:193], v[120:123]
	v_mfma_f32_16x16x32_bf16 v[108:111], v[146:149], v[198:201], v[108:111]
	v_mfma_f32_16x16x32_bf16 v[104:107], v[160:163], v[198:201], v[104:107]
	v_mfma_f32_16x16x32_bf16 v[92:95], v[146:149], v[206:209], v[92:95]
	v_mfma_f32_16x16x32_bf16 v[88:91], v[160:163], v[206:209], v[88:91]
	v_mfma_f32_16x16x32_bf16 v[76:79], v[146:149], v[214:217], v[76:79]
	v_mfma_f32_16x16x32_bf16 v[72:75], v[160:163], v[214:217], v[72:75]
	v_mfma_f32_16x16x32_bf16 v[124:127], v[156:159], v[194:197], v[124:127]
	v_mfma_f32_16x16x32_bf16 v[120:123], v[164:167], v[194:197], v[120:123]
	v_mfma_f32_16x16x32_bf16 v[108:111], v[156:159], v[202:205], v[108:111]
	v_mfma_f32_16x16x32_bf16 v[104:107], v[164:167], v[202:205], v[104:107]
	v_mfma_f32_16x16x32_bf16 v[92:95], v[156:159], v[210:213], v[92:95]
	v_mfma_f32_16x16x32_bf16 v[88:91], v[164:167], v[210:213], v[88:91]
	v_mfma_f32_16x16x32_bf16 v[76:79], v[156:159], v[218:221], v[76:79]
	v_mfma_f32_16x16x32_bf16 v[72:75], v[164:167], v[218:221], v[72:75]
	s_setprio 0
	s_setprio 1
	v_mfma_f32_16x16x32_bf16 v[116:119], v[168:171], v[190:193], v[116:119]
	v_mfma_f32_16x16x32_bf16 v[112:115], v[176:179], v[190:193], v[112:115]
	v_mfma_f32_16x16x32_bf16 v[100:103], v[168:171], v[198:201], v[100:103]
	v_mfma_f32_16x16x32_bf16 v[96:99], v[176:179], v[198:201], v[96:99]
	v_mfma_f32_16x16x32_bf16 v[84:87], v[168:171], v[206:209], v[84:87]
	v_mfma_f32_16x16x32_bf16 v[80:83], v[176:179], v[206:209], v[80:83]
	v_mfma_f32_16x16x32_bf16 v[68:71], v[168:171], v[214:217], v[68:71]
	v_mfma_f32_16x16x32_bf16 v[64:67], v[176:179], v[214:217], v[64:67]
	v_mfma_f32_16x16x32_bf16 v[116:119], v[172:175], v[194:197], v[116:119]
	v_mfma_f32_16x16x32_bf16 v[112:115], v[186:189], v[194:197], v[112:115]
	v_mfma_f32_16x16x32_bf16 v[100:103], v[172:175], v[202:205], v[100:103]
	v_mfma_f32_16x16x32_bf16 v[96:99], v[186:189], v[202:205], v[96:99]
	v_mfma_f32_16x16x32_bf16 v[84:87], v[172:175], v[210:213], v[84:87]
	v_mfma_f32_16x16x32_bf16 v[80:83], v[186:189], v[210:213], v[80:83]
	v_mfma_f32_16x16x32_bf16 v[68:71], v[172:175], v[218:221], v[68:71]
	v_mfma_f32_16x16x32_bf16 v[64:67], v[186:189], v[218:221], v[64:67]
	s_setprio 0
	s_barrier
; #define PG8_STAGE(bufoff, gbase, voff) do { _Pragma("unroll") for (int _i = 0; _i < 2; ++_i) \
;         __builtin_amdgcn_global_load_lds((const unsigned*)((const char*)(gbase) + (voff)[_i]), (PG8_LAS unsigned*)(lds + (bufoff) + ldsw + _i * 8192), 16, 0, 0); } while (0)
; #define PG8_LDA(dst, b, h) do { _Pragma("unroll") for (int m = 0; m < 4; ++m) _Pragma("unroll") for (int k = 0; k < 2; ++k) dst[m][k] = *(const PG8_LAS bf16x8*)(lds + PG8_SA(b, h) + aoff + m * 2048 + k * 1024); } while (0)
; #define PG8_LDB(dst, b, h) do { _Pragma("unroll") for (int n = 0; n < 2; ++n) _Pragma("unroll") for (int k = 0; k < 2; ++k) dst[n][k] = *(const PG8_LAS bf16x8*)(lds + PG8_SB(b, h) + boff + n * 2048 + k * 1024); } while (0)
; #define PG8_MMA(ai, bj, At, Bt) do { __builtin_amdgcn_s_setprio(1); _Pragma("unroll") for (int m = 0; m < 4; ++m) _Pragma("unroll") for (int n = 0; n < 2; ++n) _Pragma("unroll") for (int k = 0; k < 2; ++k) \
;         acc[ai][bj][m][n] = __builtin_amdgcn_mfma_f32_16x16x32_bf16(Bt[n][k], At[m][k], acc[ai][bj][m][n], 0, 0, 0); __builtin_amdgcn_s_setprio(0); } while (0)
; #define PG8_WAIT_V(n) asm volatile("s_waitcnt vmcnt(" #n ")" ::: "memory")
; #define PG8_WAIT_L(n) asm volatile("s_waitcnt lgkmcnt(" #n ")" ::: "memory")
; #define PG8_BAR __builtin_amdgcn_s_barrier()
; #define PG8_SCHED __builtin_amdgcn_sched_barrier(0)
; template <class Epi, class Sched, bool ALIGN_EPI = false, bool SP2 = false>
; __device__ __forceinline__ void gemm_phase(PG8_LAS unsigned char* lds, const Gemm g, const Sched& S, const Epi& E) {
;     ...
;             PG8_LDA(At, 0, 1); PG8_STAGE(PG8_SB(0, 0), b2, voffB); PG8_STAGE(PG8_SB(0, 1), b2 + hstep, voffB); PG8_STAGE(PG8_SA(0, 0), a2, voffA);
;             PG8_WAIT_V(8); PG8_WAIT_L(0); PG8_BAR; PG8_MMA(1, 0, At, B0); PG8_MMA(1, 1, At, B1); PG8_BAR; PG8_SCHED;
;             PG8_LDB(B0, 1, 0); PG8_LDB(B1, 1, 1); PG8_SCHED; PG8_LDA(At, 1, 0); PG8_STAGE(PG8_SA(0, 1), a2 + hstep, voffA);
;             PG8_WAIT_V(8); PG8_WAIT_L(0); PG8_BAR; PG8_MMA(0, 0, At, B0); PG8_MMA(0, 1, At, B1); PG8_BAR; PG8_SCHED;
	s_add_i32 s59, s45, s35
	s_mov_b32 m0, s59
	ds_read_b128 v[190:193], v154 offset:16384
	ds_read_b128 v[194:197], v154 offset:17408
	ds_read_b128 v[198:201], v154 offset:18432
	ds_read_b128 v[202:205], v154 offset:19456
	ds_read_b128 v[206:209], v154 offset:20480
	ds_read_b128 v[210:213], v154 offset:21504
	ds_read_b128 v[214:217], v154 offset:22528
	ds_read_b128 v[218:221], v154 offset:23552
	global_load_lds_dwordx4 v132, s[28:29]
	s_add_i32 m0, s59, 0x2000
	s_add_u32 s60, s28, 0x40000
	s_addc_u32 s61, s29, 0
	s_add_u32 s98, s28, s12
	s_addc_u32 s99, s29, s13
	s_add_u32 s100, s30, s12
	s_addc_u32 s101, s31, s13
	s_add_i32 s59, s46, s35
	global_load_lds_dwordx4 v128, s[28:29]
	s_mov_b32 m0, s59
	s_nop 0
	global_load_lds_dwordx4 v132, s[60:61]
	s_add_i32 m0, s59, 0x2000
	s_nop 0
	global_load_lds_dwordx4 v128, s[60:61]
	s_mov_b32 m0, s38
	s_nop 0
	global_load_lds_dwordx4 v134, s[30:31]
	s_mov_b32 m0, s39
	s_nop 0
	global_load_lds_dwordx4 v130, s[30:31]
	s_waitcnt vmcnt(8)
	s_waitcnt lgkmcnt(0)
	s_barrier
	s_setprio 1
	s_waitcnt lgkmcnt(0)
	v_mfma_f32_16x16x32_bf16 v[60:63], v[146:149], v[190:193], v[60:63]
	v_mfma_f32_16x16x32_bf16 v[56:59], v[160:163], v[190:193], v[56:59]
	v_mfma_f32_16x16x32_bf16 v[44:47], v[146:149], v[198:201], v[44:47]
	v_mfma_f32_16x16x32_bf16 v[40:43], v[160:163], v[198:201], v[40:43]
	v_mfma_f32_16x16x32_bf16 v[28:31], v[146:149], v[206:209], v[28:31]
	v_mfma_f32_16x16x32_bf16 v[24:27], v[160:163], v[206:209], v[24:27]
	v_mfma_f32_16x16x32_bf16 v[12:15], v[146:149], v[214:217], v[12:15]
	v_mfma_f32_16x16x32_bf16 v[8:11], v[160:163], v[214:217], v[8:11]
	v_mfma_f32_16x16x32_bf16 v[60:63], v[156:159], v[194:197], v[60:63]
	v_mfma_f32_16x16x32_bf16 v[56:59], v[164:167], v[194:197], v[56:59]
	v_mfma_f32_16x16x32_bf16 v[44:47], v[156:159], v[202:205], v[44:47]
	v_mfma_f32_16x16x32_bf16 v[40:43], v[164:167], v[202:205], v[40:43]
	v_mfma_f32_16x16x32_bf16 v[28:31], v[156:159], v[210:213], v[28:31]
	v_mfma_f32_16x16x32_bf16 v[24:27], v[164:167], v[210:213], v[24:27]
	v_mfma_f32_16x16x32_bf16 v[12:15], v[156:159], v[218:221], v[12:15]
	v_mfma_f32_16x16x32_bf16 v[8:11], v[164:167], v[218:221], v[8:11]
	s_setprio 0
	s_setprio 1
	v_mfma_f32_16x16x32_bf16 v[52:55], v[168:171], v[190:193], v[52:55]
	v_mfma_f32_16x16x32_bf16 v[48:51], v[176:179], v[190:193], v[48:51]
	v_mfma_f32_16x16x32_bf16 v[36:39], v[168:171], v[198:201], v[36:39]
	v_mfma_f32_16x16x32_bf16 v[32:35], v[176:179], v[198:201], v[32:35]
	v_mfma_f32_16x16x32_bf16 v[20:23], v[168:171], v[206:209], v[20:23]
	v_mfma_f32_16x16x32_bf16 v[16:19], v[176:179], v[206:209], v[16:19]
	v_mfma_f32_16x16x32_bf16 v[4:7], v[168:171], v[214:217], v[4:7]
	v_mfma_f32_16x16x32_bf16 v[0:3], v[176:179], v[214:217], v[0:3]
	v_mfma_f32_16x16x32_bf16 v[52:55], v[172:175], v[194:197], v[52:55]
	v_mfma_f32_16x16x32_bf16 v[48:51], v[186:189], v[194:197], v[48:51]
	v_mfma_f32_16x16x32_bf16 v[36:39], v[172:175], v[202:205], v[36:39]
	v_mfma_f32_16x16x32_bf16 v[32:35], v[186:189], v[202:205], v[32:35]
	v_mfma_f32_16x16x32_bf16 v[20:23], v[172:175], v[210:213], v[20:23]
	v_mfma_f32_16x16x32_bf16 v[16:19], v[186:189], v[210:213], v[16:19]
	v_mfma_f32_16x16x32_bf16 v[4:7], v[172:175], v[218:221], v[4:7]
	v_mfma_f32_16x16x32_bf16 v[0:3], v[186:189], v[218:221], v[0:3]
	s_setprio 0
	s_barrier
	s_add_i32 s59, 0, 0x18000
	s_add_i32 s60, 0, 0x1c000
	v_add_u32_e32 v164, s59, v151
	v_add_u32_e32 v185, s60, v151
	ds_read_b128 v[146:149], v164
	ds_read_b128 v[156:159], v164 offset:1024
	ds_read_b128 v[160:163], v164 offset:2048
	ds_read_b128 v[164:167], v164 offset:3072
	ds_read_b128 v[168:171], v185
	ds_read_b128 v[172:175], v185 offset:1024
	ds_read_b128 v[176:179], v185 offset:2048
	ds_read_b128 v[186:189], v185 offset:3072
	s_add_u32 s30, s30, 0x40000
	s_addc_u32 s31, s31, 0
	s_mov_b32 m0, s40
	ds_read_b128 v[190:193], v154 offset:32768
	ds_read_b128 v[194:197], v154 offset:33792
	ds_read_b128 v[198:201], v154 offset:34816
	ds_read_b128 v[202:205], v154 offset:35840
	ds_read_b128 v[206:209], v154 offset:36864
	ds_read_b128 v[210:213], v154 offset:37888
	ds_read_b128 v[214:217], v154 offset:38912
	ds_read_b128 v[218:221], v154 offset:39936
	global_load_lds_dwordx4 v134, s[30:31]
	s_mov_b32 m0, s41
	s_nop 0
	global_load_lds_dwordx4 v130, s[30:31]
	s_waitcnt vmcnt(8)
	s_waitcnt lgkmcnt(0)
	s_barrier
; #define PG8_STAGE(bufoff, gbase, voff) do { _Pragma("unroll") for (int _i = 0; _i < 2; ++_i) \
;         __builtin_amdgcn_global_load_lds((const unsigned*)((const char*)(gbase) + (voff)[_i]), (PG8_LAS unsigned*)(lds + (bufoff) + ldsw + _i * 8192), 16, 0, 0); } while (0)
; #define PG8_LDA(dst, b, h) do { _Pragma("unroll") for (int m = 0; m < 4; ++m) _Pragma("unroll") for (int k = 0; k < 2; ++k) dst[m][k] = *(const PG8_LAS bf16x8*)(lds + PG8_SA(b, h) + aoff + m * 2048 + k * 1024); } while (0)
; #define PG8_MMA(ai, bj, At, Bt) do { __builtin_amdgcn_s_setprio(1); _Pragma("unroll") for (int m = 0; m < 4; ++m) _Pragma("unroll") for (int n = 0; n < 2; ++n) _Pragma("unroll") for (int k = 0; k < 2; ++k) \
;         acc[ai][bj][m][n] = __builtin_amdgcn_mfma_f32_16x16x32_bf16(Bt[n][k], At[m][k], acc[ai][bj][m][n], 0, 0, 0); __builtin_amdgcn_s_setprio(0); } while (0)
; #define PG8_WAIT_V(n) asm volatile("s_waitcnt vmcnt(" #n ")" ::: "memory")
; #define PG8_WAIT_L(n) asm volatile("s_waitcnt lgkmcnt(" #n ")" ::: "memory")
; #define PG8_BAR __builtin_amdgcn_s_barrier()
; #define PG8_SCHED __builtin_amdgcn_sched_barrier(0)
; template <class Epi, class Sched, bool ALIGN_EPI = false, bool SP2 = false>
; __device__ __forceinline__ void gemm_phase(PG8_LAS unsigned char* lds, const Gemm g, const Sched& S, const Epi& E) {
;     ...
;         for (int t = 0; t < nt; t += 2) {
;     ...
;             PG8_WAIT_V(8); PG8_WAIT_L(0); PG8_BAR; PG8_MMA(0, 0, At, B0); PG8_MMA(0, 1, At, B1); PG8_BAR; PG8_SCHED;
;             PG8_LDA(At, 1, 1); PG8_STAGE(PG8_SB(1, 0), b3, voffB); PG8_STAGE(PG8_SB(1, 1), b3 + hstep, voffB); PG8_STAGE(PG8_SA(1, 0), a3, voffA);
;             PG8_WAIT_V(8); PG8_WAIT_L(0); PG8_BAR; PG8_MMA(1, 0, At, B0); PG8_MMA(1, 1, At, B1); PG8_BAR; PG8_SCHED;
	s_setprio 1
	s_waitcnt lgkmcnt(0)
	v_mfma_f32_16x16x32_bf16 v[124:127], v[146:149], v[190:193], v[124:127]
	v_mfma_f32_16x16x32_bf16 v[120:123], v[160:163], v[190:193], v[120:123]
	v_mfma_f32_16x16x32_bf16 v[108:111], v[146:149], v[198:201], v[108:111]
	v_mfma_f32_16x16x32_bf16 v[104:107], v[160:163], v[198:201], v[104:107]
	v_mfma_f32_16x16x32_bf16 v[92:95], v[146:149], v[206:209], v[92:95]
	v_mfma_f32_16x16x32_bf16 v[88:91], v[160:163], v[206:209], v[88:91]
	v_mfma_f32_16x16x32_bf16 v[76:79], v[146:149], v[214:217], v[76:79]
	v_mfma_f32_16x16x32_bf16 v[72:75], v[160:163], v[214:217], v[72:75]
	v_mfma_f32_16x16x32_bf16 v[124:127], v[156:159], v[194:197], v[124:127]
	v_mfma_f32_16x16x32_bf16 v[120:123], v[164:167], v[194:197], v[120:123]
	v_mfma_f32_16x16x32_bf16 v[108:111], v[156:159], v[202:205], v[108:111]
	v_mfma_f32_16x16x32_bf16 v[104:107], v[164:167], v[202:205], v[104:107]
	v_mfma_f32_16x16x32_bf16 v[92:95], v[156:159], v[210:213], v[92:95]
	v_mfma_f32_16x16x32_bf16 v[88:91], v[164:167], v[210:213], v[88:91]
	v_mfma_f32_16x16x32_bf16 v[76:79], v[156:159], v[218:221], v[76:79]
	v_mfma_f32_16x16x32_bf16 v[72:75], v[164:167], v[218:221], v[72:75]
	s_setprio 0
	s_setprio 1
	v_mfma_f32_16x16x32_bf16 v[116:119], v[168:171], v[190:193], v[116:119]
	v_mfma_f32_16x16x32_bf16 v[112:115], v[176:179], v[190:193], v[112:115]
	v_mfma_f32_16x16x32_bf16 v[100:103], v[168:171], v[198:201], v[100:103]
	v_mfma_f32_16x16x32_bf16 v[96:99], v[176:179], v[198:201], v[96:99]
	v_mfma_f32_16x16x32_bf16 v[84:87], v[168:171], v[206:209], v[84:87]
	v_mfma_f32_16x16x32_bf16 v[80:83], v[176:179], v[206:209], v[80:83]
	v_mfma_f32_16x16x32_bf16 v[68:71], v[168:171], v[214:217], v[68:71]
	v_mfma_f32_16x16x32_bf16 v[64:67], v[176:179], v[214:217], v[64:67]
	v_mfma_f32_16x16x32_bf16 v[116:119], v[172:175], v[194:197], v[116:119]
	v_mfma_f32_16x16x32_bf16 v[112:115], v[186:189], v[194:197], v[112:115]
	v_mfma_f32_16x16x32_bf16 v[100:103], v[172:175], v[202:205], v[100:103]
	v_mfma_f32_16x16x32_bf16 v[96:99], v[186:189], v[202:205], v[96:99]
	v_mfma_f32_16x16x32_bf16 v[84:87], v[172:175], v[210:213], v[84:87]
	v_mfma_f32_16x16x32_bf16 v[80:83], v[186:189], v[210:213], v[80:83]
	v_mfma_f32_16x16x32_bf16 v[68:71], v[172:175], v[218:221], v[68:71]
	v_mfma_f32_16x16x32_bf16 v[64:67], v[186:189], v[218:221], v[64:67]
	s_setprio 0
	s_barrier
	s_add_i32 s30, s59, s35
	s_mov_b32 m0, s30
	ds_read_b128 v[190:193], v154 offset:49152
	ds_read_b128 v[194:197], v154 offset:50176
	ds_read_b128 v[198:201], v154 offset:51200
	ds_read_b128 v[202:205], v154 offset:52224
	ds_read_b128 v[206:209], v154 offset:53248
	ds_read_b128 v[210:213], v154 offset:54272
	ds_read_b128 v[214:217], v154 offset:55296
	ds_read_b128 v[218:221], v154 offset:56320
	global_load_lds_dwordx4 v132, s[98:99]
	s_add_i32 m0, s30, 0x2000
	s_add_u32 s28, s28, 0x40080
	s_addc_u32 s29, s29, 0
	s_add_i32 s30, s60, s35
	global_load_lds_dwordx4 v128, s[98:99]
	s_mov_b32 m0, s30
	s_nop 0
	global_load_lds_dwordx4 v132, s[28:29]
	s_add_i32 m0, s30, 0x2000
	s_nop 0
	global_load_lds_dwordx4 v128, s[28:29]
	s_mov_b32 m0, s42
	s_nop 0
	global_load_lds_dwordx4 v134, s[100:101]
	s_mov_b32 m0, s43
	s_nop 0
	global_load_lds_dwordx4 v130, s[100:101]
	s_waitcnt vmcnt(8)
	s_waitcnt lgkmcnt(0)
	s_barrier
	s_setprio 1
	s_waitcnt lgkmcnt(0)
	v_mfma_f32_16x16x32_bf16 v[60:63], v[146:149], v[190:193], v[60:63]
	v_mfma_f32_16x16x32_bf16 v[56:59], v[160:163], v[190:193], v[56:59]
	v_mfma_f32_16x16x32_bf16 v[44:47], v[146:149], v[198:201], v[44:47]
	v_mfma_f32_16x16x32_bf16 v[40:43], v[160:163], v[198:201], v[40:43]
	v_mfma_f32_16x16x32_bf16 v[28:31], v[146:149], v[206:209], v[28:31]
	v_mfma_f32_16x16x32_bf16 v[24:27], v[160:163], v[206:209], v[24:27]
	v_mfma_f32_16x16x32_bf16 v[12:15], v[146:149], v[214:217], v[12:15]
	v_mfma_f32_16x16x32_bf16 v[8:11], v[160:163], v[214:217], v[8:11]
	v_mfma_f32_16x16x32_bf16 v[60:63], v[156:159], v[194:197], v[60:63]
	v_mfma_f32_16x16x32_bf16 v[56:59], v[164:167], v[194:197], v[56:59]
	v_mfma_f32_16x16x32_bf16 v[44:47], v[156:159], v[202:205], v[44:47]
	v_mfma_f32_16x16x32_bf16 v[40:43], v[164:167], v[202:205], v[40:43]
	v_mfma_f32_16x16x32_bf16 v[28:31], v[156:159], v[210:213], v[28:31]
	v_mfma_f32_16x16x32_bf16 v[24:27], v[164:167], v[210:213], v[24:27]
	v_mfma_f32_16x16x32_bf16 v[12:15], v[156:159], v[218:221], v[12:15]
	v_mfma_f32_16x16x32_bf16 v[8:11], v[164:167], v[218:221], v[8:11]
	s_setprio 0
	s_setprio 1
	v_mfma_f32_16x16x32_bf16 v[52:55], v[168:171], v[190:193], v[52:55]
	v_mfma_f32_16x16x32_bf16 v[48:51], v[176:179], v[190:193], v[48:51]
	v_mfma_f32_16x16x32_bf16 v[36:39], v[168:171], v[198:201], v[36:39]
	v_mfma_f32_16x16x32_bf16 v[32:35], v[176:179], v[198:201], v[32:35]
	v_mfma_f32_16x16x32_bf16 v[20:23], v[168:171], v[206:209], v[20:23]
	v_mfma_f32_16x16x32_bf16 v[16:19], v[176:179], v[206:209], v[16:19]
	v_mfma_f32_16x16x32_bf16 v[4:7], v[168:171], v[214:217], v[4:7]
	v_mfma_f32_16x16x32_bf16 v[0:3], v[176:179], v[214:217], v[0:3]
	v_mfma_f32_16x16x32_bf16 v[52:55], v[172:175], v[194:197], v[52:55]
	v_mfma_f32_16x16x32_bf16 v[48:51], v[186:189], v[194:197], v[48:51]
	v_mfma_f32_16x16x32_bf16 v[36:39], v[172:175], v[202:205], v[36:39]
	v_mfma_f32_16x16x32_bf16 v[32:35], v[186:189], v[202:205], v[32:35]
	v_mfma_f32_16x16x32_bf16 v[20:23], v[172:175], v[210:213], v[20:23]
	v_mfma_f32_16x16x32_bf16 v[16:19], v[186:189], v[210:213], v[16:19]
	v_mfma_f32_16x16x32_bf16 v[4:7], v[172:175], v[218:221], v[4:7]
	v_mfma_f32_16x16x32_bf16 v[0:3], v[186:189], v[218:221], v[0:3]
	s_setprio 0
	s_barrier
	s_add_i32 s58, s58, 2
	s_add_u32 s26, s26, 0x100
	s_addc_u32 s27, s27, 0
	s_add_u32 s56, s56, 0x100
	s_addc_u32 s57, s57, 0
	s_cmp_gt_u32 s58, 13
	s_cbranch_scc0 .LBB0_860
	s_and_b64 vcc, exec, s[14:15]
	s_cbranch_vccz .LBB0_863
	s_barrier

; #define PG8_STAGE(bufoff, gbase, voff) do { _Pragma("unroll") for (int _i = 0; _i < 2; ++_i) \
;         __builtin_amdgcn_global_load_lds((const unsigned*)((const char*)(gbase) + (voff)[_i]), (PG8_LAS unsigned*)(lds + (bufoff) + ldsw + _i * 8192), 16, 0, 0); } while (0)
; #define PG8_LDA(dst, b, h) do { _Pragma("unroll") for (int m = 0; m < 4; ++m) _Pragma("unroll") for (int k = 0; k < 2; ++k) dst[m][k] = *(const PG8_LAS bf16x8*)(lds + PG8_SA(b, h) + aoff + m * 2048 + k * 1024); } while (0)
; #define PG8_LDB(dst, b, h) do { _Pragma("unroll") for (int n = 0; n < 2; ++n) _Pragma("unroll") for (int k = 0; k < 2; ++k) dst[n][k] = *(const PG8_LAS bf16x8*)(lds + PG8_SB(b, h) + boff + n * 2048 + k * 1024); } while (0)
; #define PG8_MMA(ai, bj, At, Bt) do { __builtin_amdgcn_s_setprio(1); _Pragma("unroll") for (int m = 0; m < 4; ++m) _Pragma("unroll") for (int n = 0; n < 2; ++n) _Pragma("unroll") for (int k = 0; k < 2; ++k) \
;         acc[ai][bj][m][n] = __builtin_amdgcn_mfma_f32_16x16x32_bf16(Bt[n][k], At[m][k], acc[ai][bj][m][n], 0, 0, 0); __builtin_amdgcn_s_setprio(0); } while (0)
; #define PG8_WAIT_V(n) asm volatile("s_waitcnt vmcnt(" #n ")" ::: "memory")
; #define PG8_WAIT_L(n) asm volatile("s_waitcnt lgkmcnt(" #n ")" ::: "memory")
; #define PG8_BAR __builtin_amdgcn_s_barrier()
; #define PG8_SCHED __builtin_amdgcn_sched_barrier(0)
; template <class Epi, class Sched, bool ALIGN_EPI = false, bool SP2 = false>
; __device__ __forceinline__ void gemm_phase(PG8_LAS unsigned char* lds, const Gemm g, const Sched& S, const Epi& E) {
;     ...
;             PG8_LDB(B0, 0, 0); PG8_LDB(B1, 0, 1); PG8_SCHED; PG8_LDA(At, 0, 0); PG8_STAGE(PG8_SA(1, 1), a1 + hstep, voffA);
;             PG8_WAIT_V(8); PG8_WAIT_L(0); PG8_BAR; PG8_MMA(0, 0, At, B0); PG8_MMA(0, 1, At, B1); PG8_BAR; PG8_SCHED;
;             PG8_LDA(At, 0, 1); PG8_STAGE(PG8_SB(0, 0), b2, voffB); PG8_STAGE(PG8_SB(0, 1), b2 + hstep, voffB); PG8_STAGE(PG8_SA(0, 0), a2, voffA);
;             PG8_WAIT_V(8); PG8_WAIT_L(0); PG8_BAR; PG8_MMA(1, 0, At, B0); PG8_MMA(1, 1, At, B1); PG8_BAR; PG8_SCHED;
;             PG8_LDB(B0, 1, 0); PG8_LDB(B1, 1, 1); PG8_SCHED; PG8_LDA(At, 1, 0); PG8_STAGE(PG8_SA(0, 1), a2 + hstep, voffA);
;             PG8_WAIT_V(8); PG8_WAIT_L(0); PG8_BAR; PG8_MMA(0, 0, At, B0); PG8_MMA(0, 1, At, B1); PG8_BAR; PG8_SCHED;
.Lsk5_nokoff:
	s_add_u32 s25, s18, 0x100
	s_addc_u32 s46, s19, 0
	s_mov_b32 s47, -2
	s_waitcnt vmcnt(0)
	ds_read_b128 v[172:175], v169
	ds_read_b128 v[176:179], v169 offset:1024
	ds_read_b128 v[180:183], v169 offset:2048
	ds_read_b128 v[184:187], v169 offset:3072
	ds_read_b128 v[188:191], v170
	ds_read_b128 v[192:195], v170 offset:1024
	ds_read_b128 v[196:199], v170 offset:2048
	ds_read_b128 v[200:203], v170 offset:3072
	s_add_u32 s18, s16, 0x100
	s_addc_u32 s19, s17, 0
	s_cmp_eq_u32 s47, s98
	s_cselect_b32 s23, s5, s19
	s_cselect_b32 s22, s4, s18
	s_cselect_b32 s21, s15, s46
	s_cselect_b32 s20, s14, s25
	s_add_i32 m0, s31, 0xc000
	ds_read_b128 v[204:207], v160
	ds_read_b128 v[208:211], v160 offset:1024
	ds_read_b128 v[212:215], v160 offset:2048
	ds_read_b128 v[216:219], v160 offset:3072
	ds_read_b128 v[220:223], v160 offset:4096
	ds_read_b128 v[224:227], v160 offset:5120
	ds_read_b128 v[228:231], v160 offset:6144
	ds_read_b128 v[232:235], v160 offset:7168
	global_load_lds_dwordx4 v138, s[16:17]
	s_add_i32 m0, s31, 0xe000
	s_nop 0
	global_load_lds_dwordx4 v140, s[16:17]
	s_waitcnt vmcnt(8)
	s_waitcnt lgkmcnt(0)
	s_barrier
	s_setprio 1
	s_waitcnt lgkmcnt(0)
	v_mfma_f32_16x16x32_bf16 v[124:127], v[172:175], v[204:207], 0
	v_mfma_f32_16x16x32_bf16 v[120:123], v[180:183], v[204:207], 0
	v_mfma_f32_16x16x32_bf16 v[108:111], v[172:175], v[212:215], 0
	v_mfma_f32_16x16x32_bf16 v[104:107], v[180:183], v[212:215], 0
	v_mfma_f32_16x16x32_bf16 v[92:95], v[172:175], v[220:223], 0
	v_mfma_f32_16x16x32_bf16 v[88:91], v[180:183], v[220:223], 0
	v_mfma_f32_16x16x32_bf16 v[76:79], v[172:175], v[228:231], 0
	v_mfma_f32_16x16x32_bf16 v[72:75], v[180:183], v[228:231], 0
	v_mfma_f32_16x16x32_bf16 v[124:127], v[176:179], v[208:211], v[124:127]
	v_mfma_f32_16x16x32_bf16 v[120:123], v[184:187], v[208:211], v[120:123]
	v_mfma_f32_16x16x32_bf16 v[108:111], v[176:179], v[216:219], v[108:111]
	v_mfma_f32_16x16x32_bf16 v[104:107], v[184:187], v[216:219], v[104:107]
	v_mfma_f32_16x16x32_bf16 v[92:95], v[176:179], v[224:227], v[92:95]
	v_mfma_f32_16x16x32_bf16 v[88:91], v[184:187], v[224:227], v[88:91]
	v_mfma_f32_16x16x32_bf16 v[76:79], v[176:179], v[232:235], v[76:79]
	v_mfma_f32_16x16x32_bf16 v[72:75], v[184:187], v[232:235], v[72:75]
	s_setprio 0
	s_setprio 1
	v_mfma_f32_16x16x32_bf16 v[116:119], v[188:191], v[204:207], 0
	v_mfma_f32_16x16x32_bf16 v[112:115], v[196:199], v[204:207], 0
	v_mfma_f32_16x16x32_bf16 v[100:103], v[188:191], v[212:215], 0
	v_mfma_f32_16x16x32_bf16 v[96:99], v[196:199], v[212:215], 0
	v_mfma_f32_16x16x32_bf16 v[84:87], v[188:191], v[220:223], 0
	v_mfma_f32_16x16x32_bf16 v[80:83], v[196:199], v[220:223], 0
	v_mfma_f32_16x16x32_bf16 v[68:71], v[188:191], v[228:231], 0
	v_mfma_f32_16x16x32_bf16 v[64:67], v[196:199], v[228:231], 0
	v_mfma_f32_16x16x32_bf16 v[116:119], v[192:195], v[208:211], v[116:119]
	v_mfma_f32_16x16x32_bf16 v[112:115], v[200:203], v[208:211], v[112:115]
	v_mfma_f32_16x16x32_bf16 v[100:103], v[192:195], v[216:219], v[100:103]
	v_mfma_f32_16x16x32_bf16 v[96:99], v[200:203], v[216:219], v[96:99]
	v_mfma_f32_16x16x32_bf16 v[84:87], v[192:195], v[224:227], v[84:87]
	v_mfma_f32_16x16x32_bf16 v[80:83], v[200:203], v[224:227], v[80:83]
	v_mfma_f32_16x16x32_bf16 v[68:71], v[192:195], v[232:235], v[68:71]
	v_mfma_f32_16x16x32_bf16 v[64:67], v[200:203], v[232:235], v[64:67]
	s_setprio 0
	s_barrier
	s_add_i32 s16, s41, s28
	s_mov_b32 m0, s16
	ds_read_b128 v[204:207], v160 offset:16384
	ds_read_b128 v[208:211], v160 offset:17408
	ds_read_b128 v[212:215], v160 offset:18432
	ds_read_b128 v[216:219], v160 offset:19456
	ds_read_b128 v[220:223], v160 offset:20480
	ds_read_b128 v[224:227], v160 offset:21504
	ds_read_b128 v[228:231], v160 offset:22528
	ds_read_b128 v[232:235], v160 offset:23552
	global_load_lds_dwordx4 v132, s[20:21]
	s_add_i32 m0, s16, 0x2000
	s_add_u32 s16, s20, 0xb0000
	s_addc_u32 s17, s21, 0
	s_add_u32 s94, s20, s10
	s_addc_u32 s95, s21, s11
	s_add_u32 s96, s22, s10
	s_addc_u32 s97, s23, s11
	s_add_i32 s48, s42, s28
	global_load_lds_dwordx4 v128, s[20:21]
	s_mov_b32 m0, s48
	s_nop 0
	global_load_lds_dwordx4 v132, s[16:17]
	s_add_i32 m0, s48, 0x2000
	s_nop 0
	global_load_lds_dwordx4 v128, s[16:17]
	s_mov_b32 m0, s31
	s_nop 0
	global_load_lds_dwordx4 v134, s[22:23]
	s_mov_b32 m0, s33
	s_nop 0
	global_load_lds_dwordx4 v130, s[22:23]
	s_waitcnt vmcnt(8)
	s_waitcnt lgkmcnt(0)
	s_barrier
	s_setprio 1
	s_waitcnt lgkmcnt(0)
	v_mfma_f32_16x16x32_bf16 v[60:63], v[172:175], v[204:207], 0
	v_mfma_f32_16x16x32_bf16 v[56:59], v[180:183], v[204:207], 0
	v_mfma_f32_16x16x32_bf16 v[44:47], v[172:175], v[212:215], 0
	v_mfma_f32_16x16x32_bf16 v[40:43], v[180:183], v[212:215], 0
	v_mfma_f32_16x16x32_bf16 v[28:31], v[172:175], v[220:223], 0
	v_mfma_f32_16x16x32_bf16 v[24:27], v[180:183], v[220:223], 0
	v_mfma_f32_16x16x32_bf16 v[12:15], v[172:175], v[228:231], 0
	v_mfma_f32_16x16x32_bf16 v[8:11], v[180:183], v[228:231], 0
	v_mfma_f32_16x16x32_bf16 v[60:63], v[176:179], v[208:211], v[60:63]
	v_mfma_f32_16x16x32_bf16 v[56:59], v[184:187], v[208:211], v[56:59]
	v_mfma_f32_16x16x32_bf16 v[44:47], v[176:179], v[216:219], v[44:47]
	v_mfma_f32_16x16x32_bf16 v[40:43], v[184:187], v[216:219], v[40:43]
	v_mfma_f32_16x16x32_bf16 v[28:31], v[176:179], v[224:227], v[28:31]
	v_mfma_f32_16x16x32_bf16 v[24:27], v[184:187], v[224:227], v[24:27]
	v_mfma_f32_16x16x32_bf16 v[12:15], v[176:179], v[232:235], v[12:15]
	v_mfma_f32_16x16x32_bf16 v[8:11], v[184:187], v[232:235], v[8:11]
	s_setprio 0
	s_setprio 1
	v_mfma_f32_16x16x32_bf16 v[52:55], v[188:191], v[204:207], 0
	v_mfma_f32_16x16x32_bf16 v[48:51], v[196:199], v[204:207], 0
	v_mfma_f32_16x16x32_bf16 v[36:39], v[188:191], v[212:215], 0
	v_mfma_f32_16x16x32_bf16 v[32:35], v[196:199], v[212:215], 0
	v_mfma_f32_16x16x32_bf16 v[20:23], v[188:191], v[220:223], 0
	v_mfma_f32_16x16x32_bf16 v[16:19], v[196:199], v[220:223], 0
	v_mfma_f32_16x16x32_bf16 v[4:7], v[188:191], v[228:231], 0
	v_mfma_f32_16x16x32_bf16 v[0:3], v[196:199], v[228:231], 0
	v_mfma_f32_16x16x32_bf16 v[52:55], v[192:195], v[208:211], v[52:55]
	v_mfma_f32_16x16x32_bf16 v[48:51], v[200:203], v[208:211], v[48:51]
	v_mfma_f32_16x16x32_bf16 v[36:39], v[192:195], v[216:219], v[36:39]
	v_mfma_f32_16x16x32_bf16 v[32:35], v[200:203], v[216:219], v[32:35]
	v_mfma_f32_16x16x32_bf16 v[20:23], v[192:195], v[224:227], v[20:23]
	v_mfma_f32_16x16x32_bf16 v[16:19], v[200:203], v[224:227], v[16:19]
	v_mfma_f32_16x16x32_bf16 v[4:7], v[192:195], v[232:235], v[4:7]
	v_mfma_f32_16x16x32_bf16 v[0:3], v[200:203], v[232:235], v[0:3]
	s_setprio 0
	s_barrier
; #define PG8_STAGE(bufoff, gbase, voff) do { _Pragma("unroll") for (int _i = 0; _i < 2; ++_i) \
;         __builtin_amdgcn_global_load_lds((const unsigned*)((const char*)(gbase) + (voff)[_i]), (PG8_LAS unsigned*)(lds + (bufoff) + ldsw + _i * 8192), 16, 0, 0); } while (0)
; #define PG8_LDA(dst, b, h) do { _Pragma("unroll") for (int m = 0; m < 4; ++m) _Pragma("unroll") for (int k = 0; k < 2; ++k) dst[m][k] = *(const PG8_LAS bf16x8*)(lds + PG8_SA(b, h) + aoff + m * 2048 + k * 1024); } while (0)
; #define PG8_LDB(dst, b, h) do { _Pragma("unroll") for (int n = 0; n < 2; ++n) _Pragma("unroll") for (int k = 0; k < 2; ++k) dst[n][k] = *(const PG8_LAS bf16x8*)(lds + PG8_SB(b, h) + boff + n * 2048 + k * 1024); } while (0)
; #define PG8_MMA(ai, bj, At, Bt) do { __builtin_amdgcn_s_setprio(1); _Pragma("unroll") for (int m = 0; m < 4; ++m) _Pragma("unroll") for (int n = 0; n < 2; ++n) _Pragma("unroll") for (int k = 0; k < 2; ++k) \
;         acc[ai][bj][m][n] = __builtin_amdgcn_mfma_f32_16x16x32_bf16(Bt[n][k], At[m][k], acc[ai][bj][m][n], 0, 0, 0); __builtin_amdgcn_s_setprio(0); } while (0)
; #define PG8_WAIT_V(n) asm volatile("s_waitcnt vmcnt(" #n ")" ::: "memory")
; #define PG8_WAIT_L(n) asm volatile("s_waitcnt lgkmcnt(" #n ")" ::: "memory")
; #define PG8_BAR __builtin_amdgcn_s_barrier()
; #define PG8_SCHED __builtin_amdgcn_sched_barrier(0)
; template <class Epi, class Sched, bool ALIGN_EPI = false, bool SP2 = false>
; __device__ __forceinline__ void gemm_phase(PG8_LAS unsigned char* lds, const Gemm g, const Sched& S, const Epi& E) {
;     ...
;         for (int t = 0; t < nt; t += 2) {
;     ...
;             PG8_LDB(B0, 1, 0); PG8_LDB(B1, 1, 1); PG8_SCHED; PG8_LDA(At, 1, 0); PG8_STAGE(PG8_SA(0, 1), a2 + hstep, voffA);
;             PG8_WAIT_V(8); PG8_WAIT_L(0); PG8_BAR; PG8_MMA(0, 0, At, B0); PG8_MMA(0, 1, At, B1); PG8_BAR; PG8_SCHED;
;             PG8_LDA(At, 1, 1); PG8_STAGE(PG8_SB(1, 0), b3, voffB); PG8_STAGE(PG8_SB(1, 1), b3 + hstep, voffB); PG8_STAGE(PG8_SA(1, 0), a3, voffA);
;             PG8_WAIT_V(8); PG8_WAIT_L(0); PG8_BAR; PG8_MMA(1, 0, At, B0); PG8_MMA(1, 1, At, B1); PG8_BAR; PG8_SCHED;
	s_add_i32 s48, 0, 0x18000
	v_add_u32_e32 v143, s48, v159
	s_add_i32 s49, 0, 0x1c000
	ds_read_b128 v[172:175], v143
	ds_read_b128 v[176:179], v143 offset:1024
	ds_read_b128 v[180:183], v143 offset:2048
	ds_read_b128 v[184:187], v143 offset:3072
	v_add_u32_e32 v143, s49, v159
	ds_read_b128 v[188:191], v143
	ds_read_b128 v[192:195], v143 offset:1024
	ds_read_b128 v[196:199], v143 offset:2048
	ds_read_b128 v[200:203], v143 offset:3072
	s_add_u32 s16, s22, 0xb0000
	s_addc_u32 s17, s23, 0
	s_mov_b32 m0, s34
	ds_read_b128 v[204:207], v160 offset:32768
	ds_read_b128 v[208:211], v160 offset:33792
	ds_read_b128 v[212:215], v160 offset:34816
	ds_read_b128 v[216:219], v160 offset:35840
	ds_read_b128 v[220:223], v160 offset:36864
	ds_read_b128 v[224:227], v160 offset:37888
	ds_read_b128 v[228:231], v160 offset:38912
	ds_read_b128 v[232:235], v160 offset:39936
	global_load_lds_dwordx4 v134, s[16:17]
	s_mov_b32 m0, s35
	s_nop 0
	global_load_lds_dwordx4 v130, s[16:17]
	s_waitcnt vmcnt(8)
	s_waitcnt lgkmcnt(0)
	s_barrier
	s_setprio 1
	s_waitcnt lgkmcnt(0)
	v_mfma_f32_16x16x32_bf16 v[124:127], v[172:175], v[204:207], v[124:127]
	v_mfma_f32_16x16x32_bf16 v[120:123], v[180:183], v[204:207], v[120:123]
	v_mfma_f32_16x16x32_bf16 v[108:111], v[172:175], v[212:215], v[108:111]
	v_mfma_f32_16x16x32_bf16 v[104:107], v[180:183], v[212:215], v[104:107]
	v_mfma_f32_16x16x32_bf16 v[92:95], v[172:175], v[220:223], v[92:95]
	v_mfma_f32_16x16x32_bf16 v[88:91], v[180:183], v[220:223], v[88:91]
	v_mfma_f32_16x16x32_bf16 v[76:79], v[172:175], v[228:231], v[76:79]
	v_mfma_f32_16x16x32_bf16 v[72:75], v[180:183], v[228:231], v[72:75]
	v_mfma_f32_16x16x32_bf16 v[124:127], v[176:179], v[208:211], v[124:127]
	v_mfma_f32_16x16x32_bf16 v[120:123], v[184:187], v[208:211], v[120:123]
	v_mfma_f32_16x16x32_bf16 v[108:111], v[176:179], v[216:219], v[108:111]
	v_mfma_f32_16x16x32_bf16 v[104:107], v[184:187], v[216:219], v[104:107]
	v_mfma_f32_16x16x32_bf16 v[92:95], v[176:179], v[224:227], v[92:95]
	v_mfma_f32_16x16x32_bf16 v[88:91], v[184:187], v[224:227], v[88:91]
	v_mfma_f32_16x16x32_bf16 v[76:79], v[176:179], v[232:235], v[76:79]
	v_mfma_f32_16x16x32_bf16 v[72:75], v[184:187], v[232:235], v[72:75]
	s_setprio 0
	s_setprio 1
	v_mfma_f32_16x16x32_bf16 v[116:119], v[188:191], v[204:207], v[116:119]
	v_mfma_f32_16x16x32_bf16 v[112:115], v[196:199], v[204:207], v[112:115]
	v_mfma_f32_16x16x32_bf16 v[100:103], v[188:191], v[212:215], v[100:103]
	v_mfma_f32_16x16x32_bf16 v[96:99], v[196:199], v[212:215], v[96:99]
	v_mfma_f32_16x16x32_bf16 v[84:87], v[188:191], v[220:223], v[84:87]
	v_mfma_f32_16x16x32_bf16 v[80:83], v[196:199], v[220:223], v[80:83]
	v_mfma_f32_16x16x32_bf16 v[68:71], v[188:191], v[228:231], v[68:71]
	v_mfma_f32_16x16x32_bf16 v[64:67], v[196:199], v[228:231], v[64:67]
	v_mfma_f32_16x16x32_bf16 v[116:119], v[192:195], v[208:211], v[116:119]
	v_mfma_f32_16x16x32_bf16 v[112:115], v[200:203], v[208:211], v[112:115]
	v_mfma_f32_16x16x32_bf16 v[100:103], v[192:195], v[216:219], v[100:103]
	v_mfma_f32_16x16x32_bf16 v[96:99], v[200:203], v[216:219], v[96:99]
	v_mfma_f32_16x16x32_bf16 v[84:87], v[192:195], v[224:227], v[84:87]
	v_mfma_f32_16x16x32_bf16 v[80:83], v[200:203], v[224:227], v[80:83]
	v_mfma_f32_16x16x32_bf16 v[68:71], v[192:195], v[232:235], v[68:71]
	v_mfma_f32_16x16x32_bf16 v[64:67], v[200:203], v[232:235], v[64:67]
	s_setprio 0
	s_barrier
	s_add_i32 s16, s48, s28
	s_mov_b32 m0, s16
	ds_read_b128 v[204:207], v160 offset:49152
	ds_read_b128 v[208:211], v160 offset:50176
	ds_read_b128 v[212:215], v160 offset:51200
	ds_read_b128 v[216:219], v160 offset:52224
	ds_read_b128 v[220:223], v160 offset:53248
	ds_read_b128 v[224:227], v160 offset:54272
	ds_read_b128 v[228:231], v160 offset:55296
	ds_read_b128 v[232:235], v160 offset:56320
	global_load_lds_dwordx4 v132, s[94:95]
	s_add_i32 m0, s16, 0x2000
	s_add_u32 s16, s20, 0xb0080
	s_addc_u32 s17, s21, 0
	s_add_i32 s20, s49, s28
	global_load_lds_dwordx4 v128, s[94:95]
	s_mov_b32 m0, s20
	s_nop 0
	global_load_lds_dwordx4 v132, s[16:17]
	s_add_i32 m0, s20, 0x2000
	s_nop 0
	global_load_lds_dwordx4 v128, s[16:17]
	s_mov_b32 m0, s38
	s_nop 0
	global_load_lds_dwordx4 v134, s[96:97]
	s_mov_b32 m0, s39
	s_nop 0
	global_load_lds_dwordx4 v130, s[96:97]
	s_waitcnt vmcnt(8)
	s_waitcnt lgkmcnt(0)
	s_barrier
	s_setprio 1
	s_waitcnt lgkmcnt(0)
	v_mfma_f32_16x16x32_bf16 v[60:63], v[172:175], v[204:207], v[60:63]
	v_mfma_f32_16x16x32_bf16 v[56:59], v[180:183], v[204:207], v[56:59]
	v_mfma_f32_16x16x32_bf16 v[44:47], v[172:175], v[212:215], v[44:47]
	v_mfma_f32_16x16x32_bf16 v[40:43], v[180:183], v[212:215], v[40:43]
	v_mfma_f32_16x16x32_bf16 v[28:31], v[172:175], v[220:223], v[28:31]
	v_mfma_f32_16x16x32_bf16 v[24:27], v[180:183], v[220:223], v[24:27]
	v_mfma_f32_16x16x32_bf16 v[12:15], v[172:175], v[228:231], v[12:15]
	v_mfma_f32_16x16x32_bf16 v[8:11], v[180:183], v[228:231], v[8:11]
	v_mfma_f32_16x16x32_bf16 v[60:63], v[176:179], v[208:211], v[60:63]
	v_mfma_f32_16x16x32_bf16 v[56:59], v[184:187], v[208:211], v[56:59]
	v_mfma_f32_16x16x32_bf16 v[44:47], v[176:179], v[216:219], v[44:47]
	v_mfma_f32_16x16x32_bf16 v[40:43], v[184:187], v[216:219], v[40:43]
	v_mfma_f32_16x16x32_bf16 v[28:31], v[176:179], v[224:227], v[28:31]
	v_mfma_f32_16x16x32_bf16 v[24:27], v[184:187], v[224:227], v[24:27]
	v_mfma_f32_16x16x32_bf16 v[12:15], v[176:179], v[232:235], v[12:15]
	v_mfma_f32_16x16x32_bf16 v[8:11], v[184:187], v[232:235], v[8:11]
	s_setprio 0
	s_setprio 1
	v_mfma_f32_16x16x32_bf16 v[52:55], v[188:191], v[204:207], v[52:55]
	v_mfma_f32_16x16x32_bf16 v[48:51], v[196:199], v[204:207], v[48:51]
	v_mfma_f32_16x16x32_bf16 v[36:39], v[188:191], v[212:215], v[36:39]
	v_mfma_f32_16x16x32_bf16 v[32:35], v[196:199], v[212:215], v[32:35]
	v_mfma_f32_16x16x32_bf16 v[20:23], v[188:191], v[220:223], v[20:23]
	v_mfma_f32_16x16x32_bf16 v[16:19], v[196:199], v[220:223], v[16:19]
	v_mfma_f32_16x16x32_bf16 v[4:7], v[188:191], v[228:231], v[4:7]
	v_mfma_f32_16x16x32_bf16 v[0:3], v[196:199], v[228:231], v[0:3]
	v_mfma_f32_16x16x32_bf16 v[52:55], v[192:195], v[208:211], v[52:55]
	v_mfma_f32_16x16x32_bf16 v[48:51], v[200:203], v[208:211], v[48:51]
	v_mfma_f32_16x16x32_bf16 v[36:39], v[192:195], v[216:219], v[36:39]
	v_mfma_f32_16x16x32_bf16 v[32:35], v[200:203], v[216:219], v[32:35]
	v_mfma_f32_16x16x32_bf16 v[20:23], v[192:195], v[224:227], v[20:23]
	v_mfma_f32_16x16x32_bf16 v[16:19], v[200:203], v[224:227], v[16:19]
	v_mfma_f32_16x16x32_bf16 v[4:7], v[192:195], v[232:235], v[4:7]
	v_mfma_f32_16x16x32_bf16 v[0:3], v[200:203], v[232:235], v[0:3]
	s_setprio 0
	s_barrier
	s_add_i32 s47, s47, 2
	s_add_u32 s25, s25, 0x100
	s_addc_u32 s46, s46, 0
	s_cmp_gt_u32 s47, s99
	s_mov_b64 s[16:17], s[18:19]
; #define PG8_STAGE(bufoff, gbase, voff) do { _Pragma("unroll") for (int _i = 0; _i < 2; ++_i) \
;         __builtin_amdgcn_global_load_lds((const unsigned*)((const char*)(gbase) + (voff)[_i]), (PG8_LAS unsigned*)(lds + (bufoff) + ldsw + _i * 8192), 16, 0, 0); } while (0)
; #define PG8_LDA(dst, b, h) do { _Pragma("unroll") for (int m = 0; m < 4; ++m) _Pragma("unroll") for (int k = 0; k < 2; ++k) dst[m][k] = *(const PG8_LAS bf16x8*)(lds + PG8_SA(b, h) + aoff + m * 2048 + k * 1024); } while (0)
; #define PG8_LDB(dst, b, h) do { _Pragma("unroll") for (int n = 0; n < 2; ++n) _Pragma("unroll") for (int k = 0; k < 2; ++k) dst[n][k] = *(const PG8_LAS bf16x8*)(lds + PG8_SB(b, h) + boff + n * 2048 + k * 1024); } while (0)
; #define PG8_MMA(ai, bj, At, Bt) do { __builtin_amdgcn_s_setprio(1); _Pragma("unroll") for (int m = 0; m < 4; ++m) _Pragma("unroll") for (int n = 0; n < 2; ++n) _Pragma("unroll") for (int k = 0; k < 2; ++k) \
;         acc[ai][bj][m][n] = __builtin_amdgcn_mfma_f32_16x16x32_bf16(Bt[n][k], At[m][k], acc[ai][bj][m][n], 0, 0, 0); __builtin_amdgcn_s_setprio(0); } while (0)
; #define PG8_WAIT_V(n) asm volatile("s_waitcnt vmcnt(" #n ")" ::: "memory")
; #define PG8_WAIT_L(n) asm volatile("s_waitcnt lgkmcnt(" #n ")" ::: "memory")
; #define PG8_BAR __builtin_amdgcn_s_barrier()
; #define PG8_SCHED __builtin_amdgcn_sched_barrier(0)
; template <class Epi, class Sched, bool ALIGN_EPI = false, bool SP2 = false>
; __device__ __forceinline__ void gemm_phase(PG8_LAS unsigned char* lds, const Gemm g, const Sched& S, const Epi& E) {
;     ...
;             PG8_LDB(B0, 0, 0); PG8_LDB(B1, 0, 1); PG8_SCHED; PG8_LDA(At, 0, 0); PG8_STAGE(PG8_SA(1, 1), a1 + hstep, voffA);
;             PG8_WAIT_V(8); PG8_WAIT_L(0); PG8_BAR; PG8_MMA(0, 0, At, B0); PG8_MMA(0, 1, At, B1); PG8_BAR; PG8_SCHED;
;             PG8_LDA(At, 0, 1); PG8_STAGE(PG8_SB(0, 0), b2, voffB); PG8_STAGE(PG8_SB(0, 1), b2 + hstep, voffB); PG8_STAGE(PG8_SA(0, 0), a2, voffA);
;             PG8_WAIT_V(8); PG8_WAIT_L(0); PG8_BAR; PG8_MMA(1, 0, At, B0); PG8_MMA(1, 1, At, B1); PG8_BAR; PG8_SCHED;
;             PG8_LDB(B0, 1, 0); PG8_LDB(B1, 1, 1); PG8_SCHED; PG8_LDA(At, 1, 0); PG8_STAGE(PG8_SA(0, 1), a2 + hstep, voffA);
;             PG8_WAIT_V(8); PG8_WAIT_L(0); PG8_BAR; PG8_MMA(0, 0, At, B0); PG8_MMA(0, 1, At, B1); PG8_BAR; PG8_SCHED;
.LBB0_898:
	ds_read_b128 v[172:175], v169
	ds_read_b128 v[176:179], v169 offset:1024
	ds_read_b128 v[180:183], v169 offset:2048
	ds_read_b128 v[184:187], v169 offset:3072
	ds_read_b128 v[188:191], v170
	ds_read_b128 v[192:195], v170 offset:1024
	ds_read_b128 v[196:199], v170 offset:2048
	ds_read_b128 v[200:203], v170 offset:3072
	s_add_u32 s18, s16, 0x100
	s_addc_u32 s19, s17, 0
	s_cmp_eq_u32 s47, s98
	s_cselect_b32 s23, s5, s19
	s_cselect_b32 s22, s4, s18
	s_cselect_b32 s21, s15, s46
	s_cselect_b32 s20, s14, s25
	s_add_i32 m0, s31, 0xc000
	ds_read_b128 v[204:207], v160
	ds_read_b128 v[208:211], v160 offset:1024
	ds_read_b128 v[212:215], v160 offset:2048
	ds_read_b128 v[216:219], v160 offset:3072
	ds_read_b128 v[220:223], v160 offset:4096
	ds_read_b128 v[224:227], v160 offset:5120
	ds_read_b128 v[228:231], v160 offset:6144
	ds_read_b128 v[232:235], v160 offset:7168
	global_load_lds_dwordx4 v138, s[16:17]
	s_add_i32 m0, s31, 0xe000
	s_nop 0
	global_load_lds_dwordx4 v140, s[16:17]
	s_waitcnt vmcnt(8)
	s_waitcnt lgkmcnt(0)
	s_barrier
	s_setprio 1
	s_waitcnt lgkmcnt(0)
	v_mfma_f32_16x16x32_bf16 v[124:127], v[172:175], v[204:207], v[124:127]
	v_mfma_f32_16x16x32_bf16 v[120:123], v[180:183], v[204:207], v[120:123]
	v_mfma_f32_16x16x32_bf16 v[108:111], v[172:175], v[212:215], v[108:111]
	v_mfma_f32_16x16x32_bf16 v[104:107], v[180:183], v[212:215], v[104:107]
	v_mfma_f32_16x16x32_bf16 v[92:95], v[172:175], v[220:223], v[92:95]
	v_mfma_f32_16x16x32_bf16 v[88:91], v[180:183], v[220:223], v[88:91]
	v_mfma_f32_16x16x32_bf16 v[76:79], v[172:175], v[228:231], v[76:79]
	v_mfma_f32_16x16x32_bf16 v[72:75], v[180:183], v[228:231], v[72:75]
	v_mfma_f32_16x16x32_bf16 v[124:127], v[176:179], v[208:211], v[124:127]
	v_mfma_f32_16x16x32_bf16 v[120:123], v[184:187], v[208:211], v[120:123]
	v_mfma_f32_16x16x32_bf16 v[108:111], v[176:179], v[216:219], v[108:111]
	v_mfma_f32_16x16x32_bf16 v[104:107], v[184:187], v[216:219], v[104:107]
	v_mfma_f32_16x16x32_bf16 v[92:95], v[176:179], v[224:227], v[92:95]
	v_mfma_f32_16x16x32_bf16 v[88:91], v[184:187], v[224:227], v[88:91]
	v_mfma_f32_16x16x32_bf16 v[76:79], v[176:179], v[232:235], v[76:79]
	v_mfma_f32_16x16x32_bf16 v[72:75], v[184:187], v[232:235], v[72:75]
	s_setprio 0
	s_setprio 1
	v_mfma_f32_16x16x32_bf16 v[116:119], v[188:191], v[204:207], v[116:119]
	v_mfma_f32_16x16x32_bf16 v[112:115], v[196:199], v[204:207], v[112:115]
	v_mfma_f32_16x16x32_bf16 v[100:103], v[188:191], v[212:215], v[100:103]
	v_mfma_f32_16x16x32_bf16 v[96:99], v[196:199], v[212:215], v[96:99]
	v_mfma_f32_16x16x32_bf16 v[84:87], v[188:191], v[220:223], v[84:87]
	v_mfma_f32_16x16x32_bf16 v[80:83], v[196:199], v[220:223], v[80:83]
	v_mfma_f32_16x16x32_bf16 v[68:71], v[188:191], v[228:231], v[68:71]
	v_mfma_f32_16x16x32_bf16 v[64:67], v[196:199], v[228:231], v[64:67]
	v_mfma_f32_16x16x32_bf16 v[116:119], v[192:195], v[208:211], v[116:119]
	v_mfma_f32_16x16x32_bf16 v[112:115], v[200:203], v[208:211], v[112:115]
	v_mfma_f32_16x16x32_bf16 v[100:103], v[192:195], v[216:219], v[100:103]
	v_mfma_f32_16x16x32_bf16 v[96:99], v[200:203], v[216:219], v[96:99]
	v_mfma_f32_16x16x32_bf16 v[84:87], v[192:195], v[224:227], v[84:87]
	v_mfma_f32_16x16x32_bf16 v[80:83], v[200:203], v[224:227], v[80:83]
	v_mfma_f32_16x16x32_bf16 v[68:71], v[192:195], v[232:235], v[68:71]
	v_mfma_f32_16x16x32_bf16 v[64:67], v[200:203], v[232:235], v[64:67]
	s_setprio 0
	s_barrier
	s_add_i32 s16, s41, s28
	s_mov_b32 m0, s16
	ds_read_b128 v[204:207], v160 offset:16384
	ds_read_b128 v[208:211], v160 offset:17408
	ds_read_b128 v[212:215], v160 offset:18432
	ds_read_b128 v[216:219], v160 offset:19456
	ds_read_b128 v[220:223], v160 offset:20480
	ds_read_b128 v[224:227], v160 offset:21504
	ds_read_b128 v[228:231], v160 offset:22528
	ds_read_b128 v[232:235], v160 offset:23552
	global_load_lds_dwordx4 v132, s[20:21]
	s_add_i32 m0, s16, 0x2000
	s_add_u32 s16, s20, 0xb0000
	s_addc_u32 s17, s21, 0
	s_add_u32 s94, s20, s10
	s_addc_u32 s95, s21, s11
	s_add_u32 s96, s22, s10
	s_addc_u32 s97, s23, s11
	s_add_i32 s48, s42, s28
	global_load_lds_dwordx4 v128, s[20:21]
	s_mov_b32 m0, s48
	s_nop 0
	global_load_lds_dwordx4 v132, s[16:17]
	s_add_i32 m0, s48, 0x2000
	s_nop 0
	global_load_lds_dwordx4 v128, s[16:17]
	s_mov_b32 m0, s31
	s_nop 0
	global_load_lds_dwordx4 v134, s[22:23]
	s_mov_b32 m0, s33
	s_nop 0
	global_load_lds_dwordx4 v130, s[22:23]
	s_waitcnt vmcnt(8)
	s_waitcnt lgkmcnt(0)
	s_barrier
	s_setprio 1
	s_waitcnt lgkmcnt(0)
	v_mfma_f32_16x16x32_bf16 v[60:63], v[172:175], v[204:207], v[60:63]
	v_mfma_f32_16x16x32_bf16 v[56:59], v[180:183], v[204:207], v[56:59]
	v_mfma_f32_16x16x32_bf16 v[44:47], v[172:175], v[212:215], v[44:47]
	v_mfma_f32_16x16x32_bf16 v[40:43], v[180:183], v[212:215], v[40:43]
	v_mfma_f32_16x16x32_bf16 v[28:31], v[172:175], v[220:223], v[28:31]
	v_mfma_f32_16x16x32_bf16 v[24:27], v[180:183], v[220:223], v[24:27]
	v_mfma_f32_16x16x32_bf16 v[12:15], v[172:175], v[228:231], v[12:15]
	v_mfma_f32_16x16x32_bf16 v[8:11], v[180:183], v[228:231], v[8:11]
	v_mfma_f32_16x16x32_bf16 v[60:63], v[176:179], v[208:211], v[60:63]
	v_mfma_f32_16x16x32_bf16 v[56:59], v[184:187], v[208:211], v[56:59]
	v_mfma_f32_16x16x32_bf16 v[44:47], v[176:179], v[216:219], v[44:47]
	v_mfma_f32_16x16x32_bf16 v[40:43], v[184:187], v[216:219], v[40:43]
	v_mfma_f32_16x16x32_bf16 v[28:31], v[176:179], v[224:227], v[28:31]
	v_mfma_f32_16x16x32_bf16 v[24:27], v[184:187], v[224:227], v[24:27]
	v_mfma_f32_16x16x32_bf16 v[12:15], v[176:179], v[232:235], v[12:15]
	v_mfma_f32_16x16x32_bf16 v[8:11], v[184:187], v[232:235], v[8:11]
	s_setprio 0
	s_setprio 1
	v_mfma_f32_16x16x32_bf16 v[52:55], v[188:191], v[204:207], v[52:55]
	v_mfma_f32_16x16x32_bf16 v[48:51], v[196:199], v[204:207], v[48:51]
	v_mfma_f32_16x16x32_bf16 v[36:39], v[188:191], v[212:215], v[36:39]
	v_mfma_f32_16x16x32_bf16 v[32:35], v[196:199], v[212:215], v[32:35]
	v_mfma_f32_16x16x32_bf16 v[20:23], v[188:191], v[220:223], v[20:23]
	v_mfma_f32_16x16x32_bf16 v[16:19], v[196:199], v[220:223], v[16:19]
	v_mfma_f32_16x16x32_bf16 v[4:7], v[188:191], v[228:231], v[4:7]
	v_mfma_f32_16x16x32_bf16 v[0:3], v[196:199], v[228:231], v[0:3]
	v_mfma_f32_16x16x32_bf16 v[52:55], v[192:195], v[208:211], v[52:55]
	v_mfma_f32_16x16x32_bf16 v[48:51], v[200:203], v[208:211], v[48:51]
	v_mfma_f32_16x16x32_bf16 v[36:39], v[192:195], v[216:219], v[36:39]
	v_mfma_f32_16x16x32_bf16 v[32:35], v[200:203], v[216:219], v[32:35]
	v_mfma_f32_16x16x32_bf16 v[20:23], v[192:195], v[224:227], v[20:23]
	v_mfma_f32_16x16x32_bf16 v[16:19], v[200:203], v[224:227], v[16:19]
	v_mfma_f32_16x16x32_bf16 v[4:7], v[192:195], v[232:235], v[4:7]
	v_mfma_f32_16x16x32_bf16 v[0:3], v[200:203], v[232:235], v[0:3]
	s_setprio 0
	s_barrier
; #define PG8_STAGE(bufoff, gbase, voff) do { _Pragma("unroll") for (int _i = 0; _i < 2; ++_i) \
;         __builtin_amdgcn_global_load_lds((const unsigned*)((const char*)(gbase) + (voff)[_i]), (PG8_LAS unsigned*)(lds + (bufoff) + ldsw + _i * 8192), 16, 0, 0); } while (0)
; #define PG8_LDA(dst, b, h) do { _Pragma("unroll") for (int m = 0; m < 4; ++m) _Pragma("unroll") for (int k = 0; k < 2; ++k) dst[m][k] = *(const PG8_LAS bf16x8*)(lds + PG8_SA(b, h) + aoff + m * 2048 + k * 1024); } while (0)
; #define PG8_LDB(dst, b, h) do { _Pragma("unroll") for (int n = 0; n < 2; ++n) _Pragma("unroll") for (int k = 0; k < 2; ++k) dst[n][k] = *(const PG8_LAS bf16x8*)(lds + PG8_SB(b, h) + boff + n * 2048 + k * 1024); } while (0)
; #define PG8_MMA(ai, bj, At, Bt) do { __builtin_amdgcn_s_setprio(1); _Pragma("unroll") for (int m = 0; m < 4; ++m) _Pragma("unroll") for (int n = 0; n < 2; ++n) _Pragma("unroll") for (int k = 0; k < 2; ++k) \
;         acc[ai][bj][m][n] = __builtin_amdgcn_mfma_f32_16x16x32_bf16(Bt[n][k], At[m][k], acc[ai][bj][m][n], 0, 0, 0); __builtin_amdgcn_s_setprio(0); } while (0)
; #define PG8_WAIT_V(n) asm volatile("s_waitcnt vmcnt(" #n ")" ::: "memory")
; #define PG8_WAIT_L(n) asm volatile("s_waitcnt lgkmcnt(" #n ")" ::: "memory")
; #define PG8_BAR __builtin_amdgcn_s_barrier()
; #define PG8_SCHED __builtin_amdgcn_sched_barrier(0)
; template <class Epi, class Sched, bool ALIGN_EPI = false, bool SP2 = false>
; __device__ __forceinline__ void gemm_phase(PG8_LAS unsigned char* lds, const Gemm g, const Sched& S, const Epi& E) {
;     ...
;         for (int t = 0; t < nt; t += 2) {
;     ...
;             PG8_LDB(B0, 1, 0); PG8_LDB(B1, 1, 1); PG8_SCHED; PG8_LDA(At, 1, 0); PG8_STAGE(PG8_SA(0, 1), a2 + hstep, voffA);
;             PG8_WAIT_V(8); PG8_WAIT_L(0); PG8_BAR; PG8_MMA(0, 0, At, B0); PG8_MMA(0, 1, At, B1); PG8_BAR; PG8_SCHED;
;             PG8_LDA(At, 1, 1); PG8_STAGE(PG8_SB(1, 0), b3, voffB); PG8_STAGE(PG8_SB(1, 1), b3 + hstep, voffB); PG8_STAGE(PG8_SA(1, 0), a3, voffA);
;             PG8_WAIT_V(8); PG8_WAIT_L(0); PG8_BAR; PG8_MMA(1, 0, At, B0); PG8_MMA(1, 1, At, B1); PG8_BAR; PG8_SCHED;
	s_add_i32 s48, 0, 0x18000
	v_add_u32_e32 v143, s48, v159
	s_add_i32 s49, 0, 0x1c000
	ds_read_b128 v[172:175], v143
	ds_read_b128 v[176:179], v143 offset:1024
	ds_read_b128 v[180:183], v143 offset:2048
	ds_read_b128 v[184:187], v143 offset:3072
	v_add_u32_e32 v143, s49, v159
	ds_read_b128 v[188:191], v143
	ds_read_b128 v[192:195], v143 offset:1024
	ds_read_b128 v[196:199], v143 offset:2048
	ds_read_b128 v[200:203], v143 offset:3072
	s_add_u32 s16, s22, 0xb0000
	s_addc_u32 s17, s23, 0
	s_mov_b32 m0, s34
	ds_read_b128 v[204:207], v160 offset:32768
	ds_read_b128 v[208:211], v160 offset:33792
	ds_read_b128 v[212:215], v160 offset:34816
	ds_read_b128 v[216:219], v160 offset:35840
	ds_read_b128 v[220:223], v160 offset:36864
	ds_read_b128 v[224:227], v160 offset:37888
	ds_read_b128 v[228:231], v160 offset:38912
	ds_read_b128 v[232:235], v160 offset:39936
	global_load_lds_dwordx4 v134, s[16:17]
	s_mov_b32 m0, s35
	s_nop 0
	global_load_lds_dwordx4 v130, s[16:17]
	s_waitcnt vmcnt(8)
	s_waitcnt lgkmcnt(0)
	s_barrier
	s_setprio 1
	s_waitcnt lgkmcnt(0)
	v_mfma_f32_16x16x32_bf16 v[124:127], v[172:175], v[204:207], v[124:127]
	v_mfma_f32_16x16x32_bf16 v[120:123], v[180:183], v[204:207], v[120:123]
	v_mfma_f32_16x16x32_bf16 v[108:111], v[172:175], v[212:215], v[108:111]
	v_mfma_f32_16x16x32_bf16 v[104:107], v[180:183], v[212:215], v[104:107]
	v_mfma_f32_16x16x32_bf16 v[92:95], v[172:175], v[220:223], v[92:95]
	v_mfma_f32_16x16x32_bf16 v[88:91], v[180:183], v[220:223], v[88:91]
	v_mfma_f32_16x16x32_bf16 v[76:79], v[172:175], v[228:231], v[76:79]
	v_mfma_f32_16x16x32_bf16 v[72:75], v[180:183], v[228:231], v[72:75]
	v_mfma_f32_16x16x32_bf16 v[124:127], v[176:179], v[208:211], v[124:127]
	v_mfma_f32_16x16x32_bf16 v[120:123], v[184:187], v[208:211], v[120:123]
	v_mfma_f32_16x16x32_bf16 v[108:111], v[176:179], v[216:219], v[108:111]
	v_mfma_f32_16x16x32_bf16 v[104:107], v[184:187], v[216:219], v[104:107]
	v_mfma_f32_16x16x32_bf16 v[92:95], v[176:179], v[224:227], v[92:95]
	v_mfma_f32_16x16x32_bf16 v[88:91], v[184:187], v[224:227], v[88:91]
	v_mfma_f32_16x16x32_bf16 v[76:79], v[176:179], v[232:235], v[76:79]
	v_mfma_f32_16x16x32_bf16 v[72:75], v[184:187], v[232:235], v[72:75]
	s_setprio 0
	s_setprio 1
	v_mfma_f32_16x16x32_bf16 v[116:119], v[188:191], v[204:207], v[116:119]
	v_mfma_f32_16x16x32_bf16 v[112:115], v[196:199], v[204:207], v[112:115]
	v_mfma_f32_16x16x32_bf16 v[100:103], v[188:191], v[212:215], v[100:103]
	v_mfma_f32_16x16x32_bf16 v[96:99], v[196:199], v[212:215], v[96:99]
	v_mfma_f32_16x16x32_bf16 v[84:87], v[188:191], v[220:223], v[84:87]
	v_mfma_f32_16x16x32_bf16 v[80:83], v[196:199], v[220:223], v[80:83]
	v_mfma_f32_16x16x32_bf16 v[68:71], v[188:191], v[228:231], v[68:71]
	v_mfma_f32_16x16x32_bf16 v[64:67], v[196:199], v[228:231], v[64:67]
	v_mfma_f32_16x16x32_bf16 v[116:119], v[192:195], v[208:211], v[116:119]
	v_mfma_f32_16x16x32_bf16 v[112:115], v[200:203], v[208:211], v[112:115]
	v_mfma_f32_16x16x32_bf16 v[100:103], v[192:195], v[216:219], v[100:103]
	v_mfma_f32_16x16x32_bf16 v[96:99], v[200:203], v[216:219], v[96:99]
	v_mfma_f32_16x16x32_bf16 v[84:87], v[192:195], v[224:227], v[84:87]
	v_mfma_f32_16x16x32_bf16 v[80:83], v[200:203], v[224:227], v[80:83]
	v_mfma_f32_16x16x32_bf16 v[68:71], v[192:195], v[232:235], v[68:71]
	v_mfma_f32_16x16x32_bf16 v[64:67], v[200:203], v[232:235], v[64:67]
	s_setprio 0
	s_barrier
	s_add_i32 s16, s48, s28
	s_mov_b32 m0, s16
	ds_read_b128 v[204:207], v160 offset:49152
	ds_read_b128 v[208:211], v160 offset:50176
	ds_read_b128 v[212:215], v160 offset:51200
	ds_read_b128 v[216:219], v160 offset:52224
	ds_read_b128 v[220:223], v160 offset:53248
	ds_read_b128 v[224:227], v160 offset:54272
	ds_read_b128 v[228:231], v160 offset:55296
	ds_read_b128 v[232:235], v160 offset:56320
	global_load_lds_dwordx4 v132, s[94:95]
	s_add_i32 m0, s16, 0x2000
	s_add_u32 s16, s20, 0xb0080
	s_addc_u32 s17, s21, 0
	s_add_i32 s20, s49, s28
	global_load_lds_dwordx4 v128, s[94:95]
	s_mov_b32 m0, s20
	s_nop 0
	global_load_lds_dwordx4 v132, s[16:17]
	s_add_i32 m0, s20, 0x2000
	s_nop 0
	global_load_lds_dwordx4 v128, s[16:17]
	s_mov_b32 m0, s38
	s_nop 0
	global_load_lds_dwordx4 v134, s[96:97]
	s_mov_b32 m0, s39
	s_nop 0
	global_load_lds_dwordx4 v130, s[96:97]
	s_waitcnt vmcnt(8)
	s_waitcnt lgkmcnt(0)
	s_barrier
	s_setprio 1
	s_waitcnt lgkmcnt(0)
	v_mfma_f32_16x16x32_bf16 v[60:63], v[172:175], v[204:207], v[60:63]
	v_mfma_f32_16x16x32_bf16 v[56:59], v[180:183], v[204:207], v[56:59]
	v_mfma_f32_16x16x32_bf16 v[44:47], v[172:175], v[212:215], v[44:47]
	v_mfma_f32_16x16x32_bf16 v[40:43], v[180:183], v[212:215], v[40:43]
	v_mfma_f32_16x16x32_bf16 v[28:31], v[172:175], v[220:223], v[28:31]
	v_mfma_f32_16x16x32_bf16 v[24:27], v[180:183], v[220:223], v[24:27]
	v_mfma_f32_16x16x32_bf16 v[12:15], v[172:175], v[228:231], v[12:15]
	v_mfma_f32_16x16x32_bf16 v[8:11], v[180:183], v[228:231], v[8:11]
	v_mfma_f32_16x16x32_bf16 v[60:63], v[176:179], v[208:211], v[60:63]
	v_mfma_f32_16x16x32_bf16 v[56:59], v[184:187], v[208:211], v[56:59]
	v_mfma_f32_16x16x32_bf16 v[44:47], v[176:179], v[216:219], v[44:47]
	v_mfma_f32_16x16x32_bf16 v[40:43], v[184:187], v[216:219], v[40:43]
	v_mfma_f32_16x16x32_bf16 v[28:31], v[176:179], v[224:227], v[28:31]
	v_mfma_f32_16x16x32_bf16 v[24:27], v[184:187], v[224:227], v[24:27]
	v_mfma_f32_16x16x32_bf16 v[12:15], v[176:179], v[232:235], v[12:15]
	v_mfma_f32_16x16x32_bf16 v[8:11], v[184:187], v[232:235], v[8:11]
	s_setprio 0
	s_setprio 1
	v_mfma_f32_16x16x32_bf16 v[52:55], v[188:191], v[204:207], v[52:55]
	v_mfma_f32_16x16x32_bf16 v[48:51], v[196:199], v[204:207], v[48:51]
	v_mfma_f32_16x16x32_bf16 v[36:39], v[188:191], v[212:215], v[36:39]
	v_mfma_f32_16x16x32_bf16 v[32:35], v[196:199], v[212:215], v[32:35]
	v_mfma_f32_16x16x32_bf16 v[20:23], v[188:191], v[220:223], v[20:23]
	v_mfma_f32_16x16x32_bf16 v[16:19], v[196:199], v[220:223], v[16:19]
	v_mfma_f32_16x16x32_bf16 v[4:7], v[188:191], v[228:231], v[4:7]
	v_mfma_f32_16x16x32_bf16 v[0:3], v[196:199], v[228:231], v[0:3]
	v_mfma_f32_16x16x32_bf16 v[52:55], v[192:195], v[208:211], v[52:55]
	v_mfma_f32_16x16x32_bf16 v[48:51], v[200:203], v[208:211], v[48:51]
	v_mfma_f32_16x16x32_bf16 v[36:39], v[192:195], v[216:219], v[36:39]
	v_mfma_f32_16x16x32_bf16 v[32:35], v[200:203], v[216:219], v[32:35]
	v_mfma_f32_16x16x32_bf16 v[20:23], v[192:195], v[224:227], v[20:23]
	v_mfma_f32_16x16x32_bf16 v[16:19], v[200:203], v[224:227], v[16:19]
	v_mfma_f32_16x16x32_bf16 v[4:7], v[192:195], v[232:235], v[4:7]
	v_mfma_f32_16x16x32_bf16 v[0:3], v[200:203], v[232:235], v[0:3]
	s_setprio 0
	s_barrier
	s_add_i32 s47, s47, 2
	s_add_u32 s25, s25, 0x100
	s_addc_u32 s46, s46, 0
	s_cmp_gt_u32 s47, s99
	s_mov_b64 s[16:17], s[18:19]
	s_cbranch_scc0 .LBB0_898
	s_and_b64 vcc, exec, s[12:13]
	s_cbranch_vccz .LBB0_901
	s_barrier
